# baseline (speedup 1.0000x reference)
; #define LDA(dst, b, h)                                                                                     \
;   _Pragma("unroll") for (int m = 0; m < 4; ++m) _Pragma("unroll") for (int k = 0; k < 2; ++k) dst[m][k] = \
;       *reinterpret_cast<const bf16x8*>(shmc + aL + (((b) * 2 + (h)) * 16384 + (m * 2 + k) * 1024))
; #define LDB(dst, b, h)                                                                                     \
;   _Pragma("unroll") for (int n = 0; n < 2; ++n) _Pragma("unroll") for (int k = 0; k < 2; ++k) dst[n][k] = \
;       *reinterpret_cast<const bf16x8*>(shmc + bL + (((b) * 2 + (h)) * 16384 + (n * 2 + k) * 1024))
; #define OPAQ asm volatile("" : "+v"(aL), "+v"(bL))
; #define WAIT_V(n) asm volatile("s_waitcnt vmcnt(" #n ")" ::: "memory")
; #define WAIT_L(n) asm volatile("s_waitcnt lgkmcnt(" #n ")" ::: "memory")
; #define BAR __builtin_amdgcn_s_barrier()
; #define SCHED __builtin_amdgcn_sched_barrier(0)
; template <int EPI>
; __device__ __forceinline__ void phase_gemm(const Params& p, const GemmDesc& d, char* shmc) {
;     ...
;     for (int t = 0; t < nt - 2; t += 2) {
;       OPAQ;
;       LDB(B0, 0, 0); SCHED; LDA(At, 0, 0); STAGE_A(SA(1, 1), 1, t + 1);
;       WAIT_L(8); BAR; WAIT_L(0); MMA(0, 0, At, B0); BAR; SCHED;
;       LDB(B1, 0, 1); STAGE_B(SB(0, 0), 0, t + 2);
;       BAR; WAIT_L(0); MMA(0, 1, At, B1); BAR;
;       LDA(At, 0, 1); STAGE_A(SA(0, 0), 0, t + 2);
;       BAR; WAIT_L(0); MMA(1, 0, At, B0); BAR; SCHED;
;       STAGE_B(SB(0, 1), 1, t + 2);
;       WAIT_V(6); BAR; MMA(1, 1, At, B1); BAR;
.LBB0_296:
	s_nop 0
	v_add_u32_e32 v162, 0, v205
	v_add_u32_e32 v175, 0, v204
	ds_read_b128 v[138:141], v162
	ds_read_b128 v[142:145], v162 offset:1024
	ds_read_b128 v[146:149], v162 offset:2048
	ds_read_b128 v[150:153], v162 offset:3072
	ds_read_b128 v[208:211], v162 offset:16384
	ds_read_b128 v[212:215], v162 offset:17408
	ds_read_b128 v[216:219], v162 offset:18432
	ds_read_b128 v[220:223], v162 offset:19456
	ds_read_b128 v[154:157], v175
	ds_read_b128 v[158:161], v175 offset:1024
	ds_read_b128 v[178:181], v175 offset:2048
	ds_read_b128 v[182:185], v175 offset:3072
	ds_read_b128 v[186:189], v175 offset:4096
	ds_read_b128 v[190:193], v175 offset:5120
	ds_read_b128 v[194:197], v175 offset:6144
	ds_read_b128 v[198:201], v175 offset:7168
	s_mov_b32 m0, s93
	s_nop 0
	global_load_lds_dwordx4 v202, s[98:99]
	s_mov_b32 m0, s94
	s_nop 0
	global_load_lds_dwordx4 v203, s[98:99]
	s_waitcnt vmcnt(8)
	s_waitcnt lgkmcnt(0)
	s_barrier
	v_mfma_f32_16x16x32_bf16 v[2:5], v[154:157], v[138:141], v[2:5]
	v_mfma_f32_16x16x32_bf16 v[6:9], v[154:157], v[146:149], v[6:9]
	v_mfma_f32_16x16x32_bf16 v[10:13], v[178:181], v[138:141], v[10:13]
	v_mfma_f32_16x16x32_bf16 v[18:21], v[178:181], v[146:149], v[18:21]
	v_mfma_f32_16x16x32_bf16 v[30:33], v[186:189], v[138:141], v[30:33]
	v_mfma_f32_16x16x32_bf16 v[42:45], v[186:189], v[146:149], v[42:45]
	v_mfma_f32_16x16x32_bf16 v[54:57], v[194:197], v[138:141], v[54:57]
	v_mfma_f32_16x16x32_bf16 v[66:69], v[194:197], v[146:149], v[66:69]
	v_mfma_f32_16x16x32_bf16 v[2:5], v[158:161], v[142:145], v[2:5]
	v_mfma_f32_16x16x32_bf16 v[6:9], v[158:161], v[150:153], v[6:9]
	v_mfma_f32_16x16x32_bf16 v[10:13], v[182:185], v[142:145], v[10:13]
	v_mfma_f32_16x16x32_bf16 v[18:21], v[182:185], v[150:153], v[18:21]
	v_mfma_f32_16x16x32_bf16 v[30:33], v[190:193], v[142:145], v[30:33]
	v_mfma_f32_16x16x32_bf16 v[42:45], v[190:193], v[150:153], v[42:45]
	v_mfma_f32_16x16x32_bf16 v[54:57], v[198:201], v[142:145], v[54:57]
	v_mfma_f32_16x16x32_bf16 v[66:69], v[198:201], v[150:153], v[66:69]
	v_mfma_f32_16x16x32_bf16 v[14:17], v[154:157], v[208:211], v[14:17]
	v_mfma_f32_16x16x32_bf16 v[22:25], v[154:157], v[216:219], v[22:25]
	v_mfma_f32_16x16x32_bf16 v[34:37], v[178:181], v[208:211], v[34:37]
	v_mfma_f32_16x16x32_bf16 v[46:49], v[178:181], v[216:219], v[46:49]
	v_mfma_f32_16x16x32_bf16 v[58:61], v[186:189], v[208:211], v[58:61]
	v_mfma_f32_16x16x32_bf16 v[70:73], v[186:189], v[216:219], v[70:73]
	v_mfma_f32_16x16x32_bf16 v[78:81], v[194:197], v[208:211], v[78:81]
	v_mfma_f32_16x16x32_bf16 v[86:89], v[194:197], v[216:219], v[86:89]
	v_mfma_f32_16x16x32_bf16 v[14:17], v[158:161], v[212:215], v[14:17]
	v_mfma_f32_16x16x32_bf16 v[22:25], v[158:161], v[220:223], v[22:25]
	v_mfma_f32_16x16x32_bf16 v[34:37], v[182:185], v[212:215], v[34:37]
	v_mfma_f32_16x16x32_bf16 v[46:49], v[182:185], v[220:223], v[46:49]
	v_mfma_f32_16x16x32_bf16 v[58:61], v[190:193], v[212:215], v[58:61]
	v_mfma_f32_16x16x32_bf16 v[70:73], v[190:193], v[220:223], v[70:73]
	v_mfma_f32_16x16x32_bf16 v[78:81], v[198:201], v[212:215], v[78:81]
	v_mfma_f32_16x16x32_bf16 v[86:89], v[198:201], v[220:223], v[86:89]
	s_barrier
	ds_read_b128 v[154:157], v175 offset:16384
	ds_read_b128 v[158:161], v175 offset:17408
	ds_read_b128 v[178:181], v175 offset:18432
	ds_read_b128 v[182:185], v175 offset:19456
	ds_read_b128 v[186:189], v175 offset:20480
	ds_read_b128 v[190:193], v175 offset:21504
	ds_read_b128 v[194:197], v175 offset:22528
	ds_read_b128 v[198:201], v175 offset:23552
	s_mov_b32 m0, s80
	s_nop 0
	global_load_lds_dwordx4 v224, s[100:101]
	s_mov_b32 m0, s81
	s_nop 0
	global_load_lds_dwordx4 v225, s[100:101]
	s_mov_b32 m0, s77
	s_nop 0
	global_load_lds_dwordx4 v226, s[98:99]
	s_mov_b32 m0, s82
	s_nop 0
	global_load_lds_dwordx4 v227, s[98:99]
	s_mov_b32 m0, s83
	s_nop 0
	global_load_lds_dwordx4 v228, s[100:101]
	s_mov_b32 m0, s84
	s_nop 0
	global_load_lds_dwordx4 v229, s[100:101]
	s_waitcnt vmcnt(8)
	s_waitcnt lgkmcnt(0)
	s_barrier
	v_mfma_f32_16x16x32_bf16 v[26:29], v[154:157], v[138:141], v[26:29]
	v_mfma_f32_16x16x32_bf16 v[38:41], v[154:157], v[146:149], v[38:41]
	v_mfma_f32_16x16x32_bf16 v[50:53], v[178:181], v[138:141], v[50:53]
	v_mfma_f32_16x16x32_bf16 v[62:65], v[178:181], v[146:149], v[62:65]
	v_mfma_f32_16x16x32_bf16 v[74:77], v[186:189], v[138:141], v[74:77]
	v_mfma_f32_16x16x32_bf16 v[82:85], v[186:189], v[146:149], v[82:85]
	v_mfma_f32_16x16x32_bf16 v[90:93], v[194:197], v[138:141], v[90:93]
	v_mfma_f32_16x16x32_bf16 v[94:97], v[194:197], v[146:149], v[94:97]
	v_mfma_f32_16x16x32_bf16 v[26:29], v[158:161], v[142:145], v[26:29]
	v_mfma_f32_16x16x32_bf16 v[38:41], v[158:161], v[150:153], v[38:41]
	v_mfma_f32_16x16x32_bf16 v[50:53], v[182:185], v[142:145], v[50:53]
	v_mfma_f32_16x16x32_bf16 v[62:65], v[182:185], v[150:153], v[62:65]
	v_mfma_f32_16x16x32_bf16 v[74:77], v[190:193], v[142:145], v[74:77]
	v_mfma_f32_16x16x32_bf16 v[82:85], v[190:193], v[150:153], v[82:85]
	v_mfma_f32_16x16x32_bf16 v[90:93], v[198:201], v[142:145], v[90:93]
	v_mfma_f32_16x16x32_bf16 v[94:97], v[198:201], v[150:153], v[94:97]
	v_mfma_f32_16x16x32_bf16 v[98:101], v[154:157], v[208:211], v[98:101]
	v_mfma_f32_16x16x32_bf16 v[102:105], v[154:157], v[216:219], v[102:105]
	v_mfma_f32_16x16x32_bf16 v[106:109], v[178:181], v[208:211], v[106:109]
	v_mfma_f32_16x16x32_bf16 v[110:113], v[178:181], v[216:219], v[110:113]
	v_mfma_f32_16x16x32_bf16 v[114:117], v[186:189], v[208:211], v[114:117]
	v_mfma_f32_16x16x32_bf16 v[118:121], v[186:189], v[216:219], v[118:121]
	v_mfma_f32_16x16x32_bf16 v[122:125], v[194:197], v[208:211], v[122:125]
	v_mfma_f32_16x16x32_bf16 v[126:129], v[194:197], v[216:219], v[126:129]
	v_mfma_f32_16x16x32_bf16 v[98:101], v[158:161], v[212:215], v[98:101]
	v_mfma_f32_16x16x32_bf16 v[102:105], v[158:161], v[220:223], v[102:105]
	v_mfma_f32_16x16x32_bf16 v[106:109], v[182:185], v[212:215], v[106:109]
	v_mfma_f32_16x16x32_bf16 v[110:113], v[182:185], v[220:223], v[110:113]
	v_mfma_f32_16x16x32_bf16 v[114:117], v[190:193], v[212:215], v[114:117]
	v_mfma_f32_16x16x32_bf16 v[118:121], v[190:193], v[220:223], v[118:121]
	v_mfma_f32_16x16x32_bf16 v[122:125], v[198:201], v[212:215], v[122:125]
	v_mfma_f32_16x16x32_bf16 v[126:129], v[198:201], v[220:223], v[126:129]
	s_barrier
; #define LDA(dst, b, h)                                                                                     \
;   _Pragma("unroll") for (int m = 0; m < 4; ++m) _Pragma("unroll") for (int k = 0; k < 2; ++k) dst[m][k] = \
;       *reinterpret_cast<const bf16x8*>(shmc + aL + (((b) * 2 + (h)) * 16384 + (m * 2 + k) * 1024))
; #define LDB(dst, b, h)                                                                                     \
;   _Pragma("unroll") for (int n = 0; n < 2; ++n) _Pragma("unroll") for (int k = 0; k < 2; ++k) dst[n][k] = \
;       *reinterpret_cast<const bf16x8*>(shmc + bL + (((b) * 2 + (h)) * 16384 + (n * 2 + k) * 1024))
; #define WAIT_V(n) asm volatile("s_waitcnt vmcnt(" #n ")" ::: "memory")
; #define WAIT_L(n) asm volatile("s_waitcnt lgkmcnt(" #n ")" ::: "memory")
; #define BAR __builtin_amdgcn_s_barrier()
; #define SCHED __builtin_amdgcn_sched_barrier(0)
; template <int EPI>
; __device__ __forceinline__ void phase_gemm(const Params& p, const GemmDesc& d, char* shmc) {
;     ...
;       LDB(B0, 1, 0); SCHED; LDA(At, 1, 0); STAGE_A(SA(0, 1), 1, t + 2);
;       WAIT_L(8); BAR; WAIT_L(0); MMA(0, 0, At, B0); BAR; SCHED;
;       LDB(B1, 1, 1); STAGE_B(SB(1, 0), 0, t + 3);
;       BAR; WAIT_L(0); MMA(0, 1, At, B1); BAR;
;       LDA(At, 1, 1); STAGE_A(SA(1, 0), 0, t + 3);
;       BAR; WAIT_L(0); MMA(1, 0, At, B0); BAR; SCHED;
;       STAGE_B(SB(1, 1), 1, t + 3);
;       WAIT_V(6); BAR; MMA(1, 1, At, B1); BAR;
;     }
	ds_read_b128 v[138:141], v162 offset:32768
	ds_read_b128 v[142:145], v162 offset:33792
	ds_read_b128 v[146:149], v162 offset:34816
	ds_read_b128 v[150:153], v162 offset:35840
	ds_read_b128 v[208:211], v162 offset:49152
	ds_read_b128 v[212:215], v162 offset:50176
	ds_read_b128 v[216:219], v162 offset:51200
	ds_read_b128 v[220:223], v162 offset:52224
	ds_read_b128 v[154:157], v175 offset:32768
	ds_read_b128 v[158:161], v175 offset:33792
	ds_read_b128 v[178:181], v175 offset:34816
	ds_read_b128 v[182:185], v175 offset:35840
	ds_read_b128 v[186:189], v175 offset:36864
	ds_read_b128 v[190:193], v175 offset:37888
	ds_read_b128 v[194:197], v175 offset:38912
	ds_read_b128 v[198:201], v175 offset:39936
	s_mov_b32 m0, s85
	s_nop 0
	global_load_lds_dwordx4 v230, s[98:99]
	s_mov_b32 m0, s86
	s_nop 0
	global_load_lds_dwordx4 v231, s[98:99]
	s_waitcnt vmcnt(8)
	s_waitcnt lgkmcnt(0)
	s_barrier
	v_mfma_f32_16x16x32_bf16 v[2:5], v[154:157], v[138:141], v[2:5]
	v_mfma_f32_16x16x32_bf16 v[6:9], v[154:157], v[146:149], v[6:9]
	v_mfma_f32_16x16x32_bf16 v[10:13], v[178:181], v[138:141], v[10:13]
	v_mfma_f32_16x16x32_bf16 v[18:21], v[178:181], v[146:149], v[18:21]
	v_mfma_f32_16x16x32_bf16 v[30:33], v[186:189], v[138:141], v[30:33]
	v_mfma_f32_16x16x32_bf16 v[42:45], v[186:189], v[146:149], v[42:45]
	v_mfma_f32_16x16x32_bf16 v[54:57], v[194:197], v[138:141], v[54:57]
	v_mfma_f32_16x16x32_bf16 v[66:69], v[194:197], v[146:149], v[66:69]
	v_mfma_f32_16x16x32_bf16 v[2:5], v[158:161], v[142:145], v[2:5]
	v_mfma_f32_16x16x32_bf16 v[6:9], v[158:161], v[150:153], v[6:9]
	v_mfma_f32_16x16x32_bf16 v[10:13], v[182:185], v[142:145], v[10:13]
	v_mfma_f32_16x16x32_bf16 v[18:21], v[182:185], v[150:153], v[18:21]
	v_mfma_f32_16x16x32_bf16 v[30:33], v[190:193], v[142:145], v[30:33]
	v_mfma_f32_16x16x32_bf16 v[42:45], v[190:193], v[150:153], v[42:45]
	v_mfma_f32_16x16x32_bf16 v[54:57], v[198:201], v[142:145], v[54:57]
	v_mfma_f32_16x16x32_bf16 v[66:69], v[198:201], v[150:153], v[66:69]
	v_mfma_f32_16x16x32_bf16 v[14:17], v[154:157], v[208:211], v[14:17]
	v_mfma_f32_16x16x32_bf16 v[22:25], v[154:157], v[216:219], v[22:25]
	v_mfma_f32_16x16x32_bf16 v[34:37], v[178:181], v[208:211], v[34:37]
	v_mfma_f32_16x16x32_bf16 v[46:49], v[178:181], v[216:219], v[46:49]
	v_mfma_f32_16x16x32_bf16 v[58:61], v[186:189], v[208:211], v[58:61]
	v_mfma_f32_16x16x32_bf16 v[70:73], v[186:189], v[216:219], v[70:73]
	v_mfma_f32_16x16x32_bf16 v[78:81], v[194:197], v[208:211], v[78:81]
	v_mfma_f32_16x16x32_bf16 v[86:89], v[194:197], v[216:219], v[86:89]
	v_mfma_f32_16x16x32_bf16 v[14:17], v[158:161], v[212:215], v[14:17]
	v_mfma_f32_16x16x32_bf16 v[22:25], v[158:161], v[220:223], v[22:25]
	v_mfma_f32_16x16x32_bf16 v[34:37], v[182:185], v[212:215], v[34:37]
	v_mfma_f32_16x16x32_bf16 v[46:49], v[182:185], v[220:223], v[46:49]
	v_mfma_f32_16x16x32_bf16 v[58:61], v[190:193], v[212:215], v[58:61]
	v_mfma_f32_16x16x32_bf16 v[70:73], v[190:193], v[220:223], v[70:73]
	v_mfma_f32_16x16x32_bf16 v[78:81], v[198:201], v[212:215], v[78:81]
	v_mfma_f32_16x16x32_bf16 v[86:89], v[198:201], v[220:223], v[86:89]
	s_barrier
	ds_read_b128 v[154:157], v175 offset:49152
	ds_read_b128 v[158:161], v175 offset:50176
	ds_read_b128 v[178:181], v175 offset:51200
	ds_read_b128 v[182:185], v175 offset:52224
	ds_read_b128 v[186:189], v175 offset:53248
	ds_read_b128 v[190:193], v175 offset:54272
	ds_read_b128 v[194:197], v175 offset:55296
	ds_read_b128 v[198:201], v175 offset:56320
	s_mov_b32 m0, s87
	s_nop 0
	global_load_lds_dwordx4 v232, s[100:101]
	s_mov_b32 m0, s88
	s_nop 0
	global_load_lds_dwordx4 v233, s[100:101]
	s_mov_b32 m0, s89
	s_nop 0
	global_load_lds_dwordx4 v234, s[98:99]
	s_mov_b32 m0, s90
	s_nop 0
	global_load_lds_dwordx4 v235, s[98:99]
	s_mov_b32 m0, s91
	s_nop 0
	global_load_lds_dwordx4 v236, s[100:101]
	s_mov_b32 m0, s92
	s_nop 0
	global_load_lds_dwordx4 v237, s[100:101]
	s_add_i32 s35, s35, 2
	s_add_u32 s10, s10, 0x100
	s_addc_u32 s11, s11, 0
	s_add_u32 s98, s98, 0x100
	s_addc_u32 s99, s99, 0
	s_add_u32 s100, s100, 0x100
	s_addc_u32 s101, s101, 0
	s_cmp_gt_u32 s35, 27
	s_waitcnt vmcnt(8)
	s_waitcnt lgkmcnt(0)
	s_barrier
	v_mfma_f32_16x16x32_bf16 v[26:29], v[154:157], v[138:141], v[26:29]
	v_mfma_f32_16x16x32_bf16 v[38:41], v[154:157], v[146:149], v[38:41]
	v_mfma_f32_16x16x32_bf16 v[50:53], v[178:181], v[138:141], v[50:53]
	v_mfma_f32_16x16x32_bf16 v[62:65], v[178:181], v[146:149], v[62:65]
	v_mfma_f32_16x16x32_bf16 v[74:77], v[186:189], v[138:141], v[74:77]
	v_mfma_f32_16x16x32_bf16 v[82:85], v[186:189], v[146:149], v[82:85]
	v_mfma_f32_16x16x32_bf16 v[90:93], v[194:197], v[138:141], v[90:93]
	v_mfma_f32_16x16x32_bf16 v[94:97], v[194:197], v[146:149], v[94:97]
	v_mfma_f32_16x16x32_bf16 v[26:29], v[158:161], v[142:145], v[26:29]
	v_mfma_f32_16x16x32_bf16 v[38:41], v[158:161], v[150:153], v[38:41]
	v_mfma_f32_16x16x32_bf16 v[50:53], v[182:185], v[142:145], v[50:53]
	v_mfma_f32_16x16x32_bf16 v[62:65], v[182:185], v[150:153], v[62:65]
	v_mfma_f32_16x16x32_bf16 v[74:77], v[190:193], v[142:145], v[74:77]
	v_mfma_f32_16x16x32_bf16 v[82:85], v[190:193], v[150:153], v[82:85]
	v_mfma_f32_16x16x32_bf16 v[90:93], v[198:201], v[142:145], v[90:93]
	v_mfma_f32_16x16x32_bf16 v[94:97], v[198:201], v[150:153], v[94:97]
	v_mfma_f32_16x16x32_bf16 v[98:101], v[154:157], v[208:211], v[98:101]
	v_mfma_f32_16x16x32_bf16 v[102:105], v[154:157], v[216:219], v[102:105]
	v_mfma_f32_16x16x32_bf16 v[106:109], v[178:181], v[208:211], v[106:109]
	v_mfma_f32_16x16x32_bf16 v[110:113], v[178:181], v[216:219], v[110:113]
	v_mfma_f32_16x16x32_bf16 v[114:117], v[186:189], v[208:211], v[114:117]
	v_mfma_f32_16x16x32_bf16 v[118:121], v[186:189], v[216:219], v[118:121]
	v_mfma_f32_16x16x32_bf16 v[122:125], v[194:197], v[208:211], v[122:125]
	v_mfma_f32_16x16x32_bf16 v[126:129], v[194:197], v[216:219], v[126:129]
	v_mfma_f32_16x16x32_bf16 v[98:101], v[158:161], v[212:215], v[98:101]
	v_mfma_f32_16x16x32_bf16 v[102:105], v[158:161], v[220:223], v[102:105]
	v_mfma_f32_16x16x32_bf16 v[106:109], v[182:185], v[212:215], v[106:109]
	v_mfma_f32_16x16x32_bf16 v[110:113], v[182:185], v[220:223], v[110:113]
	v_mfma_f32_16x16x32_bf16 v[114:117], v[190:193], v[212:215], v[114:117]
	v_mfma_f32_16x16x32_bf16 v[118:121], v[190:193], v[220:223], v[118:121]
	v_mfma_f32_16x16x32_bf16 v[122:125], v[198:201], v[212:215], v[122:125]
	v_mfma_f32_16x16x32_bf16 v[126:129], v[198:201], v[220:223], v[126:129]
	s_barrier
; #define LDA(dst, b, h)                                                                                     \
;   _Pragma("unroll") for (int m = 0; m < 4; ++m) _Pragma("unroll") for (int k = 0; k < 2; ++k) dst[m][k] = \
;       *reinterpret_cast<const bf16x8*>(shmc + aL + (((b) * 2 + (h)) * 16384 + (m * 2 + k) * 1024))
; #define LDB(dst, b, h)                                                                                     \
;   _Pragma("unroll") for (int n = 0; n < 2; ++n) _Pragma("unroll") for (int k = 0; k < 2; ++k) dst[n][k] = \
;       *reinterpret_cast<const bf16x8*>(shmc + bL + (((b) * 2 + (h)) * 16384 + (n * 2 + k) * 1024))
; #define OPAQ asm volatile("" : "+v"(aL), "+v"(bL))
; #define WAIT_V(n) asm volatile("s_waitcnt vmcnt(" #n ")" ::: "memory")
; #define WAIT_L(n) asm volatile("s_waitcnt lgkmcnt(" #n ")" ::: "memory")
; #define BAR __builtin_amdgcn_s_barrier()
; template <int EPI>
; __device__ __forceinline__ void phase_gemm(const Params& p, const GemmDesc& d, char* shmc) {
;     ...
;     }
;     {
;       OPAQ;
;       LDB(B0, 0, 0); LDA(At, 0, 0); STAGE_A(SA(1, 1), 1, nt - 1);
;       BAR; WAIT_L(0); MMA(0, 0, At, B0); BAR;
;       LDB(B1, 0, 1); BAR; WAIT_L(0); MMA(0, 1, At, B1); BAR;
;       LDA(At, 0, 1); WAIT_V(4); BAR; WAIT_L(0); MMA(1, 0, At, B0); MMA(1, 1, At, B1); BAR;
;     }
	s_cbranch_scc0 .LBB0_296
	s_setprio 0
	s_add_u32 s8, s8, 0x80f80
	s_addc_u32 s9, s9, 0
	v_add_u32_e32 v162, 0, v205
	v_add_u32_e32 v175, 0, v204
	s_mov_b32 m0, s93
	ds_read_b128 v[130:133], v162
	ds_read_b128 v[134:137], v162 offset:1024
	ds_read_b128 v[138:141], v162 offset:2048
	ds_read_b128 v[142:145], v162 offset:3072
	ds_read_b128 v[146:149], v175
	ds_read_b128 v[150:153], v175 offset:1024
	ds_read_b128 v[154:157], v175 offset:2048
	ds_read_b128 v[158:161], v175 offset:3072
	ds_read_b128 v[178:181], v175 offset:4096
	ds_read_b128 v[182:185], v175 offset:5120
	ds_read_b128 v[186:189], v175 offset:6144
	ds_read_b128 v[190:193], v175 offset:7168
	global_load_lds_dwordx4 v174, s[8:9]
	s_mov_b32 m0, s94
	s_nop 0
	global_load_lds_dwordx4 v176, s[8:9]
	s_waitcnt vmcnt(8)
	s_barrier
	s_waitcnt lgkmcnt(0)
	s_setprio 1
	s_waitcnt lgkmcnt(0)
	v_mfma_f32_16x16x32_bf16 v[2:5], v[146:149], v[130:133], v[2:5]
	v_mfma_f32_16x16x32_bf16 v[6:9], v[146:149], v[138:141], v[6:9]
	v_mfma_f32_16x16x32_bf16 v[10:13], v[154:157], v[130:133], v[10:13]
	v_mfma_f32_16x16x32_bf16 v[18:21], v[154:157], v[138:141], v[18:21]
	v_mfma_f32_16x16x32_bf16 v[66:69], v[186:189], v[138:141], v[66:69]
	v_mfma_f32_16x16x32_bf16 v[2:5], v[150:153], v[134:137], v[2:5]
	v_mfma_f32_16x16x32_bf16 v[6:9], v[150:153], v[142:145], v[6:9]
	v_mfma_f32_16x16x32_bf16 v[10:13], v[158:161], v[134:137], v[10:13]
	v_mfma_f32_16x16x32_bf16 v[18:21], v[158:161], v[142:145], v[18:21]
	v_mfma_f32_16x16x32_bf16 v[30:33], v[178:181], v[130:133], v[30:33]
	v_mfma_f32_16x16x32_bf16 v[42:45], v[178:181], v[138:141], v[42:45]
	v_mfma_f32_16x16x32_bf16 v[54:57], v[186:189], v[130:133], v[54:57]
	v_mfma_f32_16x16x32_bf16 v[66:69], v[190:193], v[142:145], v[66:69]
	v_mfma_f32_16x16x32_bf16 v[30:33], v[182:185], v[134:137], v[30:33]
	v_mfma_f32_16x16x32_bf16 v[42:45], v[182:185], v[142:145], v[42:45]
	v_mfma_f32_16x16x32_bf16 v[54:57], v[190:193], v[134:137], v[54:57]
	s_setprio 0
	s_barrier
	ds_read_b128 v[194:197], v162 offset:16384
	ds_read_b128 v[198:201], v162 offset:17408
	ds_read_b128 v[208:211], v162 offset:18432
	ds_read_b128 v[212:215], v162 offset:19456
	s_barrier
	s_waitcnt lgkmcnt(0)
	s_setprio 1
	s_waitcnt lgkmcnt(0)
	v_mfma_f32_16x16x32_bf16 v[14:17], v[146:149], v[194:197], v[14:17]
	v_mfma_f32_16x16x32_bf16 v[22:25], v[146:149], v[208:211], v[22:25]
	v_mfma_f32_16x16x32_bf16 v[58:61], v[178:181], v[194:197], v[58:61]
	v_mfma_f32_16x16x32_bf16 v[14:17], v[150:153], v[198:201], v[14:17]
	v_mfma_f32_16x16x32_bf16 v[22:25], v[150:153], v[212:215], v[22:25]
	v_mfma_f32_16x16x32_bf16 v[150:153], v[182:185], v[198:201], v[58:61]
	v_mfma_f32_16x16x32_bf16 v[58:61], v[178:181], v[208:211], v[70:73]
	v_mfma_f32_16x16x32_bf16 v[34:37], v[154:157], v[194:197], v[34:37]
	v_mfma_f32_16x16x32_bf16 v[46:49], v[154:157], v[208:211], v[46:49]
	v_mfma_f32_16x16x32_bf16 v[154:157], v[182:185], v[212:215], v[58:61]
	v_mfma_f32_16x16x32_bf16 v[58:61], v[186:189], v[194:197], v[78:81]
	v_mfma_f32_16x16x32_bf16 v[78:81], v[190:193], v[198:201], v[58:61]
	v_mfma_f32_16x16x32_bf16 v[58:61], v[186:189], v[208:211], v[86:89]
	v_mfma_f32_16x16x32_bf16 v[86:89], v[190:193], v[212:215], v[58:61]
	v_mfma_f32_16x16x32_bf16 v[34:37], v[158:161], v[198:201], v[34:37]
	v_mfma_f32_16x16x32_bf16 v[46:49], v[158:161], v[212:215], v[46:49]
	s_setprio 0
	s_barrier
	s_nop 2
	ds_read_b128 v[58:61], v175 offset:16384
	ds_read_b128 v[70:73], v175 offset:17408
	ds_read_b128 v[146:149], v175 offset:18432
	ds_read_b128 v[158:161], v175 offset:19456
	ds_read_b128 v[178:181], v175 offset:20480
	ds_read_b128 v[182:185], v175 offset:21504
	ds_read_b128 v[186:189], v175 offset:22528
	ds_read_b128 v[190:193], v175 offset:23552
	s_waitcnt vmcnt(4)
	s_barrier
	s_waitcnt lgkmcnt(0)
	s_setprio 1
	s_waitcnt lgkmcnt(0)
	v_mfma_f32_16x16x32_bf16 v[74:77], v[178:181], v[130:133], v[74:77]
	v_mfma_f32_16x16x32_bf16 v[216:219], v[182:185], v[134:137], v[74:77]
	v_mfma_f32_16x16x32_bf16 v[74:77], v[178:181], v[138:141], v[82:85]
	v_mfma_f32_16x16x32_bf16 v[26:29], v[58:61], v[130:133], v[26:29]
	v_mfma_f32_16x16x32_bf16 v[82:85], v[182:185], v[142:145], v[74:77]
	v_mfma_f32_16x16x32_bf16 v[74:77], v[186:189], v[130:133], v[90:93]
	v_mfma_f32_16x16x32_bf16 v[26:29], v[70:73], v[134:137], v[26:29]
	v_mfma_f32_16x16x32_bf16 v[38:41], v[58:61], v[138:141], v[38:41]
	v_mfma_f32_16x16x32_bf16 v[50:53], v[146:149], v[130:133], v[50:53]
	v_mfma_f32_16x16x32_bf16 v[62:65], v[146:149], v[138:141], v[62:65]
	v_mfma_f32_16x16x32_bf16 v[90:93], v[190:193], v[134:137], v[74:77]
	v_mfma_f32_16x16x32_bf16 v[74:77], v[186:189], v[138:141], v[94:97]
	v_mfma_f32_16x16x32_bf16 v[38:41], v[70:73], v[142:145], v[38:41]
	v_mfma_f32_16x16x32_bf16 v[50:53], v[158:161], v[134:137], v[50:53]
	v_mfma_f32_16x16x32_bf16 v[62:65], v[158:161], v[142:145], v[62:65]
	v_mfma_f32_16x16x32_bf16 v[220:223], v[190:193], v[142:145], v[74:77]
	s_setprio 0
	s_setprio 1
	v_mfma_f32_16x16x32_bf16 v[74:77], v[58:61], v[194:197], v[98:101]
	v_mfma_f32_16x16x32_bf16 v[58:61], v[58:61], v[208:211], v[102:105]
	v_mfma_f32_16x16x32_bf16 v[228:231], v[70:73], v[212:215], v[58:61]
	v_mfma_f32_16x16x32_bf16 v[58:61], v[146:149], v[194:197], v[106:109]
	v_mfma_f32_16x16x32_bf16 v[232:235], v[158:161], v[198:201], v[58:61]
	v_mfma_f32_16x16x32_bf16 v[58:61], v[146:149], v[208:211], v[110:113]
	v_mfma_f32_16x16x32_bf16 v[236:239], v[158:161], v[212:215], v[58:61]
	v_mfma_f32_16x16x32_bf16 v[58:61], v[178:181], v[194:197], v[114:117]
	v_mfma_f32_16x16x32_bf16 v[240:243], v[182:185], v[198:201], v[58:61]
	v_mfma_f32_16x16x32_bf16 v[58:61], v[178:181], v[208:211], v[118:121]
	v_mfma_f32_16x16x32_bf16 v[178:181], v[182:185], v[212:215], v[58:61]
	v_mfma_f32_16x16x32_bf16 v[58:61], v[186:189], v[194:197], v[122:125]
	v_mfma_f32_16x16x32_bf16 v[182:185], v[190:193], v[198:201], v[58:61]
	v_mfma_f32_16x16x32_bf16 v[58:61], v[186:189], v[208:211], v[126:129]
	v_mfma_f32_16x16x32_bf16 v[224:227], v[70:73], v[198:201], v[74:77]
	v_mfma_f32_16x16x32_bf16 v[186:189], v[190:193], v[212:215], v[58:61]
	s_setprio 0
	s_barrier
; #define LDA(dst, b, h)                                                                                     \
;   _Pragma("unroll") for (int m = 0; m < 4; ++m) _Pragma("unroll") for (int k = 0; k < 2; ++k) dst[m][k] = \
;       *reinterpret_cast<const bf16x8*>(shmc + aL + (((b) * 2 + (h)) * 16384 + (m * 2 + k) * 1024))
; #define LDB(dst, b, h)                                                                                     \
;   _Pragma("unroll") for (int n = 0; n < 2; ++n) _Pragma("unroll") for (int k = 0; k < 2; ++k) dst[n][k] = \
;       *reinterpret_cast<const bf16x8*>(shmc + bL + (((b) * 2 + (h)) * 16384 + (n * 2 + k) * 1024))
; #define WAIT_V(n) asm volatile("s_waitcnt vmcnt(" #n ")" ::: "memory")
; #define WAIT_L(n) asm volatile("s_waitcnt lgkmcnt(" #n ")" ::: "memory")
; #define BAR __builtin_amdgcn_s_barrier()
; template <int EPI>
; __device__ __forceinline__ void phase_gemm(const Params& p, const GemmDesc& d, char* shmc) {
;     ...
;     {
;       LDB(B0, 1, 0); LDA(At, 1, 0); WAIT_V(2); BAR; WAIT_L(0); MMA(0, 0, At, B0); BAR;
;       LDB(B1, 1, 1); WAIT_V(0); BAR; WAIT_L(0); MMA(0, 1, At, B1); BAR;
;       LDA(At, 1, 1); BAR; WAIT_L(0); MMA(1, 0, At, B0); MMA(1, 1, At, B1); BAR;
;     }
;     if (wr == 0) BAR;
	ds_read_b128 v[98:101], v162 offset:32768
	ds_read_b128 v[106:109], v162 offset:33792
	ds_read_b128 v[190:193], v162 offset:34816
	ds_read_b128 v[194:197], v162 offset:35840
	ds_read_b128 v[58:61], v175 offset:32768
	ds_read_b128 v[70:73], v175 offset:33792
	ds_read_b128 v[114:117], v175 offset:34816
	ds_read_b128 v[122:125], v175 offset:35840
	ds_read_b128 v[130:133], v175 offset:36864
	ds_read_b128 v[138:141], v175 offset:37888
	ds_read_b128 v[198:201], v175 offset:38912
	ds_read_b128 v[208:211], v175 offset:39936
	s_waitcnt vmcnt(2)
	s_barrier
	s_waitcnt lgkmcnt(0)
	s_setprio 1
	s_waitcnt lgkmcnt(0)
	v_mfma_f32_16x16x32_bf16 v[2:5], v[58:61], v[98:101], v[2:5]
	v_mfma_f32_16x16x32_bf16 v[158:161], v[70:73], v[106:109], v[2:5]
	v_mfma_f32_16x16x32_bf16 v[2:5], v[58:61], v[190:193], v[6:9]
	v_mfma_f32_16x16x32_bf16 v[146:149], v[70:73], v[194:197], v[2:5]
	v_mfma_f32_16x16x32_bf16 v[2:5], v[114:117], v[98:101], v[10:13]
	v_mfma_f32_16x16x32_bf16 v[142:145], v[122:125], v[106:109], v[2:5]
	v_mfma_f32_16x16x32_bf16 v[2:5], v[114:117], v[190:193], v[18:21]
	v_mfma_f32_16x16x32_bf16 v[134:137], v[122:125], v[194:197], v[2:5]
	v_mfma_f32_16x16x32_bf16 v[2:5], v[130:133], v[98:101], v[30:33]
	v_mfma_f32_16x16x32_bf16 v[126:129], v[138:141], v[106:109], v[2:5]
	v_mfma_f32_16x16x32_bf16 v[2:5], v[130:133], v[190:193], v[42:45]
	v_mfma_f32_16x16x32_bf16 v[118:121], v[138:141], v[194:197], v[2:5]
	v_mfma_f32_16x16x32_bf16 v[2:5], v[198:201], v[98:101], v[54:57]
	v_mfma_f32_16x16x32_bf16 v[110:113], v[208:211], v[106:109], v[2:5]
	v_mfma_f32_16x16x32_bf16 v[2:5], v[198:201], v[190:193], v[66:69]
	v_mfma_f32_16x16x32_bf16 v[102:105], v[208:211], v[194:197], v[2:5]
	s_setprio 0
	s_barrier
	ds_read_b128 v[30:33], v162 offset:49152
	ds_read_b128 v[42:45], v162 offset:50176
	ds_read_b128 v[54:57], v162 offset:51200
	ds_read_b128 v[212:215], v162 offset:52224
	s_waitcnt vmcnt(0)
	s_barrier
	s_waitcnt lgkmcnt(0)
	s_setprio 1
	s_waitcnt lgkmcnt(0)
	v_mfma_f32_16x16x32_bf16 v[2:5], v[58:61], v[30:33], v[14:17]
	v_mfma_f32_16x16x32_bf16 v[94:97], v[70:73], v[42:45], v[2:5]
	v_mfma_f32_16x16x32_bf16 v[2:5], v[58:61], v[54:57], v[22:25]
	v_mfma_f32_16x16x32_bf16 v[58:61], v[70:73], v[212:215], v[2:5]
	v_mfma_f32_16x16x32_bf16 v[2:5], v[114:117], v[30:33], v[34:37]
	v_mfma_f32_16x16x32_bf16 v[74:77], v[122:125], v[42:45], v[2:5]
	v_mfma_f32_16x16x32_bf16 v[2:5], v[114:117], v[54:57], v[46:49]
	v_mfma_f32_16x16x32_bf16 v[10:13], v[122:125], v[212:215], v[2:5]
	v_mfma_f32_16x16x32_bf16 v[2:5], v[130:133], v[30:33], v[150:153]
	v_mfma_f32_16x16x32_bf16 v[70:73], v[138:141], v[42:45], v[2:5]
	v_mfma_f32_16x16x32_bf16 v[2:5], v[130:133], v[54:57], v[154:157]
	v_mfma_f32_16x16x32_bf16 v[6:9], v[138:141], v[212:215], v[2:5]
	v_mfma_f32_16x16x32_bf16 v[2:5], v[198:201], v[30:33], v[78:81]
	v_mfma_f32_16x16x32_bf16 v[66:69], v[208:211], v[42:45], v[2:5]
	v_mfma_f32_16x16x32_bf16 v[2:5], v[198:201], v[54:57], v[86:89]
	v_mfma_f32_16x16x32_bf16 v[2:5], v[208:211], v[212:215], v[2:5]
	s_setprio 0
	s_barrier
	ds_read_b128 v[14:17], v175 offset:49152
	ds_read_b128 v[18:21], v175 offset:50176
	ds_read_b128 v[22:25], v175 offset:51200
	ds_read_b128 v[34:37], v175 offset:52224
	ds_read_b128 v[46:49], v175 offset:53248
	ds_read_b128 v[78:81], v175 offset:54272
	ds_read_b128 v[198:201], v175 offset:55296
	ds_read_b128 v[208:211], v175 offset:56320
	s_barrier
	s_waitcnt lgkmcnt(0)
	s_setprio 1
	s_waitcnt lgkmcnt(0)
	v_mfma_f32_16x16x32_bf16 v[26:29], v[14:17], v[98:101], v[26:29]
	v_mfma_f32_16x16x32_bf16 v[154:157], v[18:21], v[106:109], v[26:29]
	v_mfma_f32_16x16x32_bf16 v[26:29], v[14:17], v[190:193], v[38:41]
	v_mfma_f32_16x16x32_bf16 v[150:153], v[18:21], v[194:197], v[26:29]
	v_mfma_f32_16x16x32_bf16 v[26:29], v[22:25], v[98:101], v[50:53]
	v_mfma_f32_16x16x32_bf16 v[138:141], v[34:37], v[106:109], v[26:29]
	v_mfma_f32_16x16x32_bf16 v[26:29], v[22:25], v[190:193], v[62:65]
	v_mfma_f32_16x16x32_bf16 v[130:133], v[34:37], v[194:197], v[26:29]
	v_mfma_f32_16x16x32_bf16 v[26:29], v[46:49], v[98:101], v[216:219]
	v_mfma_f32_16x16x32_bf16 v[122:125], v[78:81], v[106:109], v[26:29]
	v_mfma_f32_16x16x32_bf16 v[26:29], v[46:49], v[190:193], v[82:85]
	v_mfma_f32_16x16x32_bf16 v[114:117], v[78:81], v[194:197], v[26:29]
	v_mfma_f32_16x16x32_bf16 v[26:29], v[198:201], v[98:101], v[90:93]
	v_mfma_f32_16x16x32_bf16 v[106:109], v[208:211], v[106:109], v[26:29]
	v_mfma_f32_16x16x32_bf16 v[26:29], v[198:201], v[190:193], v[220:223]
	v_mfma_f32_16x16x32_bf16 v[98:101], v[208:211], v[194:197], v[26:29]
	s_setprio 0
	s_setprio 1
	v_mfma_f32_16x16x32_bf16 v[26:29], v[14:17], v[30:33], v[224:227]
	v_mfma_f32_16x16x32_bf16 v[14:17], v[14:17], v[54:57], v[228:231]
	v_mfma_f32_16x16x32_bf16 v[90:93], v[18:21], v[42:45], v[26:29]
	v_mfma_f32_16x16x32_bf16 v[26:29], v[18:21], v[212:215], v[14:17]
	v_mfma_f32_16x16x32_bf16 v[14:17], v[22:25], v[30:33], v[232:235]
	v_mfma_f32_16x16x32_bf16 v[86:89], v[34:37], v[42:45], v[14:17]
	v_mfma_f32_16x16x32_bf16 v[14:17], v[22:25], v[54:57], v[236:239]
	v_mfma_f32_16x16x32_bf16 v[22:25], v[34:37], v[212:215], v[14:17]
	v_mfma_f32_16x16x32_bf16 v[14:17], v[46:49], v[30:33], v[240:243]
	v_mfma_f32_16x16x32_bf16 v[82:85], v[78:81], v[42:45], v[14:17]
	v_mfma_f32_16x16x32_bf16 v[14:17], v[46:49], v[54:57], v[178:181]
	v_mfma_f32_16x16x32_bf16 v[18:21], v[78:81], v[212:215], v[14:17]
	v_mfma_f32_16x16x32_bf16 v[14:17], v[198:201], v[30:33], v[182:185]
	v_mfma_f32_16x16x32_bf16 v[78:81], v[208:211], v[42:45], v[14:17]
	v_mfma_f32_16x16x32_bf16 v[14:17], v[198:201], v[54:57], v[186:189]
	v_mfma_f32_16x16x32_bf16 v[14:17], v[208:211], v[212:215], v[14:17]
	s_setprio 0
	s_barrier
	s_and_saveexec_b64 s[8:9], s[6:7]
	s_cbranch_execz .LBB0_299
	s_barrier

; #define LDA(dst, b, h)                                                                                     \
;   _Pragma("unroll") for (int m = 0; m < 4; ++m) _Pragma("unroll") for (int k = 0; k < 2; ++k) dst[m][k] = \
;       *reinterpret_cast<const bf16x8*>(shmc + aL + (((b) * 2 + (h)) * 16384 + (m * 2 + k) * 1024))
; #define LDB(dst, b, h)                                                                                     \
;   _Pragma("unroll") for (int n = 0; n < 2; ++n) _Pragma("unroll") for (int k = 0; k < 2; ++k) dst[n][k] = \
;       *reinterpret_cast<const bf16x8*>(shmc + bL + (((b) * 2 + (h)) * 16384 + (n * 2 + k) * 1024))
; #define OPAQ asm volatile("" : "+v"(aL), "+v"(bL))
; #define WAIT_V(n) asm volatile("s_waitcnt vmcnt(" #n ")" ::: "memory")
; #define WAIT_L(n) asm volatile("s_waitcnt lgkmcnt(" #n ")" ::: "memory")
; #define BAR __builtin_amdgcn_s_barrier()
; #define SCHED __builtin_amdgcn_sched_barrier(0)
; template <int EPI>
; __device__ __forceinline__ void phase_gemm(const Params& p, const GemmDesc& d, char* shmc) {
;     ...
;     for (int t = 0; t < nt - 2; t += 2) {
;       OPAQ;
;       LDB(B0, 0, 0); SCHED; LDA(At, 0, 0); STAGE_A(SA(1, 1), 1, t + 1);
;       WAIT_L(8); BAR; WAIT_L(0); MMA(0, 0, At, B0); BAR; SCHED;
;       LDB(B1, 0, 1); STAGE_B(SB(0, 0), 0, t + 2);
;       BAR; WAIT_L(0); MMA(0, 1, At, B1); BAR;
;       LDA(At, 0, 1); STAGE_A(SA(0, 0), 0, t + 2);
;       BAR; WAIT_L(0); MMA(1, 0, At, B0); BAR; SCHED;
;       STAGE_B(SB(0, 1), 1, t + 2);
;       WAIT_V(6); BAR; MMA(1, 1, At, B1); BAR;
.LBB0_455:
	s_nop 0
	v_add_u32_e32 v130, 0, v153
	v_add_u32_e32 v141, 0, v152
	ds_read_b128 v[156:159], v130
	ds_read_b128 v[160:163], v130 offset:1024
	ds_read_b128 v[164:167], v130 offset:2048
	ds_read_b128 v[168:171], v130 offset:3072
	ds_read_b128 v[204:207], v130 offset:16384
	ds_read_b128 v[208:211], v130 offset:17408
	ds_read_b128 v[212:215], v130 offset:18432
	ds_read_b128 v[216:219], v130 offset:19456
	ds_read_b128 v[172:175], v141
	ds_read_b128 v[176:179], v141 offset:1024
	ds_read_b128 v[180:183], v141 offset:2048
	ds_read_b128 v[184:187], v141 offset:3072
	ds_read_b128 v[188:191], v141 offset:4096
	ds_read_b128 v[192:195], v141 offset:5120
	ds_read_b128 v[196:199], v141 offset:6144
	ds_read_b128 v[200:203], v141 offset:7168
	s_mov_b32 m0, s70
	s_nop 0
	global_load_lds_dwordx4 v220, s[98:99]
	s_mov_b32 m0, s71
	s_nop 0
	global_load_lds_dwordx4 v221, s[98:99]
	s_waitcnt vmcnt(8)
	s_waitcnt lgkmcnt(0)
	s_barrier
	v_mfma_f32_16x16x32_bf16 v[126:129], v[156:159], v[172:175], v[126:129]
	v_mfma_f32_16x16x32_bf16 v[122:125], v[164:167], v[172:175], v[122:125]
	v_mfma_f32_16x16x32_bf16 v[118:121], v[156:159], v[180:183], v[118:121]
	v_mfma_f32_16x16x32_bf16 v[114:117], v[164:167], v[180:183], v[114:117]
	v_mfma_f32_16x16x32_bf16 v[110:113], v[156:159], v[188:191], v[110:113]
	v_mfma_f32_16x16x32_bf16 v[106:109], v[164:167], v[188:191], v[106:109]
	v_mfma_f32_16x16x32_bf16 v[102:105], v[156:159], v[196:199], v[102:105]
	v_mfma_f32_16x16x32_bf16 v[98:101], v[164:167], v[196:199], v[98:101]
	v_mfma_f32_16x16x32_bf16 v[126:129], v[160:163], v[176:179], v[126:129]
	v_mfma_f32_16x16x32_bf16 v[122:125], v[168:171], v[176:179], v[122:125]
	v_mfma_f32_16x16x32_bf16 v[118:121], v[160:163], v[184:187], v[118:121]
	v_mfma_f32_16x16x32_bf16 v[114:117], v[168:171], v[184:187], v[114:117]
	v_mfma_f32_16x16x32_bf16 v[110:113], v[160:163], v[192:195], v[110:113]
	v_mfma_f32_16x16x32_bf16 v[106:109], v[168:171], v[192:195], v[106:109]
	v_mfma_f32_16x16x32_bf16 v[102:105], v[160:163], v[200:203], v[102:105]
	v_mfma_f32_16x16x32_bf16 v[98:101], v[168:171], v[200:203], v[98:101]
	v_mfma_f32_16x16x32_bf16 v[86:89], v[204:207], v[172:175], v[86:89]
	v_mfma_f32_16x16x32_bf16 v[70:73], v[212:215], v[172:175], v[70:73]
	v_mfma_f32_16x16x32_bf16 v[54:57], v[204:207], v[180:183], v[54:57]
	v_mfma_f32_16x16x32_bf16 v[50:53], v[212:215], v[180:183], v[50:53]
	v_mfma_f32_16x16x32_bf16 v[46:49], v[204:207], v[188:191], v[46:49]
	v_mfma_f32_16x16x32_bf16 v[42:45], v[212:215], v[188:191], v[42:45]
	v_mfma_f32_16x16x32_bf16 v[38:41], v[204:207], v[196:199], v[38:41]
	v_mfma_f32_16x16x32_bf16 v[34:37], v[212:215], v[196:199], v[34:37]
	v_mfma_f32_16x16x32_bf16 v[86:89], v[208:211], v[176:179], v[86:89]
	v_mfma_f32_16x16x32_bf16 v[70:73], v[216:219], v[176:179], v[70:73]
	v_mfma_f32_16x16x32_bf16 v[54:57], v[208:211], v[184:187], v[54:57]
	v_mfma_f32_16x16x32_bf16 v[50:53], v[216:219], v[184:187], v[50:53]
	v_mfma_f32_16x16x32_bf16 v[46:49], v[208:211], v[192:195], v[46:49]
	v_mfma_f32_16x16x32_bf16 v[42:45], v[216:219], v[192:195], v[42:45]
	v_mfma_f32_16x16x32_bf16 v[38:41], v[208:211], v[200:203], v[38:41]
	v_mfma_f32_16x16x32_bf16 v[34:37], v[216:219], v[200:203], v[34:37]
	s_barrier
	ds_read_b128 v[172:175], v141 offset:16384
	ds_read_b128 v[176:179], v141 offset:17408
	ds_read_b128 v[180:183], v141 offset:18432
	ds_read_b128 v[184:187], v141 offset:19456
	ds_read_b128 v[188:191], v141 offset:20480
	ds_read_b128 v[192:195], v141 offset:21504
	ds_read_b128 v[196:199], v141 offset:22528
	ds_read_b128 v[200:203], v141 offset:23552
	s_mov_b32 m0, s33
	s_nop 0
	global_load_lds_dwordx4 v222, s[100:101]
	s_mov_b32 m0, s34
	s_nop 0
	global_load_lds_dwordx4 v223, s[100:101]
	s_mov_b32 m0, s14
	s_nop 0
	global_load_lds_dwordx4 v224, s[98:99]
	s_mov_b32 m0, s35
	s_nop 0
	global_load_lds_dwordx4 v225, s[98:99]
	s_mov_b32 m0, s58
	s_nop 0
	global_load_lds_dwordx4 v226, s[100:101]
	s_mov_b32 m0, s59
	s_nop 0
	global_load_lds_dwordx4 v227, s[100:101]
	s_waitcnt vmcnt(8)
	s_waitcnt lgkmcnt(0)
	s_barrier
	v_mfma_f32_16x16x32_bf16 v[30:33], v[156:159], v[172:175], v[30:33]
	v_mfma_f32_16x16x32_bf16 v[26:29], v[164:167], v[172:175], v[26:29]
	v_mfma_f32_16x16x32_bf16 v[22:25], v[156:159], v[180:183], v[22:25]
	v_mfma_f32_16x16x32_bf16 v[18:21], v[164:167], v[180:183], v[18:21]
	v_mfma_f32_16x16x32_bf16 v[14:17], v[156:159], v[188:191], v[14:17]
	v_mfma_f32_16x16x32_bf16 v[10:13], v[164:167], v[188:191], v[10:13]
	v_mfma_f32_16x16x32_bf16 v[6:9], v[156:159], v[196:199], v[6:9]
	v_mfma_f32_16x16x32_bf16 v[2:5], v[164:167], v[196:199], v[2:5]
	v_mfma_f32_16x16x32_bf16 v[30:33], v[160:163], v[176:179], v[30:33]
	v_mfma_f32_16x16x32_bf16 v[26:29], v[168:171], v[176:179], v[26:29]
	v_mfma_f32_16x16x32_bf16 v[22:25], v[160:163], v[184:187], v[22:25]
	v_mfma_f32_16x16x32_bf16 v[18:21], v[168:171], v[184:187], v[18:21]
	v_mfma_f32_16x16x32_bf16 v[14:17], v[160:163], v[192:195], v[14:17]
	v_mfma_f32_16x16x32_bf16 v[10:13], v[168:171], v[192:195], v[10:13]
	v_mfma_f32_16x16x32_bf16 v[6:9], v[160:163], v[200:203], v[6:9]
	v_mfma_f32_16x16x32_bf16 v[2:5], v[168:171], v[200:203], v[2:5]
	v_mfma_f32_16x16x32_bf16 v[58:61], v[204:207], v[172:175], v[58:61]
	v_mfma_f32_16x16x32_bf16 v[62:65], v[212:215], v[172:175], v[62:65]
	v_mfma_f32_16x16x32_bf16 v[66:69], v[204:207], v[180:183], v[66:69]
	v_mfma_f32_16x16x32_bf16 v[74:77], v[212:215], v[180:183], v[74:77]
	v_mfma_f32_16x16x32_bf16 v[78:81], v[204:207], v[188:191], v[78:81]
	v_mfma_f32_16x16x32_bf16 v[82:85], v[212:215], v[188:191], v[82:85]
	v_mfma_f32_16x16x32_bf16 v[90:93], v[204:207], v[196:199], v[90:93]
	v_mfma_f32_16x16x32_bf16 v[94:97], v[212:215], v[196:199], v[94:97]
	v_mfma_f32_16x16x32_bf16 v[58:61], v[208:211], v[176:179], v[58:61]
	v_mfma_f32_16x16x32_bf16 v[62:65], v[216:219], v[176:179], v[62:65]
	v_mfma_f32_16x16x32_bf16 v[66:69], v[208:211], v[184:187], v[66:69]
	v_mfma_f32_16x16x32_bf16 v[74:77], v[216:219], v[184:187], v[74:77]
	v_mfma_f32_16x16x32_bf16 v[78:81], v[208:211], v[192:195], v[78:81]
	v_mfma_f32_16x16x32_bf16 v[82:85], v[216:219], v[192:195], v[82:85]
	v_mfma_f32_16x16x32_bf16 v[90:93], v[208:211], v[200:203], v[90:93]
	v_mfma_f32_16x16x32_bf16 v[94:97], v[216:219], v[200:203], v[94:97]
	s_barrier
; #define LDA(dst, b, h)                                                                                     \
;   _Pragma("unroll") for (int m = 0; m < 4; ++m) _Pragma("unroll") for (int k = 0; k < 2; ++k) dst[m][k] = \
;       *reinterpret_cast<const bf16x8*>(shmc + aL + (((b) * 2 + (h)) * 16384 + (m * 2 + k) * 1024))
; #define LDB(dst, b, h)                                                                                     \
;   _Pragma("unroll") for (int n = 0; n < 2; ++n) _Pragma("unroll") for (int k = 0; k < 2; ++k) dst[n][k] = \
;       *reinterpret_cast<const bf16x8*>(shmc + bL + (((b) * 2 + (h)) * 16384 + (n * 2 + k) * 1024))
; #define WAIT_V(n) asm volatile("s_waitcnt vmcnt(" #n ")" ::: "memory")
; #define WAIT_L(n) asm volatile("s_waitcnt lgkmcnt(" #n ")" ::: "memory")
; #define BAR __builtin_amdgcn_s_barrier()
; #define SCHED __builtin_amdgcn_sched_barrier(0)
; template <int EPI>
; __device__ __forceinline__ void phase_gemm(const Params& p, const GemmDesc& d, char* shmc) {
;     ...
;       LDB(B0, 1, 0); SCHED; LDA(At, 1, 0); STAGE_A(SA(0, 1), 1, t + 2);
;       WAIT_L(8); BAR; WAIT_L(0); MMA(0, 0, At, B0); BAR; SCHED;
;       LDB(B1, 1, 1); STAGE_B(SB(1, 0), 0, t + 3);
;       BAR; WAIT_L(0); MMA(0, 1, At, B1); BAR;
;       LDA(At, 1, 1); STAGE_A(SA(1, 0), 0, t + 3);
;       BAR; WAIT_L(0); MMA(1, 0, At, B0); BAR; SCHED;
;       STAGE_B(SB(1, 1), 1, t + 3);
;       WAIT_V(6); BAR; MMA(1, 1, At, B1); BAR;
;     }
	ds_read_b128 v[156:159], v130 offset:32768
	ds_read_b128 v[160:163], v130 offset:33792
	ds_read_b128 v[164:167], v130 offset:34816
	ds_read_b128 v[168:171], v130 offset:35840
	ds_read_b128 v[204:207], v130 offset:49152
	ds_read_b128 v[208:211], v130 offset:50176
	ds_read_b128 v[212:215], v130 offset:51200
	ds_read_b128 v[216:219], v130 offset:52224
	ds_read_b128 v[172:175], v141 offset:32768
	ds_read_b128 v[176:179], v141 offset:33792
	ds_read_b128 v[180:183], v141 offset:34816
	ds_read_b128 v[184:187], v141 offset:35840
	ds_read_b128 v[188:191], v141 offset:36864
	ds_read_b128 v[192:195], v141 offset:37888
	ds_read_b128 v[196:199], v141 offset:38912
	ds_read_b128 v[200:203], v141 offset:39936
	s_mov_b32 m0, s60
	s_nop 0
	global_load_lds_dwordx4 v228, s[98:99]
	s_mov_b32 m0, s61
	s_nop 0
	global_load_lds_dwordx4 v229, s[98:99]
	s_waitcnt vmcnt(8)
	s_waitcnt lgkmcnt(0)
	s_barrier
	v_mfma_f32_16x16x32_bf16 v[126:129], v[156:159], v[172:175], v[126:129]
	v_mfma_f32_16x16x32_bf16 v[122:125], v[164:167], v[172:175], v[122:125]
	v_mfma_f32_16x16x32_bf16 v[118:121], v[156:159], v[180:183], v[118:121]
	v_mfma_f32_16x16x32_bf16 v[114:117], v[164:167], v[180:183], v[114:117]
	v_mfma_f32_16x16x32_bf16 v[110:113], v[156:159], v[188:191], v[110:113]
	v_mfma_f32_16x16x32_bf16 v[106:109], v[164:167], v[188:191], v[106:109]
	v_mfma_f32_16x16x32_bf16 v[102:105], v[156:159], v[196:199], v[102:105]
	v_mfma_f32_16x16x32_bf16 v[98:101], v[164:167], v[196:199], v[98:101]
	v_mfma_f32_16x16x32_bf16 v[126:129], v[160:163], v[176:179], v[126:129]
	v_mfma_f32_16x16x32_bf16 v[122:125], v[168:171], v[176:179], v[122:125]
	v_mfma_f32_16x16x32_bf16 v[118:121], v[160:163], v[184:187], v[118:121]
	v_mfma_f32_16x16x32_bf16 v[114:117], v[168:171], v[184:187], v[114:117]
	v_mfma_f32_16x16x32_bf16 v[110:113], v[160:163], v[192:195], v[110:113]
	v_mfma_f32_16x16x32_bf16 v[106:109], v[168:171], v[192:195], v[106:109]
	v_mfma_f32_16x16x32_bf16 v[102:105], v[160:163], v[200:203], v[102:105]
	v_mfma_f32_16x16x32_bf16 v[98:101], v[168:171], v[200:203], v[98:101]
	v_mfma_f32_16x16x32_bf16 v[86:89], v[204:207], v[172:175], v[86:89]
	v_mfma_f32_16x16x32_bf16 v[70:73], v[212:215], v[172:175], v[70:73]
	v_mfma_f32_16x16x32_bf16 v[54:57], v[204:207], v[180:183], v[54:57]
	v_mfma_f32_16x16x32_bf16 v[50:53], v[212:215], v[180:183], v[50:53]
	v_mfma_f32_16x16x32_bf16 v[46:49], v[204:207], v[188:191], v[46:49]
	v_mfma_f32_16x16x32_bf16 v[42:45], v[212:215], v[188:191], v[42:45]
	v_mfma_f32_16x16x32_bf16 v[38:41], v[204:207], v[196:199], v[38:41]
	v_mfma_f32_16x16x32_bf16 v[34:37], v[212:215], v[196:199], v[34:37]
	v_mfma_f32_16x16x32_bf16 v[86:89], v[208:211], v[176:179], v[86:89]
	v_mfma_f32_16x16x32_bf16 v[70:73], v[216:219], v[176:179], v[70:73]
	v_mfma_f32_16x16x32_bf16 v[54:57], v[208:211], v[184:187], v[54:57]
	v_mfma_f32_16x16x32_bf16 v[50:53], v[216:219], v[184:187], v[50:53]
	v_mfma_f32_16x16x32_bf16 v[46:49], v[208:211], v[192:195], v[46:49]
	v_mfma_f32_16x16x32_bf16 v[42:45], v[216:219], v[192:195], v[42:45]
	v_mfma_f32_16x16x32_bf16 v[38:41], v[208:211], v[200:203], v[38:41]
	v_mfma_f32_16x16x32_bf16 v[34:37], v[216:219], v[200:203], v[34:37]
	s_barrier
	ds_read_b128 v[172:175], v141 offset:49152
	ds_read_b128 v[176:179], v141 offset:50176
	ds_read_b128 v[180:183], v141 offset:51200
	ds_read_b128 v[184:187], v141 offset:52224
	ds_read_b128 v[188:191], v141 offset:53248
	ds_read_b128 v[192:195], v141 offset:54272
	ds_read_b128 v[196:199], v141 offset:55296
	ds_read_b128 v[200:203], v141 offset:56320
	s_mov_b32 m0, s62
	s_nop 0
	global_load_lds_dwordx4 v232, s[100:101]
	s_mov_b32 m0, s63
	s_nop 0
	global_load_lds_dwordx4 v233, s[100:101]
	s_mov_b32 m0, s64
	s_nop 0
	global_load_lds_dwordx4 v234, s[98:99]
	s_mov_b32 m0, s65
	s_nop 0
	global_load_lds_dwordx4 v235, s[98:99]
	s_mov_b32 m0, s68
	s_nop 0
	global_load_lds_dwordx4 v236, s[100:101]
	s_mov_b32 m0, s69
	s_nop 0
	global_load_lds_dwordx4 v237, s[100:101]
	s_add_i32 s54, s54, 2
	s_add_u32 s52, s52, 0x100
	s_addc_u32 s53, s53, 0
	s_add_u32 s98, s98, 0x100
	s_addc_u32 s99, s99, 0
	s_add_u32 s100, s100, 0x100
	s_addc_u32 s101, s101, 0
	s_cmpk_gt_u32 s54, 0x53
	s_waitcnt vmcnt(8)
	s_waitcnt lgkmcnt(0)
	s_barrier
	v_mfma_f32_16x16x32_bf16 v[30:33], v[156:159], v[172:175], v[30:33]
	v_mfma_f32_16x16x32_bf16 v[26:29], v[164:167], v[172:175], v[26:29]
	v_mfma_f32_16x16x32_bf16 v[22:25], v[156:159], v[180:183], v[22:25]
	v_mfma_f32_16x16x32_bf16 v[18:21], v[164:167], v[180:183], v[18:21]
	v_mfma_f32_16x16x32_bf16 v[14:17], v[156:159], v[188:191], v[14:17]
	v_mfma_f32_16x16x32_bf16 v[10:13], v[164:167], v[188:191], v[10:13]
	v_mfma_f32_16x16x32_bf16 v[6:9], v[156:159], v[196:199], v[6:9]
	v_mfma_f32_16x16x32_bf16 v[2:5], v[164:167], v[196:199], v[2:5]
	v_mfma_f32_16x16x32_bf16 v[30:33], v[160:163], v[176:179], v[30:33]
	v_mfma_f32_16x16x32_bf16 v[26:29], v[168:171], v[176:179], v[26:29]
	v_mfma_f32_16x16x32_bf16 v[22:25], v[160:163], v[184:187], v[22:25]
	v_mfma_f32_16x16x32_bf16 v[18:21], v[168:171], v[184:187], v[18:21]
	v_mfma_f32_16x16x32_bf16 v[14:17], v[160:163], v[192:195], v[14:17]
	v_mfma_f32_16x16x32_bf16 v[10:13], v[168:171], v[192:195], v[10:13]
	v_mfma_f32_16x16x32_bf16 v[6:9], v[160:163], v[200:203], v[6:9]
	v_mfma_f32_16x16x32_bf16 v[2:5], v[168:171], v[200:203], v[2:5]
	v_mfma_f32_16x16x32_bf16 v[58:61], v[204:207], v[172:175], v[58:61]
	v_mfma_f32_16x16x32_bf16 v[62:65], v[212:215], v[172:175], v[62:65]
	v_mfma_f32_16x16x32_bf16 v[66:69], v[204:207], v[180:183], v[66:69]
	v_mfma_f32_16x16x32_bf16 v[74:77], v[212:215], v[180:183], v[74:77]
	v_mfma_f32_16x16x32_bf16 v[78:81], v[204:207], v[188:191], v[78:81]
	v_mfma_f32_16x16x32_bf16 v[82:85], v[212:215], v[188:191], v[82:85]
	v_mfma_f32_16x16x32_bf16 v[90:93], v[204:207], v[196:199], v[90:93]
	v_mfma_f32_16x16x32_bf16 v[94:97], v[212:215], v[196:199], v[94:97]
	v_mfma_f32_16x16x32_bf16 v[58:61], v[208:211], v[176:179], v[58:61]
	v_mfma_f32_16x16x32_bf16 v[62:65], v[216:219], v[176:179], v[62:65]
	v_mfma_f32_16x16x32_bf16 v[66:69], v[208:211], v[184:187], v[66:69]
	v_mfma_f32_16x16x32_bf16 v[74:77], v[216:219], v[184:187], v[74:77]
	v_mfma_f32_16x16x32_bf16 v[78:81], v[208:211], v[192:195], v[78:81]
	v_mfma_f32_16x16x32_bf16 v[82:85], v[216:219], v[192:195], v[82:85]
	v_mfma_f32_16x16x32_bf16 v[90:93], v[208:211], v[200:203], v[90:93]
	v_mfma_f32_16x16x32_bf16 v[94:97], v[216:219], v[200:203], v[94:97]
	s_barrier
; #define LDA(dst, b, h)                                                                                     \
;   _Pragma("unroll") for (int m = 0; m < 4; ++m) _Pragma("unroll") for (int k = 0; k < 2; ++k) dst[m][k] = \
;       *reinterpret_cast<const bf16x8*>(shmc + aL + (((b) * 2 + (h)) * 16384 + (m * 2 + k) * 1024))
; #define LDB(dst, b, h)                                                                                     \
;   _Pragma("unroll") for (int n = 0; n < 2; ++n) _Pragma("unroll") for (int k = 0; k < 2; ++k) dst[n][k] = \
;       *reinterpret_cast<const bf16x8*>(shmc + bL + (((b) * 2 + (h)) * 16384 + (n * 2 + k) * 1024))
; #define OPAQ asm volatile("" : "+v"(aL), "+v"(bL))
; #define WAIT_V(n) asm volatile("s_waitcnt vmcnt(" #n ")" ::: "memory")
; #define WAIT_L(n) asm volatile("s_waitcnt lgkmcnt(" #n ")" ::: "memory")
; #define BAR __builtin_amdgcn_s_barrier()
; template <int EPI>
; __device__ __forceinline__ void phase_gemm(const Params& p, const GemmDesc& d, char* shmc) {
;     ...
;     }
;     {
;       OPAQ;
;       LDB(B0, 0, 0); LDA(At, 0, 0); STAGE_A(SA(1, 1), 1, nt - 1);
;       BAR; WAIT_L(0); MMA(0, 0, At, B0); BAR;
;       LDB(B1, 0, 1); BAR; WAIT_L(0); MMA(0, 1, At, B1); BAR;
;       LDA(At, 0, 1); WAIT_V(4); BAR; WAIT_L(0); MMA(1, 0, At, B0); MMA(1, 1, At, B1); BAR;
;     }
	s_cbranch_scc0 .LBB0_455
	s_setprio 0
	s_add_u32 s48, s48, 0x162b80
	s_addc_u32 s49, s49, 0
	v_add_u32_e32 v130, 0, v153
	v_add_u32_e32 v141, 0, v152
	s_mov_b32 m0, s70
	ds_read_b128 v[144:147], v130
	ds_read_b128 v[148:151], v130 offset:1024
	ds_read_b128 v[156:159], v130 offset:2048
	ds_read_b128 v[160:163], v130 offset:3072
	ds_read_b128 v[164:167], v141
	ds_read_b128 v[168:171], v141 offset:1024
	ds_read_b128 v[172:175], v141 offset:2048
	ds_read_b128 v[176:179], v141 offset:3072
	ds_read_b128 v[180:183], v141 offset:4096
	ds_read_b128 v[184:187], v141 offset:5120
	ds_read_b128 v[188:191], v141 offset:6144
	ds_read_b128 v[192:195], v141 offset:7168
	global_load_lds_dwordx4 v140, s[48:49]
	s_mov_b32 m0, s71
	s_nop 0
	global_load_lds_dwordx4 v142, s[48:49]
	s_waitcnt vmcnt(8)
	s_barrier
	s_waitcnt lgkmcnt(0)
	s_setprio 1
	s_waitcnt lgkmcnt(0)
	v_mfma_f32_16x16x32_bf16 v[126:129], v[144:147], v[164:167], v[126:129]
	v_mfma_f32_16x16x32_bf16 v[122:125], v[156:159], v[164:167], v[122:125]
	v_mfma_f32_16x16x32_bf16 v[114:117], v[156:159], v[172:175], v[114:117]
	v_mfma_f32_16x16x32_bf16 v[110:113], v[144:147], v[180:183], v[110:113]
	v_mfma_f32_16x16x32_bf16 v[102:105], v[144:147], v[188:191], v[102:105]
	v_mfma_f32_16x16x32_bf16 v[126:129], v[148:151], v[168:171], v[126:129]
	v_mfma_f32_16x16x32_bf16 v[122:125], v[160:163], v[168:171], v[122:125]
	v_mfma_f32_16x16x32_bf16 v[118:121], v[144:147], v[172:175], v[118:121]
	v_mfma_f32_16x16x32_bf16 v[114:117], v[160:163], v[176:179], v[114:117]
	v_mfma_f32_16x16x32_bf16 v[110:113], v[148:151], v[184:187], v[110:113]
	v_mfma_f32_16x16x32_bf16 v[106:109], v[156:159], v[180:183], v[106:109]
	v_mfma_f32_16x16x32_bf16 v[102:105], v[148:151], v[192:195], v[102:105]
	v_mfma_f32_16x16x32_bf16 v[98:101], v[156:159], v[188:191], v[98:101]
	v_mfma_f32_16x16x32_bf16 v[196:199], v[148:151], v[176:179], v[118:121]
	v_mfma_f32_16x16x32_bf16 v[200:203], v[160:163], v[184:187], v[106:109]
	v_mfma_f32_16x16x32_bf16 v[204:207], v[160:163], v[192:195], v[98:101]
	s_setprio 0
	s_barrier
	s_nop 2
	ds_read_b128 v[98:101], v130 offset:16384
	ds_read_b128 v[106:109], v130 offset:17408
	ds_read_b128 v[118:121], v130 offset:18432
	ds_read_b128 v[208:211], v130 offset:19456
	s_barrier
	s_waitcnt lgkmcnt(0)
	s_setprio 1
	s_waitcnt lgkmcnt(0)
	v_mfma_f32_16x16x32_bf16 v[86:89], v[98:101], v[164:167], v[86:89]
	v_mfma_f32_16x16x32_bf16 v[70:73], v[118:121], v[164:167], v[70:73]
	v_mfma_f32_16x16x32_bf16 v[54:57], v[98:101], v[172:175], v[54:57]
	v_mfma_f32_16x16x32_bf16 v[50:53], v[118:121], v[172:175], v[50:53]
	v_mfma_f32_16x16x32_bf16 v[46:49], v[98:101], v[180:183], v[46:49]
	v_mfma_f32_16x16x32_bf16 v[42:45], v[118:121], v[180:183], v[42:45]
	v_mfma_f32_16x16x32_bf16 v[38:41], v[98:101], v[188:191], v[38:41]
	v_mfma_f32_16x16x32_bf16 v[34:37], v[118:121], v[188:191], v[34:37]
	v_mfma_f32_16x16x32_bf16 v[86:89], v[106:109], v[168:171], v[86:89]
	v_mfma_f32_16x16x32_bf16 v[70:73], v[208:211], v[168:171], v[70:73]
	v_mfma_f32_16x16x32_bf16 v[54:57], v[106:109], v[176:179], v[54:57]
	v_mfma_f32_16x16x32_bf16 v[50:53], v[208:211], v[176:179], v[50:53]
	v_mfma_f32_16x16x32_bf16 v[46:49], v[106:109], v[184:187], v[46:49]
	v_mfma_f32_16x16x32_bf16 v[42:45], v[208:211], v[184:187], v[42:45]
	v_mfma_f32_16x16x32_bf16 v[38:41], v[106:109], v[192:195], v[38:41]
	v_mfma_f32_16x16x32_bf16 v[34:37], v[208:211], v[192:195], v[34:37]
	s_setprio 0
	s_barrier
	ds_read_b128 v[164:167], v141 offset:16384
	ds_read_b128 v[168:171], v141 offset:17408
	ds_read_b128 v[172:175], v141 offset:18432
	ds_read_b128 v[176:179], v141 offset:19456
	ds_read_b128 v[180:183], v141 offset:20480
	ds_read_b128 v[184:187], v141 offset:21504
	ds_read_b128 v[188:191], v141 offset:22528
	ds_read_b128 v[192:195], v141 offset:23552
	s_waitcnt vmcnt(4)
	s_barrier
	s_waitcnt lgkmcnt(0)
	s_setprio 1
	s_waitcnt lgkmcnt(0)
	v_mfma_f32_16x16x32_bf16 v[30:33], v[144:147], v[164:167], v[30:33]
	v_mfma_f32_16x16x32_bf16 v[26:29], v[156:159], v[164:167], v[26:29]
	v_mfma_f32_16x16x32_bf16 v[22:25], v[144:147], v[172:175], v[22:25]
	v_mfma_f32_16x16x32_bf16 v[18:21], v[156:159], v[172:175], v[18:21]
	v_mfma_f32_16x16x32_bf16 v[14:17], v[144:147], v[180:183], v[14:17]
	v_mfma_f32_16x16x32_bf16 v[10:13], v[156:159], v[180:183], v[10:13]
	v_mfma_f32_16x16x32_bf16 v[6:9], v[144:147], v[188:191], v[6:9]
	v_mfma_f32_16x16x32_bf16 v[2:5], v[156:159], v[188:191], v[2:5]
	v_mfma_f32_16x16x32_bf16 v[30:33], v[148:151], v[168:171], v[30:33]
	v_mfma_f32_16x16x32_bf16 v[26:29], v[160:163], v[168:171], v[26:29]
	v_mfma_f32_16x16x32_bf16 v[22:25], v[148:151], v[176:179], v[22:25]
	v_mfma_f32_16x16x32_bf16 v[18:21], v[160:163], v[176:179], v[18:21]
	v_mfma_f32_16x16x32_bf16 v[14:17], v[148:151], v[184:187], v[14:17]
	v_mfma_f32_16x16x32_bf16 v[10:13], v[160:163], v[184:187], v[10:13]
	v_mfma_f32_16x16x32_bf16 v[6:9], v[148:151], v[192:195], v[6:9]
	v_mfma_f32_16x16x32_bf16 v[2:5], v[160:163], v[192:195], v[2:5]
	s_setprio 0
	s_setprio 1
	v_mfma_f32_16x16x32_bf16 v[62:65], v[118:121], v[164:167], v[62:65]
	v_mfma_f32_16x16x32_bf16 v[144:147], v[208:211], v[168:171], v[62:65]
	v_mfma_f32_16x16x32_bf16 v[62:65], v[98:101], v[172:175], v[66:69]
	v_mfma_f32_16x16x32_bf16 v[148:151], v[106:109], v[176:179], v[62:65]
	v_mfma_f32_16x16x32_bf16 v[62:65], v[118:121], v[172:175], v[74:77]
	v_mfma_f32_16x16x32_bf16 v[156:159], v[208:211], v[176:179], v[62:65]
	v_mfma_f32_16x16x32_bf16 v[62:65], v[98:101], v[180:183], v[78:81]
	v_mfma_f32_16x16x32_bf16 v[160:163], v[106:109], v[184:187], v[62:65]
	v_mfma_f32_16x16x32_bf16 v[62:65], v[118:121], v[180:183], v[82:85]
	v_mfma_f32_16x16x32_bf16 v[58:61], v[98:101], v[164:167], v[58:61]
	v_mfma_f32_16x16x32_bf16 v[164:167], v[208:211], v[184:187], v[62:65]
	v_mfma_f32_16x16x32_bf16 v[62:65], v[98:101], v[188:191], v[90:93]
	v_mfma_f32_16x16x32_bf16 v[58:61], v[106:109], v[168:171], v[58:61]
	v_mfma_f32_16x16x32_bf16 v[168:171], v[106:109], v[192:195], v[62:65]
	v_mfma_f32_16x16x32_bf16 v[62:65], v[118:121], v[188:191], v[94:97]
	v_mfma_f32_16x16x32_bf16 v[172:175], v[208:211], v[192:195], v[62:65]
	s_setprio 0
	s_barrier
; #define LDA(dst, b, h)                                                                                     \
;   _Pragma("unroll") for (int m = 0; m < 4; ++m) _Pragma("unroll") for (int k = 0; k < 2; ++k) dst[m][k] = \
;       *reinterpret_cast<const bf16x8*>(shmc + aL + (((b) * 2 + (h)) * 16384 + (m * 2 + k) * 1024))
; #define LDB(dst, b, h)                                                                                     \
;   _Pragma("unroll") for (int n = 0; n < 2; ++n) _Pragma("unroll") for (int k = 0; k < 2; ++k) dst[n][k] = \
;       *reinterpret_cast<const bf16x8*>(shmc + bL + (((b) * 2 + (h)) * 16384 + (n * 2 + k) * 1024))
; #define WAIT_V(n) asm volatile("s_waitcnt vmcnt(" #n ")" ::: "memory")
; #define WAIT_L(n) asm volatile("s_waitcnt lgkmcnt(" #n ")" ::: "memory")
; #define BAR __builtin_amdgcn_s_barrier()
; template <int EPI>
; __device__ __forceinline__ void phase_gemm(const Params& p, const GemmDesc& d, char* shmc) {
;     ...
;     {
;       LDB(B0, 1, 0); LDA(At, 1, 0); WAIT_V(2); BAR; WAIT_L(0); MMA(0, 0, At, B0); BAR;
;       LDB(B1, 1, 1); WAIT_V(0); BAR; WAIT_L(0); MMA(0, 1, At, B1); BAR;
;       LDA(At, 1, 1); BAR; WAIT_L(0); MMA(1, 0, At, B0); MMA(1, 1, At, B1); BAR;
;     }
;     if (wr == 0) BAR;
	ds_read_b128 v[176:179], v130 offset:32768
	ds_read_b128 v[180:183], v130 offset:33792
	ds_read_b128 v[184:187], v130 offset:34816
	ds_read_b128 v[188:191], v130 offset:35840
	s_nop 0
	ds_read_b128 v[62:65], v141 offset:32768
	ds_read_b128 v[78:81], v141 offset:33792
	ds_read_b128 v[94:97], v141 offset:34816
	ds_read_b128 v[192:195], v141 offset:35840
	ds_read_b128 v[208:211], v141 offset:36864
	ds_read_b128 v[212:215], v141 offset:37888
	ds_read_b128 v[216:219], v141 offset:38912
	ds_read_b128 v[220:223], v141 offset:39936
	s_waitcnt vmcnt(2)
	s_barrier
	s_waitcnt lgkmcnt(0)
	s_setprio 1
	s_waitcnt lgkmcnt(0)
	v_mfma_f32_16x16x32_bf16 v[66:69], v[176:179], v[62:65], v[126:129]
	v_mfma_f32_16x16x32_bf16 v[126:129], v[180:183], v[78:81], v[66:69]
	v_mfma_f32_16x16x32_bf16 v[66:69], v[184:187], v[62:65], v[122:125]
	v_mfma_f32_16x16x32_bf16 v[118:121], v[188:191], v[78:81], v[66:69]
	v_mfma_f32_16x16x32_bf16 v[66:69], v[176:179], v[94:97], v[196:199]
	v_mfma_f32_16x16x32_bf16 v[106:109], v[180:183], v[192:195], v[66:69]
	v_mfma_f32_16x16x32_bf16 v[66:69], v[184:187], v[94:97], v[114:117]
	v_mfma_f32_16x16x32_bf16 v[98:101], v[188:191], v[192:195], v[66:69]
	v_mfma_f32_16x16x32_bf16 v[66:69], v[176:179], v[208:211], v[110:113]
	v_mfma_f32_16x16x32_bf16 v[90:93], v[180:183], v[212:215], v[66:69]
	v_mfma_f32_16x16x32_bf16 v[66:69], v[184:187], v[208:211], v[200:203]
	v_mfma_f32_16x16x32_bf16 v[82:85], v[188:191], v[212:215], v[66:69]
	v_mfma_f32_16x16x32_bf16 v[66:69], v[176:179], v[216:219], v[102:105]
	v_mfma_f32_16x16x32_bf16 v[74:77], v[180:183], v[220:223], v[66:69]
	v_mfma_f32_16x16x32_bf16 v[66:69], v[184:187], v[216:219], v[204:207]
	v_mfma_f32_16x16x32_bf16 v[66:69], v[188:191], v[220:223], v[66:69]
	s_setprio 0
	s_barrier
	ds_read_b128 v[196:199], v130 offset:49152
	ds_read_b128 v[200:203], v130 offset:50176
	ds_read_b128 v[204:207], v130 offset:51200
	ds_read_b128 v[224:227], v130 offset:52224
	s_waitcnt vmcnt(0)
	s_barrier
	s_waitcnt lgkmcnt(0)
	s_setprio 1
	s_waitcnt lgkmcnt(0)
	v_mfma_f32_16x16x32_bf16 v[86:89], v[196:199], v[62:65], v[86:89]
	v_mfma_f32_16x16x32_bf16 v[62:65], v[204:207], v[62:65], v[70:73]
	v_mfma_f32_16x16x32_bf16 v[54:57], v[196:199], v[94:97], v[54:57]
	v_mfma_f32_16x16x32_bf16 v[50:53], v[204:207], v[94:97], v[50:53]
	v_mfma_f32_16x16x32_bf16 v[46:49], v[196:199], v[208:211], v[46:49]
	v_mfma_f32_16x16x32_bf16 v[42:45], v[204:207], v[208:211], v[42:45]
	v_mfma_f32_16x16x32_bf16 v[38:41], v[196:199], v[216:219], v[38:41]
	v_mfma_f32_16x16x32_bf16 v[34:37], v[204:207], v[216:219], v[34:37]
	v_mfma_f32_16x16x32_bf16 v[122:125], v[200:203], v[78:81], v[86:89]
	v_mfma_f32_16x16x32_bf16 v[114:117], v[224:227], v[78:81], v[62:65]
	v_mfma_f32_16x16x32_bf16 v[110:113], v[200:203], v[192:195], v[54:57]
	v_mfma_f32_16x16x32_bf16 v[102:105], v[224:227], v[192:195], v[50:53]
	v_mfma_f32_16x16x32_bf16 v[94:97], v[200:203], v[212:215], v[46:49]
	v_mfma_f32_16x16x32_bf16 v[86:89], v[224:227], v[212:215], v[42:45]
	v_mfma_f32_16x16x32_bf16 v[78:81], v[200:203], v[220:223], v[38:41]
	v_mfma_f32_16x16x32_bf16 v[70:73], v[224:227], v[220:223], v[34:37]
	s_setprio 0
	s_barrier
	s_nop 0
	ds_read_b128 v[34:37], v141 offset:49152
	ds_read_b128 v[42:45], v141 offset:50176
	ds_read_b128 v[192:195], v141 offset:51200
	ds_read_b128 v[208:211], v141 offset:52224
	ds_read_b128 v[212:215], v141 offset:53248
	ds_read_b128 v[216:219], v141 offset:54272
	ds_read_b128 v[220:223], v141 offset:55296
	ds_read_b128 v[228:231], v141 offset:56320
	s_barrier
	s_waitcnt lgkmcnt(0)
	s_setprio 1
	s_waitcnt lgkmcnt(0)
	v_mfma_f32_16x16x32_bf16 v[30:33], v[176:179], v[34:37], v[30:33]
	v_mfma_f32_16x16x32_bf16 v[26:29], v[184:187], v[34:37], v[26:29]
	v_mfma_f32_16x16x32_bf16 v[22:25], v[176:179], v[192:195], v[22:25]
	v_mfma_f32_16x16x32_bf16 v[18:21], v[184:187], v[192:195], v[18:21]
	v_mfma_f32_16x16x32_bf16 v[14:17], v[176:179], v[212:215], v[14:17]
	v_mfma_f32_16x16x32_bf16 v[10:13], v[184:187], v[212:215], v[10:13]
	v_mfma_f32_16x16x32_bf16 v[6:9], v[176:179], v[220:223], v[6:9]
	v_mfma_f32_16x16x32_bf16 v[2:5], v[184:187], v[220:223], v[2:5]
	v_mfma_f32_16x16x32_bf16 v[62:65], v[180:183], v[42:45], v[30:33]
	v_mfma_f32_16x16x32_bf16 v[54:57], v[188:191], v[42:45], v[26:29]
	v_mfma_f32_16x16x32_bf16 v[46:49], v[180:183], v[208:211], v[22:25]
	v_mfma_f32_16x16x32_bf16 v[38:41], v[188:191], v[208:211], v[18:21]
	v_mfma_f32_16x16x32_bf16 v[30:33], v[180:183], v[216:219], v[14:17]
	v_mfma_f32_16x16x32_bf16 v[22:25], v[188:191], v[216:219], v[10:13]
	v_mfma_f32_16x16x32_bf16 v[14:17], v[180:183], v[228:231], v[6:9]
	v_mfma_f32_16x16x32_bf16 v[6:9], v[188:191], v[228:231], v[2:5]
	s_setprio 0
	s_setprio 1
	v_mfma_f32_16x16x32_bf16 v[2:5], v[196:199], v[34:37], v[58:61]
	v_mfma_f32_16x16x32_bf16 v[58:61], v[200:203], v[42:45], v[2:5]
	v_mfma_f32_16x16x32_bf16 v[2:5], v[204:207], v[34:37], v[144:147]
	v_mfma_f32_16x16x32_bf16 v[50:53], v[224:227], v[42:45], v[2:5]
	v_mfma_f32_16x16x32_bf16 v[2:5], v[196:199], v[192:195], v[148:151]
	v_mfma_f32_16x16x32_bf16 v[42:45], v[200:203], v[208:211], v[2:5]
	v_mfma_f32_16x16x32_bf16 v[2:5], v[204:207], v[192:195], v[156:159]
	v_mfma_f32_16x16x32_bf16 v[34:37], v[224:227], v[208:211], v[2:5]
	v_mfma_f32_16x16x32_bf16 v[2:5], v[196:199], v[212:215], v[160:163]
	v_mfma_f32_16x16x32_bf16 v[26:29], v[200:203], v[216:219], v[2:5]
	v_mfma_f32_16x16x32_bf16 v[2:5], v[204:207], v[212:215], v[164:167]
	v_mfma_f32_16x16x32_bf16 v[18:21], v[224:227], v[216:219], v[2:5]
	v_mfma_f32_16x16x32_bf16 v[2:5], v[196:199], v[220:223], v[168:171]
	v_mfma_f32_16x16x32_bf16 v[10:13], v[200:203], v[228:231], v[2:5]
	v_mfma_f32_16x16x32_bf16 v[2:5], v[204:207], v[220:223], v[172:175]
	v_mfma_f32_16x16x32_bf16 v[2:5], v[224:227], v[228:231], v[2:5]
	s_setprio 0
	s_barrier
	s_and_saveexec_b64 s[48:49], s[4:5]
	s_cbranch_execz .LBB0_458
	s_barrier

; #define LDA(dst, b, h)                                                                                     \
;   _Pragma("unroll") for (int m = 0; m < 4; ++m) _Pragma("unroll") for (int k = 0; k < 2; ++k) dst[m][k] = \
;       *reinterpret_cast<const bf16x8*>(shmc + aL + (((b) * 2 + (h)) * 16384 + (m * 2 + k) * 1024))
; #define LDB(dst, b, h)                                                                                     \
;   _Pragma("unroll") for (int n = 0; n < 2; ++n) _Pragma("unroll") for (int k = 0; k < 2; ++k) dst[n][k] = \
;       *reinterpret_cast<const bf16x8*>(shmc + bL + (((b) * 2 + (h)) * 16384 + (n * 2 + k) * 1024))
; #define OPAQ asm volatile("" : "+v"(aL), "+v"(bL))
; #define WAIT_V(n) asm volatile("s_waitcnt vmcnt(" #n ")" ::: "memory")
; #define WAIT_L(n) asm volatile("s_waitcnt lgkmcnt(" #n ")" ::: "memory")
; #define BAR __builtin_amdgcn_s_barrier()
; #define SCHED __builtin_amdgcn_sched_barrier(0)
; template <int EPI>
; __device__ __forceinline__ void phase_gemm(const Params& p, const GemmDesc& d, char* shmc) {
;     ...
;     for (int t = 0; t < nt - 2; t += 2) {
;       OPAQ;
;       LDB(B0, 0, 0); SCHED; LDA(At, 0, 0); STAGE_A(SA(1, 1), 1, t + 1);
;       WAIT_L(8); BAR; WAIT_L(0); MMA(0, 0, At, B0); BAR; SCHED;
;       LDB(B1, 0, 1); STAGE_B(SB(0, 0), 0, t + 2);
;       BAR; WAIT_L(0); MMA(0, 1, At, B1); BAR;
;       LDA(At, 0, 1); STAGE_A(SA(0, 0), 0, t + 2);
;       BAR; WAIT_L(0); MMA(1, 0, At, B0); BAR; SCHED;
;       STAGE_B(SB(0, 1), 1, t + 2);
;       WAIT_V(6); BAR; MMA(1, 1, At, B1); BAR;
.LBB0_598:
	s_nop 0
	v_add_u32_e32 v175, 0, v179
	v_add_u32_e32 v176, 0, v177
	ds_read_b128 v[138:141], v175
	ds_read_b128 v[142:145], v175 offset:1024
	ds_read_b128 v[146:149], v175 offset:2048
	ds_read_b128 v[150:153], v175 offset:3072
	ds_read_b128 v[206:209], v175 offset:16384
	ds_read_b128 v[210:213], v175 offset:17408
	ds_read_b128 v[214:217], v175 offset:18432
	ds_read_b128 v[218:221], v175 offset:19456
	ds_read_b128 v[154:157], v176
	ds_read_b128 v[158:161], v176 offset:1024
	ds_read_b128 v[182:185], v176 offset:2048
	ds_read_b128 v[186:189], v176 offset:3072
	ds_read_b128 v[190:193], v176 offset:4096
	ds_read_b128 v[194:197], v176 offset:5120
	ds_read_b128 v[198:201], v176 offset:6144
	ds_read_b128 v[202:205], v176 offset:7168
	s_add_i32 s88, s68, 0xc000
	s_mov_b32 m0, s88
	s_nop 0
	global_load_lds_dwordx4 v222, s[98:99]
	s_add_i32 s89, s68, 0xe000
	s_mov_b32 m0, s89
	s_nop 0
	global_load_lds_dwordx4 v223, s[98:99]
	s_waitcnt vmcnt(8)
	s_waitcnt lgkmcnt(0)
	s_barrier
	v_mfma_f32_16x16x32_bf16 v[126:129], v[154:157], v[138:141], v[126:129]
	v_mfma_f32_16x16x32_bf16 v[122:125], v[154:157], v[146:149], v[122:125]
	v_mfma_f32_16x16x32_bf16 v[118:121], v[182:185], v[138:141], v[118:121]
	v_mfma_f32_16x16x32_bf16 v[114:117], v[182:185], v[146:149], v[114:117]
	v_mfma_f32_16x16x32_bf16 v[110:113], v[190:193], v[138:141], v[110:113]
	v_mfma_f32_16x16x32_bf16 v[106:109], v[190:193], v[146:149], v[106:109]
	v_mfma_f32_16x16x32_bf16 v[102:105], v[198:201], v[138:141], v[102:105]
	v_mfma_f32_16x16x32_bf16 v[94:97], v[198:201], v[146:149], v[94:97]
	v_mfma_f32_16x16x32_bf16 v[126:129], v[158:161], v[142:145], v[126:129]
	v_mfma_f32_16x16x32_bf16 v[122:125], v[158:161], v[150:153], v[122:125]
	v_mfma_f32_16x16x32_bf16 v[118:121], v[186:189], v[142:145], v[118:121]
	v_mfma_f32_16x16x32_bf16 v[114:117], v[186:189], v[150:153], v[114:117]
	v_mfma_f32_16x16x32_bf16 v[110:113], v[194:197], v[142:145], v[110:113]
	v_mfma_f32_16x16x32_bf16 v[106:109], v[194:197], v[150:153], v[106:109]
	v_mfma_f32_16x16x32_bf16 v[102:105], v[202:205], v[142:145], v[102:105]
	v_mfma_f32_16x16x32_bf16 v[94:97], v[202:205], v[150:153], v[94:97]
	v_mfma_f32_16x16x32_bf16 v[50:53], v[154:157], v[206:209], v[50:53]
	v_mfma_f32_16x16x32_bf16 v[42:45], v[154:157], v[214:217], v[42:45]
	v_mfma_f32_16x16x32_bf16 v[38:41], v[182:185], v[206:209], v[38:41]
	v_mfma_f32_16x16x32_bf16 v[34:37], v[182:185], v[214:217], v[34:37]
	v_mfma_f32_16x16x32_bf16 v[30:33], v[190:193], v[206:209], v[30:33]
	v_mfma_f32_16x16x32_bf16 v[26:29], v[190:193], v[214:217], v[26:29]
	v_mfma_f32_16x16x32_bf16 v[22:25], v[198:201], v[206:209], v[22:25]
	v_mfma_f32_16x16x32_bf16 v[18:21], v[198:201], v[214:217], v[18:21]
	v_mfma_f32_16x16x32_bf16 v[50:53], v[158:161], v[210:213], v[50:53]
	v_mfma_f32_16x16x32_bf16 v[42:45], v[158:161], v[218:221], v[42:45]
	v_mfma_f32_16x16x32_bf16 v[38:41], v[186:189], v[210:213], v[38:41]
	v_mfma_f32_16x16x32_bf16 v[34:37], v[186:189], v[218:221], v[34:37]
	v_mfma_f32_16x16x32_bf16 v[30:33], v[194:197], v[210:213], v[30:33]
	v_mfma_f32_16x16x32_bf16 v[26:29], v[194:197], v[218:221], v[26:29]
	v_mfma_f32_16x16x32_bf16 v[22:25], v[202:205], v[210:213], v[22:25]
	v_mfma_f32_16x16x32_bf16 v[18:21], v[202:205], v[218:221], v[18:21]
	s_barrier
	ds_read_b128 v[154:157], v176 offset:16384
	ds_read_b128 v[158:161], v176 offset:17408
	ds_read_b128 v[182:185], v176 offset:18432
	ds_read_b128 v[186:189], v176 offset:19456
	ds_read_b128 v[190:193], v176 offset:20480
	ds_read_b128 v[194:197], v176 offset:21504
	ds_read_b128 v[198:201], v176 offset:22528
	ds_read_b128 v[202:205], v176 offset:23552
	s_mov_b32 m0, s69
	s_nop 0
	global_load_lds_dwordx4 v224, s[100:101]
	s_mov_b32 m0, s70
	s_nop 0
	global_load_lds_dwordx4 v225, s[100:101]
	s_mov_b32 m0, s68
	s_nop 0
	global_load_lds_dwordx4 v226, s[98:99]
	s_mov_b32 m0, s71
	s_nop 0
	global_load_lds_dwordx4 v227, s[98:99]
	s_mov_b32 m0, s76
	s_nop 0
	global_load_lds_dwordx4 v228, s[100:101]
	s_mov_b32 m0, s77
	s_nop 0
	global_load_lds_dwordx4 v229, s[100:101]
	s_waitcnt vmcnt(8)
	s_waitcnt lgkmcnt(0)
	s_barrier
	v_mfma_f32_16x16x32_bf16 v[14:17], v[154:157], v[138:141], v[14:17]
	v_mfma_f32_16x16x32_bf16 v[10:13], v[154:157], v[146:149], v[10:13]
	v_mfma_f32_16x16x32_bf16 v[6:9], v[182:185], v[138:141], v[6:9]
	v_mfma_f32_16x16x32_bf16 v[2:5], v[182:185], v[146:149], v[2:5]
	v_mfma_f32_16x16x32_bf16 v[46:49], v[190:193], v[138:141], v[46:49]
	v_mfma_f32_16x16x32_bf16 v[54:57], v[190:193], v[146:149], v[54:57]
	v_mfma_f32_16x16x32_bf16 v[58:61], v[198:201], v[138:141], v[58:61]
	v_mfma_f32_16x16x32_bf16 v[62:65], v[198:201], v[146:149], v[62:65]
	v_mfma_f32_16x16x32_bf16 v[14:17], v[158:161], v[142:145], v[14:17]
	v_mfma_f32_16x16x32_bf16 v[10:13], v[158:161], v[150:153], v[10:13]
	v_mfma_f32_16x16x32_bf16 v[6:9], v[186:189], v[142:145], v[6:9]
	v_mfma_f32_16x16x32_bf16 v[2:5], v[186:189], v[150:153], v[2:5]
	v_mfma_f32_16x16x32_bf16 v[46:49], v[194:197], v[142:145], v[46:49]
	v_mfma_f32_16x16x32_bf16 v[54:57], v[194:197], v[150:153], v[54:57]
	v_mfma_f32_16x16x32_bf16 v[58:61], v[202:205], v[142:145], v[58:61]
	v_mfma_f32_16x16x32_bf16 v[62:65], v[202:205], v[150:153], v[62:65]
	v_mfma_f32_16x16x32_bf16 v[66:69], v[154:157], v[206:209], v[66:69]
	v_mfma_f32_16x16x32_bf16 v[70:73], v[154:157], v[214:217], v[70:73]
	v_mfma_f32_16x16x32_bf16 v[74:77], v[182:185], v[206:209], v[74:77]
	v_mfma_f32_16x16x32_bf16 v[78:81], v[182:185], v[214:217], v[78:81]
	v_mfma_f32_16x16x32_bf16 v[82:85], v[190:193], v[206:209], v[82:85]
	v_mfma_f32_16x16x32_bf16 v[86:89], v[190:193], v[214:217], v[86:89]
	v_mfma_f32_16x16x32_bf16 v[90:93], v[198:201], v[206:209], v[90:93]
	v_mfma_f32_16x16x32_bf16 v[98:101], v[198:201], v[214:217], v[98:101]
	v_mfma_f32_16x16x32_bf16 v[66:69], v[158:161], v[210:213], v[66:69]
	v_mfma_f32_16x16x32_bf16 v[70:73], v[158:161], v[218:221], v[70:73]
	v_mfma_f32_16x16x32_bf16 v[74:77], v[186:189], v[210:213], v[74:77]
	v_mfma_f32_16x16x32_bf16 v[78:81], v[186:189], v[218:221], v[78:81]
	v_mfma_f32_16x16x32_bf16 v[82:85], v[194:197], v[210:213], v[82:85]
	v_mfma_f32_16x16x32_bf16 v[86:89], v[194:197], v[218:221], v[86:89]
	v_mfma_f32_16x16x32_bf16 v[90:93], v[202:205], v[210:213], v[90:93]
	v_mfma_f32_16x16x32_bf16 v[98:101], v[202:205], v[218:221], v[98:101]
	s_barrier
; #define LDA(dst, b, h)                                                                                     \
;   _Pragma("unroll") for (int m = 0; m < 4; ++m) _Pragma("unroll") for (int k = 0; k < 2; ++k) dst[m][k] = \
;       *reinterpret_cast<const bf16x8*>(shmc + aL + (((b) * 2 + (h)) * 16384 + (m * 2 + k) * 1024))
; #define LDB(dst, b, h)                                                                                     \
;   _Pragma("unroll") for (int n = 0; n < 2; ++n) _Pragma("unroll") for (int k = 0; k < 2; ++k) dst[n][k] = \
;       *reinterpret_cast<const bf16x8*>(shmc + bL + (((b) * 2 + (h)) * 16384 + (n * 2 + k) * 1024))
; #define WAIT_V(n) asm volatile("s_waitcnt vmcnt(" #n ")" ::: "memory")
; #define WAIT_L(n) asm volatile("s_waitcnt lgkmcnt(" #n ")" ::: "memory")
; #define BAR __builtin_amdgcn_s_barrier()
; #define SCHED __builtin_amdgcn_sched_barrier(0)
; template <int EPI>
; __device__ __forceinline__ void phase_gemm(const Params& p, const GemmDesc& d, char* shmc) {
;     ...
;       LDB(B0, 1, 0); SCHED; LDA(At, 1, 0); STAGE_A(SA(0, 1), 1, t + 2);
;       WAIT_L(8); BAR; WAIT_L(0); MMA(0, 0, At, B0); BAR; SCHED;
;       LDB(B1, 1, 1); STAGE_B(SB(1, 0), 0, t + 3);
;       BAR; WAIT_L(0); MMA(0, 1, At, B1); BAR;
;       LDA(At, 1, 1); STAGE_A(SA(1, 0), 0, t + 3);
;       BAR; WAIT_L(0); MMA(1, 0, At, B0); BAR; SCHED;
;       STAGE_B(SB(1, 1), 1, t + 3);
;       WAIT_V(6); BAR; MMA(1, 1, At, B1); BAR;
;     }
	ds_read_b128 v[138:141], v175 offset:32768
	ds_read_b128 v[142:145], v175 offset:33792
	ds_read_b128 v[146:149], v175 offset:34816
	ds_read_b128 v[150:153], v175 offset:35840
	ds_read_b128 v[206:209], v175 offset:49152
	ds_read_b128 v[210:213], v175 offset:50176
	ds_read_b128 v[214:217], v175 offset:51200
	ds_read_b128 v[218:221], v175 offset:52224
	ds_read_b128 v[154:157], v176 offset:32768
	ds_read_b128 v[158:161], v176 offset:33792
	ds_read_b128 v[182:185], v176 offset:34816
	ds_read_b128 v[186:189], v176 offset:35840
	ds_read_b128 v[190:193], v176 offset:36864
	ds_read_b128 v[194:197], v176 offset:37888
	ds_read_b128 v[198:201], v176 offset:38912
	ds_read_b128 v[202:205], v176 offset:39936
	s_mov_b32 m0, s80
	s_nop 0
	global_load_lds_dwordx4 v230, s[98:99]
	s_mov_b32 m0, s81
	s_nop 0
	global_load_lds_dwordx4 v231, s[98:99]
	s_waitcnt vmcnt(8)
	s_waitcnt lgkmcnt(0)
	s_barrier
	v_mfma_f32_16x16x32_bf16 v[126:129], v[154:157], v[138:141], v[126:129]
	v_mfma_f32_16x16x32_bf16 v[122:125], v[154:157], v[146:149], v[122:125]
	v_mfma_f32_16x16x32_bf16 v[118:121], v[182:185], v[138:141], v[118:121]
	v_mfma_f32_16x16x32_bf16 v[114:117], v[182:185], v[146:149], v[114:117]
	v_mfma_f32_16x16x32_bf16 v[110:113], v[190:193], v[138:141], v[110:113]
	v_mfma_f32_16x16x32_bf16 v[106:109], v[190:193], v[146:149], v[106:109]
	v_mfma_f32_16x16x32_bf16 v[102:105], v[198:201], v[138:141], v[102:105]
	v_mfma_f32_16x16x32_bf16 v[94:97], v[198:201], v[146:149], v[94:97]
	v_mfma_f32_16x16x32_bf16 v[126:129], v[158:161], v[142:145], v[126:129]
	v_mfma_f32_16x16x32_bf16 v[122:125], v[158:161], v[150:153], v[122:125]
	v_mfma_f32_16x16x32_bf16 v[118:121], v[186:189], v[142:145], v[118:121]
	v_mfma_f32_16x16x32_bf16 v[114:117], v[186:189], v[150:153], v[114:117]
	v_mfma_f32_16x16x32_bf16 v[110:113], v[194:197], v[142:145], v[110:113]
	v_mfma_f32_16x16x32_bf16 v[106:109], v[194:197], v[150:153], v[106:109]
	v_mfma_f32_16x16x32_bf16 v[102:105], v[202:205], v[142:145], v[102:105]
	v_mfma_f32_16x16x32_bf16 v[94:97], v[202:205], v[150:153], v[94:97]
	v_mfma_f32_16x16x32_bf16 v[50:53], v[154:157], v[206:209], v[50:53]
	v_mfma_f32_16x16x32_bf16 v[42:45], v[154:157], v[214:217], v[42:45]
	v_mfma_f32_16x16x32_bf16 v[38:41], v[182:185], v[206:209], v[38:41]
	v_mfma_f32_16x16x32_bf16 v[34:37], v[182:185], v[214:217], v[34:37]
	v_mfma_f32_16x16x32_bf16 v[30:33], v[190:193], v[206:209], v[30:33]
	v_mfma_f32_16x16x32_bf16 v[26:29], v[190:193], v[214:217], v[26:29]
	v_mfma_f32_16x16x32_bf16 v[22:25], v[198:201], v[206:209], v[22:25]
	v_mfma_f32_16x16x32_bf16 v[18:21], v[198:201], v[214:217], v[18:21]
	v_mfma_f32_16x16x32_bf16 v[50:53], v[158:161], v[210:213], v[50:53]
	v_mfma_f32_16x16x32_bf16 v[42:45], v[158:161], v[218:221], v[42:45]
	v_mfma_f32_16x16x32_bf16 v[38:41], v[186:189], v[210:213], v[38:41]
	v_mfma_f32_16x16x32_bf16 v[34:37], v[186:189], v[218:221], v[34:37]
	v_mfma_f32_16x16x32_bf16 v[30:33], v[194:197], v[210:213], v[30:33]
	v_mfma_f32_16x16x32_bf16 v[26:29], v[194:197], v[218:221], v[26:29]
	v_mfma_f32_16x16x32_bf16 v[22:25], v[202:205], v[210:213], v[22:25]
	v_mfma_f32_16x16x32_bf16 v[18:21], v[202:205], v[218:221], v[18:21]
	s_barrier
	ds_read_b128 v[154:157], v176 offset:49152
	ds_read_b128 v[158:161], v176 offset:50176
	ds_read_b128 v[182:185], v176 offset:51200
	ds_read_b128 v[186:189], v176 offset:52224
	ds_read_b128 v[190:193], v176 offset:53248
	ds_read_b128 v[194:197], v176 offset:54272
	ds_read_b128 v[198:201], v176 offset:55296
	ds_read_b128 v[202:205], v176 offset:56320
	s_mov_b32 m0, s61
	s_nop 0
	global_load_lds_dwordx4 v232, s[100:101]
	s_mov_b32 m0, s78
	s_nop 0
	global_load_lds_dwordx4 v233, s[100:101]
	s_mov_b32 m0, s79
	s_nop 0
	global_load_lds_dwordx4 v234, s[98:99]
	s_mov_b32 m0, s86
	s_nop 0
	global_load_lds_dwordx4 v235, s[98:99]
	s_mov_b32 m0, s64
	s_nop 0
	global_load_lds_dwordx4 v236, s[100:101]
	s_mov_b32 m0, s65
	s_nop 0
	global_load_lds_dwordx4 v237, s[100:101]
	s_add_i32 s87, s87, 2
	s_add_u32 s62, s62, 0x100
	s_addc_u32 s63, s63, 0
	s_add_u32 s98, s98, 0x100
	s_addc_u32 s99, s99, 0
	s_add_u32 s100, s100, 0x100
	s_addc_u32 s101, s101, 0
	s_cmp_gt_u32 s87, 27
	s_waitcnt vmcnt(8)
	s_waitcnt lgkmcnt(0)
	s_barrier
	v_mfma_f32_16x16x32_bf16 v[14:17], v[154:157], v[138:141], v[14:17]
	v_mfma_f32_16x16x32_bf16 v[10:13], v[154:157], v[146:149], v[10:13]
	v_mfma_f32_16x16x32_bf16 v[6:9], v[182:185], v[138:141], v[6:9]
	v_mfma_f32_16x16x32_bf16 v[2:5], v[182:185], v[146:149], v[2:5]
	v_mfma_f32_16x16x32_bf16 v[46:49], v[190:193], v[138:141], v[46:49]
	v_mfma_f32_16x16x32_bf16 v[54:57], v[190:193], v[146:149], v[54:57]
	v_mfma_f32_16x16x32_bf16 v[58:61], v[198:201], v[138:141], v[58:61]
	v_mfma_f32_16x16x32_bf16 v[62:65], v[198:201], v[146:149], v[62:65]
	v_mfma_f32_16x16x32_bf16 v[14:17], v[158:161], v[142:145], v[14:17]
	v_mfma_f32_16x16x32_bf16 v[10:13], v[158:161], v[150:153], v[10:13]
	v_mfma_f32_16x16x32_bf16 v[6:9], v[186:189], v[142:145], v[6:9]
	v_mfma_f32_16x16x32_bf16 v[2:5], v[186:189], v[150:153], v[2:5]
	v_mfma_f32_16x16x32_bf16 v[46:49], v[194:197], v[142:145], v[46:49]
	v_mfma_f32_16x16x32_bf16 v[54:57], v[194:197], v[150:153], v[54:57]
	v_mfma_f32_16x16x32_bf16 v[58:61], v[202:205], v[142:145], v[58:61]
	v_mfma_f32_16x16x32_bf16 v[62:65], v[202:205], v[150:153], v[62:65]
	v_mfma_f32_16x16x32_bf16 v[66:69], v[154:157], v[206:209], v[66:69]
	v_mfma_f32_16x16x32_bf16 v[70:73], v[154:157], v[214:217], v[70:73]
	v_mfma_f32_16x16x32_bf16 v[74:77], v[182:185], v[206:209], v[74:77]
	v_mfma_f32_16x16x32_bf16 v[78:81], v[182:185], v[214:217], v[78:81]
	v_mfma_f32_16x16x32_bf16 v[82:85], v[190:193], v[206:209], v[82:85]
	v_mfma_f32_16x16x32_bf16 v[86:89], v[190:193], v[214:217], v[86:89]
	v_mfma_f32_16x16x32_bf16 v[90:93], v[198:201], v[206:209], v[90:93]
	v_mfma_f32_16x16x32_bf16 v[98:101], v[198:201], v[214:217], v[98:101]
	v_mfma_f32_16x16x32_bf16 v[66:69], v[158:161], v[210:213], v[66:69]
	v_mfma_f32_16x16x32_bf16 v[70:73], v[158:161], v[218:221], v[70:73]
	v_mfma_f32_16x16x32_bf16 v[74:77], v[186:189], v[210:213], v[74:77]
	v_mfma_f32_16x16x32_bf16 v[78:81], v[186:189], v[218:221], v[78:81]
	v_mfma_f32_16x16x32_bf16 v[82:85], v[194:197], v[210:213], v[82:85]
	v_mfma_f32_16x16x32_bf16 v[86:89], v[194:197], v[218:221], v[86:89]
	v_mfma_f32_16x16x32_bf16 v[90:93], v[202:205], v[210:213], v[90:93]
	v_mfma_f32_16x16x32_bf16 v[98:101], v[202:205], v[218:221], v[98:101]
	s_barrier
; #define LDA(dst, b, h)                                                                                     \
;   _Pragma("unroll") for (int m = 0; m < 4; ++m) _Pragma("unroll") for (int k = 0; k < 2; ++k) dst[m][k] = \
;       *reinterpret_cast<const bf16x8*>(shmc + aL + (((b) * 2 + (h)) * 16384 + (m * 2 + k) * 1024))
; #define LDB(dst, b, h)                                                                                     \
;   _Pragma("unroll") for (int n = 0; n < 2; ++n) _Pragma("unroll") for (int k = 0; k < 2; ++k) dst[n][k] = \
;       *reinterpret_cast<const bf16x8*>(shmc + bL + (((b) * 2 + (h)) * 16384 + (n * 2 + k) * 1024))
; #define OPAQ asm volatile("" : "+v"(aL), "+v"(bL))
; #define WAIT_V(n) asm volatile("s_waitcnt vmcnt(" #n ")" ::: "memory")
; #define WAIT_L(n) asm volatile("s_waitcnt lgkmcnt(" #n ")" ::: "memory")
; #define BAR __builtin_amdgcn_s_barrier()
; template <int EPI>
; __device__ __forceinline__ void phase_gemm(const Params& p, const GemmDesc& d, char* shmc) {
;     ...
;     {
;       OPAQ;
;       LDB(B0, 0, 0); LDA(At, 0, 0); STAGE_A(SA(1, 1), 1, nt - 1);
;       BAR; WAIT_L(0); MMA(0, 0, At, B0); BAR;
;       LDB(B1, 0, 1); BAR; WAIT_L(0); MMA(0, 1, At, B1); BAR;
;       LDA(At, 0, 1); WAIT_V(4); BAR; WAIT_L(0); MMA(1, 0, At, B0); MMA(1, 1, At, B1); BAR;
;     }
	s_cbranch_scc0 .LBB0_598
	s_setprio 0
	s_add_u32 s8, s8, 0x80f80
	s_addc_u32 s9, s9, 0
	v_add_u32_e32 v175, 0, v179
	v_add_u32_e32 v176, 0, v177
	s_mov_b32 m0, s88
	ds_read_b128 v[130:133], v175
	ds_read_b128 v[134:137], v175 offset:1024
	ds_read_b128 v[138:141], v175 offset:2048
	ds_read_b128 v[142:145], v175 offset:3072
	ds_read_b128 v[146:149], v176
	ds_read_b128 v[150:153], v176 offset:1024
	ds_read_b128 v[154:157], v176 offset:2048
	ds_read_b128 v[158:161], v176 offset:3072
	ds_read_b128 v[182:185], v176 offset:4096
	ds_read_b128 v[186:189], v176 offset:5120
	ds_read_b128 v[190:193], v176 offset:6144
	ds_read_b128 v[194:197], v176 offset:7168
	global_load_lds_dwordx4 v162, s[8:9]
	s_mov_b32 m0, s89
	s_nop 0
	global_load_lds_dwordx4 v174, s[8:9]
	s_waitcnt vmcnt(8)
	s_barrier
	s_waitcnt lgkmcnt(0)
	s_setprio 1
	s_waitcnt lgkmcnt(0)
	v_mfma_f32_16x16x32_bf16 v[126:129], v[146:149], v[130:133], v[126:129]
	v_mfma_f32_16x16x32_bf16 v[122:125], v[146:149], v[138:141], v[122:125]
	v_mfma_f32_16x16x32_bf16 v[114:117], v[154:157], v[138:141], v[114:117]
	v_mfma_f32_16x16x32_bf16 v[110:113], v[182:185], v[130:133], v[110:113]
	v_mfma_f32_16x16x32_bf16 v[126:129], v[150:153], v[134:137], v[126:129]
	v_mfma_f32_16x16x32_bf16 v[122:125], v[150:153], v[142:145], v[122:125]
	v_mfma_f32_16x16x32_bf16 v[118:121], v[154:157], v[130:133], v[118:121]
	v_mfma_f32_16x16x32_bf16 v[114:117], v[158:161], v[142:145], v[114:117]
	v_mfma_f32_16x16x32_bf16 v[110:113], v[186:189], v[134:137], v[110:113]
	v_mfma_f32_16x16x32_bf16 v[106:109], v[182:185], v[138:141], v[106:109]
	v_mfma_f32_16x16x32_bf16 v[102:105], v[190:193], v[130:133], v[102:105]
	v_mfma_f32_16x16x32_bf16 v[94:97], v[190:193], v[138:141], v[94:97]
	v_mfma_f32_16x16x32_bf16 v[118:121], v[158:161], v[134:137], v[118:121]
	v_mfma_f32_16x16x32_bf16 v[106:109], v[186:189], v[142:145], v[106:109]
	v_mfma_f32_16x16x32_bf16 v[102:105], v[194:197], v[134:137], v[102:105]
	v_mfma_f32_16x16x32_bf16 v[94:97], v[194:197], v[142:145], v[94:97]
	s_setprio 0
	s_barrier
	ds_read_b128 v[198:201], v175 offset:16384
	ds_read_b128 v[202:205], v175 offset:17408
	ds_read_b128 v[206:209], v175 offset:18432
	ds_read_b128 v[210:213], v175 offset:19456
	s_barrier
	s_waitcnt lgkmcnt(0)
	s_setprio 1
	s_waitcnt lgkmcnt(0)
	v_mfma_f32_16x16x32_bf16 v[50:53], v[146:149], v[198:201], v[50:53]
	v_mfma_f32_16x16x32_bf16 v[42:45], v[146:149], v[206:209], v[42:45]
	v_mfma_f32_16x16x32_bf16 v[38:41], v[154:157], v[198:201], v[38:41]
	v_mfma_f32_16x16x32_bf16 v[30:33], v[182:185], v[198:201], v[30:33]
	v_mfma_f32_16x16x32_bf16 v[22:25], v[190:193], v[198:201], v[22:25]
	v_mfma_f32_16x16x32_bf16 v[50:53], v[150:153], v[202:205], v[50:53]
	v_mfma_f32_16x16x32_bf16 v[42:45], v[150:153], v[210:213], v[42:45]
	v_mfma_f32_16x16x32_bf16 v[38:41], v[158:161], v[202:205], v[38:41]
	v_mfma_f32_16x16x32_bf16 v[34:37], v[154:157], v[206:209], v[34:37]
	v_mfma_f32_16x16x32_bf16 v[30:33], v[186:189], v[202:205], v[30:33]
	v_mfma_f32_16x16x32_bf16 v[26:29], v[182:185], v[206:209], v[26:29]
	v_mfma_f32_16x16x32_bf16 v[22:25], v[194:197], v[202:205], v[22:25]
	v_mfma_f32_16x16x32_bf16 v[18:21], v[190:193], v[206:209], v[18:21]
	v_mfma_f32_16x16x32_bf16 v[34:37], v[158:161], v[210:213], v[34:37]
	v_mfma_f32_16x16x32_bf16 v[26:29], v[186:189], v[210:213], v[26:29]
	v_mfma_f32_16x16x32_bf16 v[18:21], v[194:197], v[210:213], v[18:21]
	s_setprio 0
	s_barrier
	ds_read_b128 v[146:149], v176 offset:16384
	ds_read_b128 v[150:153], v176 offset:17408
	ds_read_b128 v[154:157], v176 offset:18432
	ds_read_b128 v[158:161], v176 offset:19456
	ds_read_b128 v[182:185], v176 offset:20480
	ds_read_b128 v[186:189], v176 offset:21504
	ds_read_b128 v[190:193], v176 offset:22528
	ds_read_b128 v[194:197], v176 offset:23552
	s_waitcnt vmcnt(4)
	s_barrier
	s_waitcnt lgkmcnt(0)
	s_setprio 1
	s_waitcnt lgkmcnt(0)
	v_mfma_f32_16x16x32_bf16 v[14:17], v[146:149], v[130:133], v[14:17]
	v_mfma_f32_16x16x32_bf16 v[6:9], v[154:157], v[130:133], v[6:9]
	v_mfma_f32_16x16x32_bf16 v[2:5], v[154:157], v[138:141], v[2:5]
	v_mfma_f32_16x16x32_bf16 v[46:49], v[182:185], v[130:133], v[46:49]
	v_mfma_f32_16x16x32_bf16 v[54:57], v[182:185], v[138:141], v[54:57]
	v_mfma_f32_16x16x32_bf16 v[58:61], v[190:193], v[130:133], v[58:61]
	v_mfma_f32_16x16x32_bf16 v[14:17], v[150:153], v[134:137], v[14:17]
	v_mfma_f32_16x16x32_bf16 v[10:13], v[146:149], v[138:141], v[10:13]
	v_mfma_f32_16x16x32_bf16 v[6:9], v[158:161], v[134:137], v[6:9]
	v_mfma_f32_16x16x32_bf16 v[2:5], v[158:161], v[142:145], v[2:5]
	v_mfma_f32_16x16x32_bf16 v[46:49], v[186:189], v[134:137], v[46:49]
	v_mfma_f32_16x16x32_bf16 v[54:57], v[186:189], v[142:145], v[54:57]
	v_mfma_f32_16x16x32_bf16 v[214:217], v[194:197], v[134:137], v[58:61]
	v_mfma_f32_16x16x32_bf16 v[58:61], v[190:193], v[138:141], v[62:65]
	v_mfma_f32_16x16x32_bf16 v[10:13], v[150:153], v[142:145], v[10:13]
	v_mfma_f32_16x16x32_bf16 v[218:221], v[194:197], v[142:145], v[58:61]
	s_setprio 0
	s_setprio 1
	v_mfma_f32_16x16x32_bf16 v[58:61], v[146:149], v[198:201], v[66:69]
	v_mfma_f32_16x16x32_bf16 v[222:225], v[150:153], v[202:205], v[58:61]
	v_mfma_f32_16x16x32_bf16 v[58:61], v[146:149], v[206:209], v[70:73]
	v_mfma_f32_16x16x32_bf16 v[226:229], v[150:153], v[210:213], v[58:61]
	v_mfma_f32_16x16x32_bf16 v[58:61], v[154:157], v[198:201], v[74:77]
	v_mfma_f32_16x16x32_bf16 v[230:233], v[158:161], v[202:205], v[58:61]
	v_mfma_f32_16x16x32_bf16 v[58:61], v[154:157], v[206:209], v[78:81]
	v_mfma_f32_16x16x32_bf16 v[234:237], v[158:161], v[210:213], v[58:61]
	v_mfma_f32_16x16x32_bf16 v[58:61], v[182:185], v[198:201], v[82:85]
	v_mfma_f32_16x16x32_bf16 v[238:241], v[186:189], v[202:205], v[58:61]
	v_mfma_f32_16x16x32_bf16 v[58:61], v[182:185], v[206:209], v[86:89]
	v_mfma_f32_16x16x32_bf16 v[182:185], v[186:189], v[210:213], v[58:61]
	v_mfma_f32_16x16x32_bf16 v[58:61], v[190:193], v[198:201], v[90:93]
	v_mfma_f32_16x16x32_bf16 v[186:189], v[194:197], v[202:205], v[58:61]
	v_mfma_f32_16x16x32_bf16 v[58:61], v[190:193], v[206:209], v[98:101]
	v_mfma_f32_16x16x32_bf16 v[190:193], v[194:197], v[210:213], v[58:61]
	s_setprio 0
	s_barrier
; #define LDA(dst, b, h)                                                                                     \
;   _Pragma("unroll") for (int m = 0; m < 4; ++m) _Pragma("unroll") for (int k = 0; k < 2; ++k) dst[m][k] = \
;       *reinterpret_cast<const bf16x8*>(shmc + aL + (((b) * 2 + (h)) * 16384 + (m * 2 + k) * 1024))
; #define LDB(dst, b, h)                                                                                     \
;   _Pragma("unroll") for (int n = 0; n < 2; ++n) _Pragma("unroll") for (int k = 0; k < 2; ++k) dst[n][k] = \
;       *reinterpret_cast<const bf16x8*>(shmc + bL + (((b) * 2 + (h)) * 16384 + (n * 2 + k) * 1024))
; #define WAIT_V(n) asm volatile("s_waitcnt vmcnt(" #n ")" ::: "memory")
; #define WAIT_L(n) asm volatile("s_waitcnt lgkmcnt(" #n ")" ::: "memory")
; #define BAR __builtin_amdgcn_s_barrier()
; template <int EPI>
; __device__ __forceinline__ void phase_gemm(const Params& p, const GemmDesc& d, char* shmc) {
;     ...
;     {
;       LDB(B0, 1, 0); LDA(At, 1, 0); WAIT_V(2); BAR; WAIT_L(0); MMA(0, 0, At, B0); BAR;
;       LDB(B1, 1, 1); WAIT_V(0); BAR; WAIT_L(0); MMA(0, 1, At, B1); BAR;
;       LDA(At, 1, 1); BAR; WAIT_L(0); MMA(1, 0, At, B0); MMA(1, 1, At, B1); BAR;
;     }
;     if (wr == 0) BAR;
	ds_read_b128 v[66:69], v175 offset:32768
	ds_read_b128 v[194:197], v175 offset:33792
	ds_read_b128 v[198:201], v175 offset:34816
	ds_read_b128 v[202:205], v175 offset:35840
	s_nop 0
	ds_read_b128 v[58:61], v176 offset:32768
	ds_read_b128 v[62:65], v176 offset:33792
	ds_read_b128 v[70:73], v176 offset:34816
	ds_read_b128 v[74:77], v176 offset:35840
	ds_read_b128 v[78:81], v176 offset:36864
	ds_read_b128 v[82:85], v176 offset:37888
	ds_read_b128 v[206:209], v176 offset:38912
	ds_read_b128 v[210:213], v176 offset:39936
	s_waitcnt vmcnt(2)
	s_barrier
	s_waitcnt lgkmcnt(0)
	s_setprio 1
	s_waitcnt lgkmcnt(0)
	v_mfma_f32_16x16x32_bf16 v[86:89], v[58:61], v[66:69], v[126:129]
	v_mfma_f32_16x16x32_bf16 v[158:161], v[62:65], v[194:197], v[86:89]
	v_mfma_f32_16x16x32_bf16 v[86:89], v[58:61], v[198:201], v[122:125]
	v_mfma_f32_16x16x32_bf16 v[142:145], v[62:65], v[202:205], v[86:89]
	v_mfma_f32_16x16x32_bf16 v[86:89], v[70:73], v[66:69], v[118:121]
	v_mfma_f32_16x16x32_bf16 v[154:157], v[74:77], v[194:197], v[86:89]
	v_mfma_f32_16x16x32_bf16 v[86:89], v[70:73], v[198:201], v[114:117]
	v_mfma_f32_16x16x32_bf16 v[138:141], v[74:77], v[202:205], v[86:89]
	v_mfma_f32_16x16x32_bf16 v[86:89], v[78:81], v[66:69], v[110:113]
	v_mfma_f32_16x16x32_bf16 v[150:153], v[82:85], v[194:197], v[86:89]
	v_mfma_f32_16x16x32_bf16 v[86:89], v[78:81], v[198:201], v[106:109]
	v_mfma_f32_16x16x32_bf16 v[134:137], v[82:85], v[202:205], v[86:89]
	v_mfma_f32_16x16x32_bf16 v[86:89], v[206:209], v[66:69], v[102:105]
	v_mfma_f32_16x16x32_bf16 v[146:149], v[210:213], v[194:197], v[86:89]
	v_mfma_f32_16x16x32_bf16 v[86:89], v[206:209], v[198:201], v[94:97]
	v_mfma_f32_16x16x32_bf16 v[130:133], v[210:213], v[202:205], v[86:89]
	s_setprio 0
	s_barrier
	ds_read_b128 v[94:97], v175 offset:49152
	ds_read_b128 v[102:105], v175 offset:50176
	ds_read_b128 v[106:109], v175 offset:51200
	ds_read_b128 v[118:121], v175 offset:52224
	s_waitcnt vmcnt(0)
	s_barrier
	s_waitcnt lgkmcnt(0)
	s_setprio 1
	s_waitcnt lgkmcnt(0)
	v_mfma_f32_16x16x32_bf16 v[50:53], v[58:61], v[94:97], v[50:53]
	v_mfma_f32_16x16x32_bf16 v[42:45], v[58:61], v[106:109], v[42:45]
	v_mfma_f32_16x16x32_bf16 v[38:41], v[70:73], v[94:97], v[38:41]
	v_mfma_f32_16x16x32_bf16 v[34:37], v[70:73], v[106:109], v[34:37]
	v_mfma_f32_16x16x32_bf16 v[30:33], v[78:81], v[94:97], v[30:33]
	v_mfma_f32_16x16x32_bf16 v[26:29], v[78:81], v[106:109], v[26:29]
	v_mfma_f32_16x16x32_bf16 v[22:25], v[206:209], v[94:97], v[22:25]
	v_mfma_f32_16x16x32_bf16 v[18:21], v[206:209], v[106:109], v[18:21]
	v_mfma_f32_16x16x32_bf16 v[126:129], v[62:65], v[102:105], v[50:53]
	v_mfma_f32_16x16x32_bf16 v[98:101], v[62:65], v[118:121], v[42:45]
	v_mfma_f32_16x16x32_bf16 v[122:125], v[74:77], v[102:105], v[38:41]
	v_mfma_f32_16x16x32_bf16 v[90:93], v[74:77], v[118:121], v[34:37]
	v_mfma_f32_16x16x32_bf16 v[114:117], v[82:85], v[102:105], v[30:33]
	v_mfma_f32_16x16x32_bf16 v[86:89], v[82:85], v[118:121], v[26:29]
	v_mfma_f32_16x16x32_bf16 v[110:113], v[210:213], v[102:105], v[22:25]
	v_mfma_f32_16x16x32_bf16 v[82:85], v[210:213], v[118:121], v[18:21]
	s_setprio 0
	s_barrier
	s_nop 0
	ds_read_b128 v[18:21], v176 offset:49152
	ds_read_b128 v[22:25], v176 offset:50176
	ds_read_b128 v[26:29], v176 offset:51200
	ds_read_b128 v[30:33], v176 offset:52224
	ds_read_b128 v[34:37], v176 offset:53248
	ds_read_b128 v[206:209], v176 offset:54272
	ds_read_b128 v[210:213], v176 offset:55296
	ds_read_b128 v[242:245], v176 offset:56320
	s_barrier
	s_waitcnt lgkmcnt(0)
	s_setprio 1
	s_waitcnt lgkmcnt(0)
	v_mfma_f32_16x16x32_bf16 v[2:5], v[26:29], v[198:201], v[2:5]
	v_mfma_f32_16x16x32_bf16 v[58:61], v[30:33], v[202:205], v[2:5]
	v_mfma_f32_16x16x32_bf16 v[2:5], v[34:37], v[66:69], v[46:49]
	v_mfma_f32_16x16x32_bf16 v[70:73], v[206:209], v[194:197], v[2:5]
	v_mfma_f32_16x16x32_bf16 v[2:5], v[34:37], v[198:201], v[54:57]
	v_mfma_f32_16x16x32_bf16 v[54:57], v[206:209], v[202:205], v[2:5]
	v_mfma_f32_16x16x32_bf16 v[2:5], v[210:213], v[66:69], v[214:217]
	v_mfma_f32_16x16x32_bf16 v[14:17], v[18:21], v[66:69], v[14:17]
	v_mfma_f32_16x16x32_bf16 v[10:13], v[18:21], v[198:201], v[10:13]
	v_mfma_f32_16x16x32_bf16 v[6:9], v[26:29], v[66:69], v[6:9]
	v_mfma_f32_16x16x32_bf16 v[66:69], v[242:245], v[194:197], v[2:5]
	v_mfma_f32_16x16x32_bf16 v[2:5], v[210:213], v[198:201], v[218:221]
	v_mfma_f32_16x16x32_bf16 v[78:81], v[22:25], v[194:197], v[14:17]
	v_mfma_f32_16x16x32_bf16 v[62:65], v[22:25], v[202:205], v[10:13]
	v_mfma_f32_16x16x32_bf16 v[74:77], v[30:33], v[194:197], v[6:9]
	v_mfma_f32_16x16x32_bf16 v[50:53], v[242:245], v[202:205], v[2:5]
	s_setprio 0
	s_setprio 1
	v_mfma_f32_16x16x32_bf16 v[2:5], v[18:21], v[94:97], v[222:225]
	v_mfma_f32_16x16x32_bf16 v[46:49], v[22:25], v[102:105], v[2:5]
	v_mfma_f32_16x16x32_bf16 v[2:5], v[18:21], v[106:109], v[226:229]
	v_mfma_f32_16x16x32_bf16 v[22:25], v[22:25], v[118:121], v[2:5]
	v_mfma_f32_16x16x32_bf16 v[2:5], v[26:29], v[94:97], v[230:233]
	v_mfma_f32_16x16x32_bf16 v[42:45], v[30:33], v[102:105], v[2:5]
	v_mfma_f32_16x16x32_bf16 v[2:5], v[26:29], v[106:109], v[234:237]
	v_mfma_f32_16x16x32_bf16 v[14:17], v[30:33], v[118:121], v[2:5]
	v_mfma_f32_16x16x32_bf16 v[2:5], v[34:37], v[94:97], v[238:241]
	v_mfma_f32_16x16x32_bf16 v[38:41], v[206:209], v[102:105], v[2:5]
	v_mfma_f32_16x16x32_bf16 v[2:5], v[34:37], v[106:109], v[182:185]
	v_mfma_f32_16x16x32_bf16 v[6:9], v[206:209], v[118:121], v[2:5]
	v_mfma_f32_16x16x32_bf16 v[2:5], v[210:213], v[94:97], v[186:189]
	v_mfma_f32_16x16x32_bf16 v[30:33], v[242:245], v[102:105], v[2:5]
	v_mfma_f32_16x16x32_bf16 v[2:5], v[210:213], v[106:109], v[190:193]
	v_mfma_f32_16x16x32_bf16 v[2:5], v[242:245], v[118:121], v[2:5]
	s_setprio 0
	s_barrier
	s_and_saveexec_b64 s[8:9], s[6:7]
	s_cbranch_execz .LBB0_601
	s_barrier

; #define LDA(dst, b, h)                                                                                     \
;   _Pragma("unroll") for (int m = 0; m < 4; ++m) _Pragma("unroll") for (int k = 0; k < 2; ++k) dst[m][k] = \
;       *reinterpret_cast<const bf16x8*>(shmc + aL + (((b) * 2 + (h)) * 16384 + (m * 2 + k) * 1024))
; #define LDB(dst, b, h)                                                                                     \
;   _Pragma("unroll") for (int n = 0; n < 2; ++n) _Pragma("unroll") for (int k = 0; k < 2; ++k) dst[n][k] = \
;       *reinterpret_cast<const bf16x8*>(shmc + bL + (((b) * 2 + (h)) * 16384 + (n * 2 + k) * 1024))
; #define OPAQ asm volatile("" : "+v"(aL), "+v"(bL))
; #define WAIT_V(n) asm volatile("s_waitcnt vmcnt(" #n ")" ::: "memory")
; #define WAIT_L(n) asm volatile("s_waitcnt lgkmcnt(" #n ")" ::: "memory")
; #define BAR __builtin_amdgcn_s_barrier()
; #define SCHED __builtin_amdgcn_sched_barrier(0)
; template <int EPI>
; __device__ __forceinline__ void phase_gemm(const Params& p, const GemmDesc& d, char* shmc) {
;     ...
;     for (int t = 0; t < nt - 2; t += 2) {
;       OPAQ;
;       LDB(B0, 0, 0); SCHED; LDA(At, 0, 0); STAGE_A(SA(1, 1), 1, t + 1);
;       WAIT_L(8); BAR; WAIT_L(0); MMA(0, 0, At, B0); BAR; SCHED;
;       LDB(B1, 0, 1); STAGE_B(SB(0, 0), 0, t + 2);
;       BAR; WAIT_L(0); MMA(0, 1, At, B1); BAR;
;       LDA(At, 0, 1); STAGE_A(SA(0, 0), 0, t + 2);
;       BAR; WAIT_L(0); MMA(1, 0, At, B0); BAR; SCHED;
;       STAGE_B(SB(0, 1), 1, t + 2);
;       WAIT_V(6); BAR; MMA(1, 1, At, B1); BAR;
.LBB0_1010:
	s_nop 0
	v_add_u32_e32 v130, 0, v153
	v_add_u32_e32 v141, 0, v152
	ds_read_b128 v[156:159], v130
	ds_read_b128 v[160:163], v130 offset:1024
	ds_read_b128 v[164:167], v130 offset:2048
	ds_read_b128 v[168:171], v130 offset:3072
	ds_read_b128 v[204:207], v130 offset:16384
	ds_read_b128 v[208:211], v130 offset:17408
	ds_read_b128 v[212:215], v130 offset:18432
	ds_read_b128 v[216:219], v130 offset:19456
	ds_read_b128 v[172:175], v141
	ds_read_b128 v[176:179], v141 offset:1024
	ds_read_b128 v[180:183], v141 offset:2048
	ds_read_b128 v[184:187], v141 offset:3072
	ds_read_b128 v[188:191], v141 offset:4096
	ds_read_b128 v[192:195], v141 offset:5120
	ds_read_b128 v[196:199], v141 offset:6144
	ds_read_b128 v[200:203], v141 offset:7168
	s_mov_b32 m0, s80
	s_nop 0
	global_load_lds_dwordx4 v220, s[98:99]
	s_mov_b32 m0, s81
	s_nop 0
	global_load_lds_dwordx4 v221, s[98:99]
	s_waitcnt vmcnt(8)
	s_waitcnt lgkmcnt(0)
	s_barrier
	v_mfma_f32_16x16x32_bf16 v[126:129], v[156:159], v[172:175], v[126:129]
	v_mfma_f32_16x16x32_bf16 v[122:125], v[164:167], v[172:175], v[122:125]
	v_mfma_f32_16x16x32_bf16 v[118:121], v[156:159], v[180:183], v[118:121]
	v_mfma_f32_16x16x32_bf16 v[114:117], v[164:167], v[180:183], v[114:117]
	v_mfma_f32_16x16x32_bf16 v[110:113], v[156:159], v[188:191], v[110:113]
	v_mfma_f32_16x16x32_bf16 v[106:109], v[164:167], v[188:191], v[106:109]
	v_mfma_f32_16x16x32_bf16 v[102:105], v[156:159], v[196:199], v[102:105]
	v_mfma_f32_16x16x32_bf16 v[98:101], v[164:167], v[196:199], v[98:101]
	v_mfma_f32_16x16x32_bf16 v[126:129], v[160:163], v[176:179], v[126:129]
	v_mfma_f32_16x16x32_bf16 v[122:125], v[168:171], v[176:179], v[122:125]
	v_mfma_f32_16x16x32_bf16 v[118:121], v[160:163], v[184:187], v[118:121]
	v_mfma_f32_16x16x32_bf16 v[114:117], v[168:171], v[184:187], v[114:117]
	v_mfma_f32_16x16x32_bf16 v[110:113], v[160:163], v[192:195], v[110:113]
	v_mfma_f32_16x16x32_bf16 v[106:109], v[168:171], v[192:195], v[106:109]
	v_mfma_f32_16x16x32_bf16 v[102:105], v[160:163], v[200:203], v[102:105]
	v_mfma_f32_16x16x32_bf16 v[98:101], v[168:171], v[200:203], v[98:101]
	v_mfma_f32_16x16x32_bf16 v[86:89], v[204:207], v[172:175], v[86:89]
	v_mfma_f32_16x16x32_bf16 v[70:73], v[212:215], v[172:175], v[70:73]
	v_mfma_f32_16x16x32_bf16 v[54:57], v[204:207], v[180:183], v[54:57]
	v_mfma_f32_16x16x32_bf16 v[50:53], v[212:215], v[180:183], v[50:53]
	v_mfma_f32_16x16x32_bf16 v[46:49], v[204:207], v[188:191], v[46:49]
	v_mfma_f32_16x16x32_bf16 v[42:45], v[212:215], v[188:191], v[42:45]
	v_mfma_f32_16x16x32_bf16 v[38:41], v[204:207], v[196:199], v[38:41]
	v_mfma_f32_16x16x32_bf16 v[34:37], v[212:215], v[196:199], v[34:37]
	v_mfma_f32_16x16x32_bf16 v[86:89], v[208:211], v[176:179], v[86:89]
	v_mfma_f32_16x16x32_bf16 v[70:73], v[216:219], v[176:179], v[70:73]
	v_mfma_f32_16x16x32_bf16 v[54:57], v[208:211], v[184:187], v[54:57]
	v_mfma_f32_16x16x32_bf16 v[50:53], v[216:219], v[184:187], v[50:53]
	v_mfma_f32_16x16x32_bf16 v[46:49], v[208:211], v[192:195], v[46:49]
	v_mfma_f32_16x16x32_bf16 v[42:45], v[216:219], v[192:195], v[42:45]
	v_mfma_f32_16x16x32_bf16 v[38:41], v[208:211], v[200:203], v[38:41]
	v_mfma_f32_16x16x32_bf16 v[34:37], v[216:219], v[200:203], v[34:37]
	s_barrier
	ds_read_b128 v[172:175], v141 offset:16384
	ds_read_b128 v[176:179], v141 offset:17408
	ds_read_b128 v[180:183], v141 offset:18432
	ds_read_b128 v[184:187], v141 offset:19456
	ds_read_b128 v[188:191], v141 offset:20480
	ds_read_b128 v[192:195], v141 offset:21504
	ds_read_b128 v[196:199], v141 offset:22528
	ds_read_b128 v[200:203], v141 offset:23552
	s_mov_b32 m0, s35
	s_nop 0
	global_load_lds_dwordx4 v222, s[100:101]
	s_mov_b32 m0, s64
	s_nop 0
	global_load_lds_dwordx4 v223, s[100:101]
	s_mov_b32 m0, s34
	s_nop 0
	global_load_lds_dwordx4 v224, s[98:99]
	s_mov_b32 m0, s65
	s_nop 0
	global_load_lds_dwordx4 v225, s[98:99]
	s_mov_b32 m0, s66
	s_nop 0
	global_load_lds_dwordx4 v226, s[100:101]
	s_mov_b32 m0, s67
	s_nop 0
	global_load_lds_dwordx4 v227, s[100:101]
	s_waitcnt vmcnt(8)
	s_waitcnt lgkmcnt(0)
	s_barrier
	v_mfma_f32_16x16x32_bf16 v[30:33], v[156:159], v[172:175], v[30:33]
	v_mfma_f32_16x16x32_bf16 v[26:29], v[164:167], v[172:175], v[26:29]
	v_mfma_f32_16x16x32_bf16 v[22:25], v[156:159], v[180:183], v[22:25]
	v_mfma_f32_16x16x32_bf16 v[18:21], v[164:167], v[180:183], v[18:21]
	v_mfma_f32_16x16x32_bf16 v[14:17], v[156:159], v[188:191], v[14:17]
	v_mfma_f32_16x16x32_bf16 v[10:13], v[164:167], v[188:191], v[10:13]
	v_mfma_f32_16x16x32_bf16 v[6:9], v[156:159], v[196:199], v[6:9]
	v_mfma_f32_16x16x32_bf16 v[2:5], v[164:167], v[196:199], v[2:5]
	v_mfma_f32_16x16x32_bf16 v[30:33], v[160:163], v[176:179], v[30:33]
	v_mfma_f32_16x16x32_bf16 v[26:29], v[168:171], v[176:179], v[26:29]
	v_mfma_f32_16x16x32_bf16 v[22:25], v[160:163], v[184:187], v[22:25]
	v_mfma_f32_16x16x32_bf16 v[18:21], v[168:171], v[184:187], v[18:21]
	v_mfma_f32_16x16x32_bf16 v[14:17], v[160:163], v[192:195], v[14:17]
	v_mfma_f32_16x16x32_bf16 v[10:13], v[168:171], v[192:195], v[10:13]
	v_mfma_f32_16x16x32_bf16 v[6:9], v[160:163], v[200:203], v[6:9]
	v_mfma_f32_16x16x32_bf16 v[2:5], v[168:171], v[200:203], v[2:5]
	v_mfma_f32_16x16x32_bf16 v[58:61], v[204:207], v[172:175], v[58:61]
	v_mfma_f32_16x16x32_bf16 v[62:65], v[212:215], v[172:175], v[62:65]
	v_mfma_f32_16x16x32_bf16 v[66:69], v[204:207], v[180:183], v[66:69]
	v_mfma_f32_16x16x32_bf16 v[74:77], v[212:215], v[180:183], v[74:77]
	v_mfma_f32_16x16x32_bf16 v[78:81], v[204:207], v[188:191], v[78:81]
	v_mfma_f32_16x16x32_bf16 v[82:85], v[212:215], v[188:191], v[82:85]
	v_mfma_f32_16x16x32_bf16 v[90:93], v[204:207], v[196:199], v[90:93]
	v_mfma_f32_16x16x32_bf16 v[94:97], v[212:215], v[196:199], v[94:97]
	v_mfma_f32_16x16x32_bf16 v[58:61], v[208:211], v[176:179], v[58:61]
	v_mfma_f32_16x16x32_bf16 v[62:65], v[216:219], v[176:179], v[62:65]
	v_mfma_f32_16x16x32_bf16 v[66:69], v[208:211], v[184:187], v[66:69]
	v_mfma_f32_16x16x32_bf16 v[74:77], v[216:219], v[184:187], v[74:77]
	v_mfma_f32_16x16x32_bf16 v[78:81], v[208:211], v[192:195], v[78:81]
	v_mfma_f32_16x16x32_bf16 v[82:85], v[216:219], v[192:195], v[82:85]
	v_mfma_f32_16x16x32_bf16 v[90:93], v[208:211], v[200:203], v[90:93]
	v_mfma_f32_16x16x32_bf16 v[94:97], v[216:219], v[200:203], v[94:97]
	s_barrier
; #define LDA(dst, b, h)                                                                                     \
;   _Pragma("unroll") for (int m = 0; m < 4; ++m) _Pragma("unroll") for (int k = 0; k < 2; ++k) dst[m][k] = \
;       *reinterpret_cast<const bf16x8*>(shmc + aL + (((b) * 2 + (h)) * 16384 + (m * 2 + k) * 1024))
; #define LDB(dst, b, h)                                                                                     \
;   _Pragma("unroll") for (int n = 0; n < 2; ++n) _Pragma("unroll") for (int k = 0; k < 2; ++k) dst[n][k] = \
;       *reinterpret_cast<const bf16x8*>(shmc + bL + (((b) * 2 + (h)) * 16384 + (n * 2 + k) * 1024))
; #define WAIT_V(n) asm volatile("s_waitcnt vmcnt(" #n ")" ::: "memory")
; #define WAIT_L(n) asm volatile("s_waitcnt lgkmcnt(" #n ")" ::: "memory")
; #define BAR __builtin_amdgcn_s_barrier()
; #define SCHED __builtin_amdgcn_sched_barrier(0)
; template <int EPI>
; __device__ __forceinline__ void phase_gemm(const Params& p, const GemmDesc& d, char* shmc) {
;     ...
;       LDB(B0, 1, 0); SCHED; LDA(At, 1, 0); STAGE_A(SA(0, 1), 1, t + 2);
;       WAIT_L(8); BAR; WAIT_L(0); MMA(0, 0, At, B0); BAR; SCHED;
;       LDB(B1, 1, 1); STAGE_B(SB(1, 0), 0, t + 3);
;       BAR; WAIT_L(0); MMA(0, 1, At, B1); BAR;
;       LDA(At, 1, 1); STAGE_A(SA(1, 0), 0, t + 3);
;       BAR; WAIT_L(0); MMA(1, 0, At, B0); BAR; SCHED;
;       STAGE_B(SB(1, 1), 1, t + 3);
;       WAIT_V(6); BAR; MMA(1, 1, At, B1); BAR;
	ds_read_b128 v[156:159], v130 offset:32768
	ds_read_b128 v[160:163], v130 offset:33792
	ds_read_b128 v[164:167], v130 offset:34816
	ds_read_b128 v[168:171], v130 offset:35840
	ds_read_b128 v[204:207], v130 offset:49152
	ds_read_b128 v[208:211], v130 offset:50176
	ds_read_b128 v[212:215], v130 offset:51200
	ds_read_b128 v[216:219], v130 offset:52224
	ds_read_b128 v[172:175], v141 offset:32768
	ds_read_b128 v[176:179], v141 offset:33792
	ds_read_b128 v[180:183], v141 offset:34816
	ds_read_b128 v[184:187], v141 offset:35840
	ds_read_b128 v[188:191], v141 offset:36864
	ds_read_b128 v[192:195], v141 offset:37888
	ds_read_b128 v[196:199], v141 offset:38912
	ds_read_b128 v[200:203], v141 offset:39936
	s_mov_b32 m0, s68
	s_nop 0
	global_load_lds_dwordx4 v228, s[98:99]
	s_mov_b32 m0, s69
	s_nop 0
	global_load_lds_dwordx4 v229, s[98:99]
	s_waitcnt vmcnt(8)
	s_waitcnt lgkmcnt(0)
	s_barrier
	v_mfma_f32_16x16x32_bf16 v[126:129], v[156:159], v[172:175], v[126:129]
	v_mfma_f32_16x16x32_bf16 v[122:125], v[164:167], v[172:175], v[122:125]
	v_mfma_f32_16x16x32_bf16 v[118:121], v[156:159], v[180:183], v[118:121]
	v_mfma_f32_16x16x32_bf16 v[114:117], v[164:167], v[180:183], v[114:117]
	v_mfma_f32_16x16x32_bf16 v[110:113], v[156:159], v[188:191], v[110:113]
	v_mfma_f32_16x16x32_bf16 v[106:109], v[164:167], v[188:191], v[106:109]
	v_mfma_f32_16x16x32_bf16 v[102:105], v[156:159], v[196:199], v[102:105]
	v_mfma_f32_16x16x32_bf16 v[98:101], v[164:167], v[196:199], v[98:101]
	v_mfma_f32_16x16x32_bf16 v[126:129], v[160:163], v[176:179], v[126:129]
	v_mfma_f32_16x16x32_bf16 v[122:125], v[168:171], v[176:179], v[122:125]
	v_mfma_f32_16x16x32_bf16 v[118:121], v[160:163], v[184:187], v[118:121]
	v_mfma_f32_16x16x32_bf16 v[114:117], v[168:171], v[184:187], v[114:117]
	v_mfma_f32_16x16x32_bf16 v[110:113], v[160:163], v[192:195], v[110:113]
	v_mfma_f32_16x16x32_bf16 v[106:109], v[168:171], v[192:195], v[106:109]
	v_mfma_f32_16x16x32_bf16 v[102:105], v[160:163], v[200:203], v[102:105]
	v_mfma_f32_16x16x32_bf16 v[98:101], v[168:171], v[200:203], v[98:101]
	v_mfma_f32_16x16x32_bf16 v[86:89], v[204:207], v[172:175], v[86:89]
	v_mfma_f32_16x16x32_bf16 v[70:73], v[212:215], v[172:175], v[70:73]
	v_mfma_f32_16x16x32_bf16 v[54:57], v[204:207], v[180:183], v[54:57]
	v_mfma_f32_16x16x32_bf16 v[50:53], v[212:215], v[180:183], v[50:53]
	v_mfma_f32_16x16x32_bf16 v[46:49], v[204:207], v[188:191], v[46:49]
	v_mfma_f32_16x16x32_bf16 v[42:45], v[212:215], v[188:191], v[42:45]
	v_mfma_f32_16x16x32_bf16 v[38:41], v[204:207], v[196:199], v[38:41]
	v_mfma_f32_16x16x32_bf16 v[34:37], v[212:215], v[196:199], v[34:37]
	v_mfma_f32_16x16x32_bf16 v[86:89], v[208:211], v[176:179], v[86:89]
	v_mfma_f32_16x16x32_bf16 v[70:73], v[216:219], v[176:179], v[70:73]
	v_mfma_f32_16x16x32_bf16 v[54:57], v[208:211], v[184:187], v[54:57]
	v_mfma_f32_16x16x32_bf16 v[50:53], v[216:219], v[184:187], v[50:53]
	v_mfma_f32_16x16x32_bf16 v[46:49], v[208:211], v[192:195], v[46:49]
	v_mfma_f32_16x16x32_bf16 v[42:45], v[216:219], v[192:195], v[42:45]
	v_mfma_f32_16x16x32_bf16 v[38:41], v[208:211], v[200:203], v[38:41]
	v_mfma_f32_16x16x32_bf16 v[34:37], v[216:219], v[200:203], v[34:37]
	s_barrier
	ds_read_b128 v[172:175], v141 offset:49152
	ds_read_b128 v[176:179], v141 offset:50176
	ds_read_b128 v[180:183], v141 offset:51200
	ds_read_b128 v[184:187], v141 offset:52224
	ds_read_b128 v[188:191], v141 offset:53248
	ds_read_b128 v[192:195], v141 offset:54272
	ds_read_b128 v[196:199], v141 offset:55296
	ds_read_b128 v[200:203], v141 offset:56320
	s_mov_b32 m0, s70
	s_nop 0
	global_load_lds_dwordx4 v232, s[100:101]
	s_mov_b32 m0, s71
	s_nop 0
	global_load_lds_dwordx4 v233, s[100:101]
	s_mov_b32 m0, s76
	s_nop 0
	global_load_lds_dwordx4 v234, s[98:99]
	s_mov_b32 m0, s77
	s_nop 0
	global_load_lds_dwordx4 v235, s[98:99]
	s_mov_b32 m0, s78
	s_nop 0
	global_load_lds_dwordx4 v236, s[100:101]
	s_mov_b32 m0, s79
	s_nop 0
	global_load_lds_dwordx4 v237, s[100:101]
	s_add_i32 s53, s53, 2
	s_add_u32 s58, s58, 0x100
	s_addc_u32 s59, s59, 0
	s_add_u32 s98, s98, 0x100
	s_addc_u32 s99, s99, 0
	s_add_u32 s100, s100, 0x100
	s_addc_u32 s101, s101, 0
	s_cmp_gt_u32 s53, 27
	s_waitcnt vmcnt(8)
	s_waitcnt lgkmcnt(0)
	s_barrier
	v_mfma_f32_16x16x32_bf16 v[30:33], v[156:159], v[172:175], v[30:33]
	v_mfma_f32_16x16x32_bf16 v[26:29], v[164:167], v[172:175], v[26:29]
	v_mfma_f32_16x16x32_bf16 v[22:25], v[156:159], v[180:183], v[22:25]
	v_mfma_f32_16x16x32_bf16 v[18:21], v[164:167], v[180:183], v[18:21]
	v_mfma_f32_16x16x32_bf16 v[14:17], v[156:159], v[188:191], v[14:17]
	v_mfma_f32_16x16x32_bf16 v[10:13], v[164:167], v[188:191], v[10:13]
	v_mfma_f32_16x16x32_bf16 v[6:9], v[156:159], v[196:199], v[6:9]
	v_mfma_f32_16x16x32_bf16 v[2:5], v[164:167], v[196:199], v[2:5]
	v_mfma_f32_16x16x32_bf16 v[30:33], v[160:163], v[176:179], v[30:33]
	v_mfma_f32_16x16x32_bf16 v[26:29], v[168:171], v[176:179], v[26:29]
	v_mfma_f32_16x16x32_bf16 v[22:25], v[160:163], v[184:187], v[22:25]
	v_mfma_f32_16x16x32_bf16 v[18:21], v[168:171], v[184:187], v[18:21]
	v_mfma_f32_16x16x32_bf16 v[14:17], v[160:163], v[192:195], v[14:17]
	v_mfma_f32_16x16x32_bf16 v[10:13], v[168:171], v[192:195], v[10:13]
	v_mfma_f32_16x16x32_bf16 v[6:9], v[160:163], v[200:203], v[6:9]
	v_mfma_f32_16x16x32_bf16 v[2:5], v[168:171], v[200:203], v[2:5]
	v_mfma_f32_16x16x32_bf16 v[58:61], v[204:207], v[172:175], v[58:61]
	v_mfma_f32_16x16x32_bf16 v[62:65], v[212:215], v[172:175], v[62:65]
	v_mfma_f32_16x16x32_bf16 v[66:69], v[204:207], v[180:183], v[66:69]
	v_mfma_f32_16x16x32_bf16 v[74:77], v[212:215], v[180:183], v[74:77]
	v_mfma_f32_16x16x32_bf16 v[78:81], v[204:207], v[188:191], v[78:81]
	v_mfma_f32_16x16x32_bf16 v[82:85], v[212:215], v[188:191], v[82:85]
	v_mfma_f32_16x16x32_bf16 v[90:93], v[204:207], v[196:199], v[90:93]
	v_mfma_f32_16x16x32_bf16 v[94:97], v[212:215], v[196:199], v[94:97]
	v_mfma_f32_16x16x32_bf16 v[58:61], v[208:211], v[176:179], v[58:61]
	v_mfma_f32_16x16x32_bf16 v[62:65], v[216:219], v[176:179], v[62:65]
	v_mfma_f32_16x16x32_bf16 v[66:69], v[208:211], v[184:187], v[66:69]
	v_mfma_f32_16x16x32_bf16 v[74:77], v[216:219], v[184:187], v[74:77]
	v_mfma_f32_16x16x32_bf16 v[78:81], v[208:211], v[192:195], v[78:81]
	v_mfma_f32_16x16x32_bf16 v[82:85], v[216:219], v[192:195], v[82:85]
	v_mfma_f32_16x16x32_bf16 v[90:93], v[208:211], v[200:203], v[90:93]
	v_mfma_f32_16x16x32_bf16 v[94:97], v[216:219], v[200:203], v[94:97]
	s_barrier
; #define LDA(dst, b, h)                                                                                     \
;   _Pragma("unroll") for (int m = 0; m < 4; ++m) _Pragma("unroll") for (int k = 0; k < 2; ++k) dst[m][k] = \
;       *reinterpret_cast<const bf16x8*>(shmc + aL + (((b) * 2 + (h)) * 16384 + (m * 2 + k) * 1024))
; #define LDB(dst, b, h)                                                                                     \
;   _Pragma("unroll") for (int n = 0; n < 2; ++n) _Pragma("unroll") for (int k = 0; k < 2; ++k) dst[n][k] = \
;       *reinterpret_cast<const bf16x8*>(shmc + bL + (((b) * 2 + (h)) * 16384 + (n * 2 + k) * 1024))
; #define OPAQ asm volatile("" : "+v"(aL), "+v"(bL))
; #define WAIT_V(n) asm volatile("s_waitcnt vmcnt(" #n ")" ::: "memory")
; #define WAIT_L(n) asm volatile("s_waitcnt lgkmcnt(" #n ")" ::: "memory")
; #define BAR __builtin_amdgcn_s_barrier()
; template <int EPI>
; __device__ __forceinline__ void phase_gemm(const Params& p, const GemmDesc& d, char* shmc) {
;     ...
;     {
;       OPAQ;
;       LDB(B0, 0, 0); LDA(At, 0, 0); STAGE_A(SA(1, 1), 1, nt - 1);
;       BAR; WAIT_L(0); MMA(0, 0, At, B0); BAR;
;       LDB(B1, 0, 1); BAR; WAIT_L(0); MMA(0, 1, At, B1); BAR;
;       LDA(At, 0, 1); WAIT_V(4); BAR; WAIT_L(0); MMA(1, 0, At, B0); MMA(1, 1, At, B1); BAR;
;     }
	s_cbranch_scc0 .LBB0_1010
	s_setprio 0
	s_add_u32 s56, s56, 0x80f80
	s_addc_u32 s57, s57, 0
	v_add_u32_e32 v130, 0, v153
	v_add_u32_e32 v141, 0, v152
	s_mov_b32 m0, s80
	ds_read_b128 v[144:147], v130
	ds_read_b128 v[148:151], v130 offset:1024
	ds_read_b128 v[156:159], v130 offset:2048
	ds_read_b128 v[160:163], v130 offset:3072
	ds_read_b128 v[164:167], v141
	ds_read_b128 v[168:171], v141 offset:1024
	ds_read_b128 v[172:175], v141 offset:2048
	ds_read_b128 v[176:179], v141 offset:3072
	ds_read_b128 v[180:183], v141 offset:4096
	ds_read_b128 v[184:187], v141 offset:5120
	ds_read_b128 v[188:191], v141 offset:6144
	ds_read_b128 v[192:195], v141 offset:7168
	global_load_lds_dwordx4 v140, s[56:57]
	s_mov_b32 m0, s81
	s_nop 0
	global_load_lds_dwordx4 v142, s[56:57]
	s_waitcnt vmcnt(8)
	s_barrier
	s_waitcnt lgkmcnt(0)
	s_setprio 1
	s_waitcnt lgkmcnt(0)
	v_mfma_f32_16x16x32_bf16 v[126:129], v[144:147], v[164:167], v[126:129]
	v_mfma_f32_16x16x32_bf16 v[122:125], v[156:159], v[164:167], v[122:125]
	v_mfma_f32_16x16x32_bf16 v[114:117], v[156:159], v[172:175], v[114:117]
	v_mfma_f32_16x16x32_bf16 v[110:113], v[144:147], v[180:183], v[110:113]
	v_mfma_f32_16x16x32_bf16 v[102:105], v[144:147], v[188:191], v[102:105]
	v_mfma_f32_16x16x32_bf16 v[126:129], v[148:151], v[168:171], v[126:129]
	v_mfma_f32_16x16x32_bf16 v[122:125], v[160:163], v[168:171], v[122:125]
	v_mfma_f32_16x16x32_bf16 v[118:121], v[144:147], v[172:175], v[118:121]
	v_mfma_f32_16x16x32_bf16 v[114:117], v[160:163], v[176:179], v[114:117]
	v_mfma_f32_16x16x32_bf16 v[110:113], v[148:151], v[184:187], v[110:113]
	v_mfma_f32_16x16x32_bf16 v[106:109], v[156:159], v[180:183], v[106:109]
	v_mfma_f32_16x16x32_bf16 v[102:105], v[148:151], v[192:195], v[102:105]
	v_mfma_f32_16x16x32_bf16 v[98:101], v[156:159], v[188:191], v[98:101]
	v_mfma_f32_16x16x32_bf16 v[196:199], v[148:151], v[176:179], v[118:121]
	v_mfma_f32_16x16x32_bf16 v[200:203], v[160:163], v[184:187], v[106:109]
	v_mfma_f32_16x16x32_bf16 v[204:207], v[160:163], v[192:195], v[98:101]
	s_setprio 0
	s_barrier
	s_nop 2
	ds_read_b128 v[98:101], v130 offset:16384
	ds_read_b128 v[106:109], v130 offset:17408
	ds_read_b128 v[118:121], v130 offset:18432
	ds_read_b128 v[208:211], v130 offset:19456
	s_barrier
	s_waitcnt lgkmcnt(0)
	s_setprio 1
	s_waitcnt lgkmcnt(0)
	v_mfma_f32_16x16x32_bf16 v[86:89], v[98:101], v[164:167], v[86:89]
	v_mfma_f32_16x16x32_bf16 v[70:73], v[118:121], v[164:167], v[70:73]
	v_mfma_f32_16x16x32_bf16 v[54:57], v[98:101], v[172:175], v[54:57]
	v_mfma_f32_16x16x32_bf16 v[50:53], v[118:121], v[172:175], v[50:53]
	v_mfma_f32_16x16x32_bf16 v[46:49], v[98:101], v[180:183], v[46:49]
	v_mfma_f32_16x16x32_bf16 v[42:45], v[118:121], v[180:183], v[42:45]
	v_mfma_f32_16x16x32_bf16 v[38:41], v[98:101], v[188:191], v[38:41]
	v_mfma_f32_16x16x32_bf16 v[34:37], v[118:121], v[188:191], v[34:37]
	v_mfma_f32_16x16x32_bf16 v[86:89], v[106:109], v[168:171], v[86:89]
	v_mfma_f32_16x16x32_bf16 v[70:73], v[208:211], v[168:171], v[70:73]
	v_mfma_f32_16x16x32_bf16 v[54:57], v[106:109], v[176:179], v[54:57]
	v_mfma_f32_16x16x32_bf16 v[50:53], v[208:211], v[176:179], v[50:53]
	v_mfma_f32_16x16x32_bf16 v[46:49], v[106:109], v[184:187], v[46:49]
	v_mfma_f32_16x16x32_bf16 v[42:45], v[208:211], v[184:187], v[42:45]
	v_mfma_f32_16x16x32_bf16 v[38:41], v[106:109], v[192:195], v[38:41]
	v_mfma_f32_16x16x32_bf16 v[34:37], v[208:211], v[192:195], v[34:37]
	s_setprio 0
	s_barrier
	ds_read_b128 v[164:167], v141 offset:16384
	ds_read_b128 v[168:171], v141 offset:17408
	ds_read_b128 v[172:175], v141 offset:18432
	ds_read_b128 v[176:179], v141 offset:19456
	ds_read_b128 v[180:183], v141 offset:20480
	ds_read_b128 v[184:187], v141 offset:21504
	ds_read_b128 v[188:191], v141 offset:22528
	ds_read_b128 v[192:195], v141 offset:23552
	s_waitcnt vmcnt(4)
	s_barrier
	s_waitcnt lgkmcnt(0)
	s_setprio 1
	s_waitcnt lgkmcnt(0)
	v_mfma_f32_16x16x32_bf16 v[30:33], v[144:147], v[164:167], v[30:33]
	v_mfma_f32_16x16x32_bf16 v[26:29], v[156:159], v[164:167], v[26:29]
	v_mfma_f32_16x16x32_bf16 v[22:25], v[144:147], v[172:175], v[22:25]
	v_mfma_f32_16x16x32_bf16 v[18:21], v[156:159], v[172:175], v[18:21]
	v_mfma_f32_16x16x32_bf16 v[14:17], v[144:147], v[180:183], v[14:17]
	v_mfma_f32_16x16x32_bf16 v[10:13], v[156:159], v[180:183], v[10:13]
	v_mfma_f32_16x16x32_bf16 v[6:9], v[144:147], v[188:191], v[6:9]
	v_mfma_f32_16x16x32_bf16 v[2:5], v[156:159], v[188:191], v[2:5]
	v_mfma_f32_16x16x32_bf16 v[30:33], v[148:151], v[168:171], v[30:33]
	v_mfma_f32_16x16x32_bf16 v[26:29], v[160:163], v[168:171], v[26:29]
	v_mfma_f32_16x16x32_bf16 v[22:25], v[148:151], v[176:179], v[22:25]
	v_mfma_f32_16x16x32_bf16 v[18:21], v[160:163], v[176:179], v[18:21]
	v_mfma_f32_16x16x32_bf16 v[14:17], v[148:151], v[184:187], v[14:17]
	v_mfma_f32_16x16x32_bf16 v[10:13], v[160:163], v[184:187], v[10:13]
	v_mfma_f32_16x16x32_bf16 v[6:9], v[148:151], v[192:195], v[6:9]
	v_mfma_f32_16x16x32_bf16 v[2:5], v[160:163], v[192:195], v[2:5]
	s_setprio 0
	s_setprio 1
	v_mfma_f32_16x16x32_bf16 v[62:65], v[118:121], v[164:167], v[62:65]
	v_mfma_f32_16x16x32_bf16 v[144:147], v[208:211], v[168:171], v[62:65]
	v_mfma_f32_16x16x32_bf16 v[62:65], v[98:101], v[172:175], v[66:69]
	v_mfma_f32_16x16x32_bf16 v[148:151], v[106:109], v[176:179], v[62:65]
	v_mfma_f32_16x16x32_bf16 v[62:65], v[118:121], v[172:175], v[74:77]
	v_mfma_f32_16x16x32_bf16 v[156:159], v[208:211], v[176:179], v[62:65]
	v_mfma_f32_16x16x32_bf16 v[62:65], v[98:101], v[180:183], v[78:81]
	v_mfma_f32_16x16x32_bf16 v[160:163], v[106:109], v[184:187], v[62:65]
	v_mfma_f32_16x16x32_bf16 v[62:65], v[118:121], v[180:183], v[82:85]
	v_mfma_f32_16x16x32_bf16 v[58:61], v[98:101], v[164:167], v[58:61]
	v_mfma_f32_16x16x32_bf16 v[164:167], v[208:211], v[184:187], v[62:65]
	v_mfma_f32_16x16x32_bf16 v[62:65], v[98:101], v[188:191], v[90:93]
	v_mfma_f32_16x16x32_bf16 v[58:61], v[106:109], v[168:171], v[58:61]
	v_mfma_f32_16x16x32_bf16 v[168:171], v[106:109], v[192:195], v[62:65]
	v_mfma_f32_16x16x32_bf16 v[62:65], v[118:121], v[188:191], v[94:97]
	v_mfma_f32_16x16x32_bf16 v[172:175], v[208:211], v[192:195], v[62:65]
	s_setprio 0
	s_barrier
; #define LDA(dst, b, h)                                                                                     \
;   _Pragma("unroll") for (int m = 0; m < 4; ++m) _Pragma("unroll") for (int k = 0; k < 2; ++k) dst[m][k] = \
;       *reinterpret_cast<const bf16x8*>(shmc + aL + (((b) * 2 + (h)) * 16384 + (m * 2 + k) * 1024))
; #define LDB(dst, b, h)                                                                                     \
;   _Pragma("unroll") for (int n = 0; n < 2; ++n) _Pragma("unroll") for (int k = 0; k < 2; ++k) dst[n][k] = \
;       *reinterpret_cast<const bf16x8*>(shmc + bL + (((b) * 2 + (h)) * 16384 + (n * 2 + k) * 1024))
; #define WAIT_V(n) asm volatile("s_waitcnt vmcnt(" #n ")" ::: "memory")
; #define WAIT_L(n) asm volatile("s_waitcnt lgkmcnt(" #n ")" ::: "memory")
; #define BAR __builtin_amdgcn_s_barrier()
; template <int EPI>
; __device__ __forceinline__ void phase_gemm(const Params& p, const GemmDesc& d, char* shmc) {
;     ...
;     {
;       LDB(B0, 1, 0); LDA(At, 1, 0); WAIT_V(2); BAR; WAIT_L(0); MMA(0, 0, At, B0); BAR;
;       LDB(B1, 1, 1); WAIT_V(0); BAR; WAIT_L(0); MMA(0, 1, At, B1); BAR;
;       LDA(At, 1, 1); BAR; WAIT_L(0); MMA(1, 0, At, B0); MMA(1, 1, At, B1); BAR;
;     }
;     if (wr == 0) BAR;
	ds_read_b128 v[176:179], v130 offset:32768
	ds_read_b128 v[180:183], v130 offset:33792
	ds_read_b128 v[184:187], v130 offset:34816
	ds_read_b128 v[188:191], v130 offset:35840
	s_nop 0
	ds_read_b128 v[62:65], v141 offset:32768
	ds_read_b128 v[78:81], v141 offset:33792
	ds_read_b128 v[94:97], v141 offset:34816
	ds_read_b128 v[192:195], v141 offset:35840
	ds_read_b128 v[208:211], v141 offset:36864
	ds_read_b128 v[212:215], v141 offset:37888
	ds_read_b128 v[216:219], v141 offset:38912
	ds_read_b128 v[220:223], v141 offset:39936
	s_waitcnt vmcnt(2)
	s_barrier
	s_waitcnt lgkmcnt(0)
	s_setprio 1
	s_waitcnt lgkmcnt(0)
	v_mfma_f32_16x16x32_bf16 v[66:69], v[176:179], v[62:65], v[126:129]
	v_mfma_f32_16x16x32_bf16 v[126:129], v[180:183], v[78:81], v[66:69]
	v_mfma_f32_16x16x32_bf16 v[66:69], v[184:187], v[62:65], v[122:125]
	v_mfma_f32_16x16x32_bf16 v[118:121], v[188:191], v[78:81], v[66:69]
	v_mfma_f32_16x16x32_bf16 v[66:69], v[176:179], v[94:97], v[196:199]
	v_mfma_f32_16x16x32_bf16 v[106:109], v[180:183], v[192:195], v[66:69]
	v_mfma_f32_16x16x32_bf16 v[66:69], v[184:187], v[94:97], v[114:117]
	v_mfma_f32_16x16x32_bf16 v[98:101], v[188:191], v[192:195], v[66:69]
	v_mfma_f32_16x16x32_bf16 v[66:69], v[176:179], v[208:211], v[110:113]
	v_mfma_f32_16x16x32_bf16 v[90:93], v[180:183], v[212:215], v[66:69]
	v_mfma_f32_16x16x32_bf16 v[66:69], v[184:187], v[208:211], v[200:203]
	v_mfma_f32_16x16x32_bf16 v[82:85], v[188:191], v[212:215], v[66:69]
	v_mfma_f32_16x16x32_bf16 v[66:69], v[176:179], v[216:219], v[102:105]
	v_mfma_f32_16x16x32_bf16 v[74:77], v[180:183], v[220:223], v[66:69]
	v_mfma_f32_16x16x32_bf16 v[66:69], v[184:187], v[216:219], v[204:207]
	v_mfma_f32_16x16x32_bf16 v[66:69], v[188:191], v[220:223], v[66:69]
	s_setprio 0
	s_barrier
	ds_read_b128 v[196:199], v130 offset:49152
	ds_read_b128 v[200:203], v130 offset:50176
	ds_read_b128 v[204:207], v130 offset:51200
	ds_read_b128 v[224:227], v130 offset:52224
	s_waitcnt vmcnt(0)
	s_barrier
	s_waitcnt lgkmcnt(0)
	s_setprio 1
	s_waitcnt lgkmcnt(0)
	v_mfma_f32_16x16x32_bf16 v[86:89], v[196:199], v[62:65], v[86:89]
	v_mfma_f32_16x16x32_bf16 v[62:65], v[204:207], v[62:65], v[70:73]
	v_mfma_f32_16x16x32_bf16 v[54:57], v[196:199], v[94:97], v[54:57]
	v_mfma_f32_16x16x32_bf16 v[50:53], v[204:207], v[94:97], v[50:53]
	v_mfma_f32_16x16x32_bf16 v[46:49], v[196:199], v[208:211], v[46:49]
	v_mfma_f32_16x16x32_bf16 v[42:45], v[204:207], v[208:211], v[42:45]
	v_mfma_f32_16x16x32_bf16 v[38:41], v[196:199], v[216:219], v[38:41]
	v_mfma_f32_16x16x32_bf16 v[34:37], v[204:207], v[216:219], v[34:37]
	v_mfma_f32_16x16x32_bf16 v[122:125], v[200:203], v[78:81], v[86:89]
	v_mfma_f32_16x16x32_bf16 v[114:117], v[224:227], v[78:81], v[62:65]
	v_mfma_f32_16x16x32_bf16 v[110:113], v[200:203], v[192:195], v[54:57]
	v_mfma_f32_16x16x32_bf16 v[102:105], v[224:227], v[192:195], v[50:53]
	v_mfma_f32_16x16x32_bf16 v[94:97], v[200:203], v[212:215], v[46:49]
	v_mfma_f32_16x16x32_bf16 v[86:89], v[224:227], v[212:215], v[42:45]
	v_mfma_f32_16x16x32_bf16 v[78:81], v[200:203], v[220:223], v[38:41]
	v_mfma_f32_16x16x32_bf16 v[70:73], v[224:227], v[220:223], v[34:37]
	s_setprio 0
	s_barrier
	s_nop 0
	ds_read_b128 v[34:37], v141 offset:49152
	ds_read_b128 v[42:45], v141 offset:50176
	ds_read_b128 v[192:195], v141 offset:51200
	ds_read_b128 v[208:211], v141 offset:52224
	ds_read_b128 v[212:215], v141 offset:53248
	ds_read_b128 v[216:219], v141 offset:54272
	ds_read_b128 v[220:223], v141 offset:55296
	ds_read_b128 v[228:231], v141 offset:56320
	s_barrier
	s_waitcnt lgkmcnt(0)
	s_setprio 1
	s_waitcnt lgkmcnt(0)
	v_mfma_f32_16x16x32_bf16 v[30:33], v[176:179], v[34:37], v[30:33]
	v_mfma_f32_16x16x32_bf16 v[26:29], v[184:187], v[34:37], v[26:29]
	v_mfma_f32_16x16x32_bf16 v[22:25], v[176:179], v[192:195], v[22:25]
	v_mfma_f32_16x16x32_bf16 v[18:21], v[184:187], v[192:195], v[18:21]
	v_mfma_f32_16x16x32_bf16 v[14:17], v[176:179], v[212:215], v[14:17]
	v_mfma_f32_16x16x32_bf16 v[10:13], v[184:187], v[212:215], v[10:13]
	v_mfma_f32_16x16x32_bf16 v[6:9], v[176:179], v[220:223], v[6:9]
	v_mfma_f32_16x16x32_bf16 v[2:5], v[184:187], v[220:223], v[2:5]
	v_mfma_f32_16x16x32_bf16 v[62:65], v[180:183], v[42:45], v[30:33]
	v_mfma_f32_16x16x32_bf16 v[54:57], v[188:191], v[42:45], v[26:29]
	v_mfma_f32_16x16x32_bf16 v[46:49], v[180:183], v[208:211], v[22:25]
	v_mfma_f32_16x16x32_bf16 v[38:41], v[188:191], v[208:211], v[18:21]
	v_mfma_f32_16x16x32_bf16 v[30:33], v[180:183], v[216:219], v[14:17]
	v_mfma_f32_16x16x32_bf16 v[22:25], v[188:191], v[216:219], v[10:13]
	v_mfma_f32_16x16x32_bf16 v[14:17], v[180:183], v[228:231], v[6:9]
	v_mfma_f32_16x16x32_bf16 v[6:9], v[188:191], v[228:231], v[2:5]
	s_setprio 0
	s_setprio 1
	v_mfma_f32_16x16x32_bf16 v[2:5], v[196:199], v[34:37], v[58:61]
	v_mfma_f32_16x16x32_bf16 v[58:61], v[200:203], v[42:45], v[2:5]
	v_mfma_f32_16x16x32_bf16 v[2:5], v[204:207], v[34:37], v[144:147]
	v_mfma_f32_16x16x32_bf16 v[50:53], v[224:227], v[42:45], v[2:5]
	v_mfma_f32_16x16x32_bf16 v[2:5], v[196:199], v[192:195], v[148:151]
	v_mfma_f32_16x16x32_bf16 v[42:45], v[200:203], v[208:211], v[2:5]
	v_mfma_f32_16x16x32_bf16 v[2:5], v[204:207], v[192:195], v[156:159]
	v_mfma_f32_16x16x32_bf16 v[34:37], v[224:227], v[208:211], v[2:5]
	v_mfma_f32_16x16x32_bf16 v[2:5], v[196:199], v[212:215], v[160:163]
	v_mfma_f32_16x16x32_bf16 v[26:29], v[200:203], v[216:219], v[2:5]
	v_mfma_f32_16x16x32_bf16 v[2:5], v[204:207], v[212:215], v[164:167]
	v_mfma_f32_16x16x32_bf16 v[18:21], v[224:227], v[216:219], v[2:5]
	v_mfma_f32_16x16x32_bf16 v[2:5], v[196:199], v[220:223], v[168:171]
	v_mfma_f32_16x16x32_bf16 v[10:13], v[200:203], v[228:231], v[2:5]
	v_mfma_f32_16x16x32_bf16 v[2:5], v[204:207], v[220:223], v[172:175]
	v_mfma_f32_16x16x32_bf16 v[2:5], v[224:227], v[228:231], v[2:5]
	s_setprio 0
	s_barrier
	s_and_saveexec_b64 s[56:57], s[4:5]
	s_cbranch_execz .LBB0_1013
	s_barrier

; #define LDA(dst, b, h)                                                                                     \
;   _Pragma("unroll") for (int m = 0; m < 4; ++m) _Pragma("unroll") for (int k = 0; k < 2; ++k) dst[m][k] = \
;       *reinterpret_cast<const bf16x8*>(shmc + aL + (((b) * 2 + (h)) * 16384 + (m * 2 + k) * 1024))
; #define LDB(dst, b, h)                                                                                     \
;   _Pragma("unroll") for (int n = 0; n < 2; ++n) _Pragma("unroll") for (int k = 0; k < 2; ++k) dst[n][k] = \
;       *reinterpret_cast<const bf16x8*>(shmc + bL + (((b) * 2 + (h)) * 16384 + (n * 2 + k) * 1024))
; #define OPAQ asm volatile("" : "+v"(aL), "+v"(bL))
; #define WAIT_V(n) asm volatile("s_waitcnt vmcnt(" #n ")" ::: "memory")
; #define WAIT_L(n) asm volatile("s_waitcnt lgkmcnt(" #n ")" ::: "memory")
; #define BAR __builtin_amdgcn_s_barrier()
; #define SCHED __builtin_amdgcn_sched_barrier(0)
; template <int EPI>
; __device__ __forceinline__ void phase_gemm(const Params& p, const GemmDesc& d, char* shmc) {
;     ...
;     for (int t = 0; t < nt - 2; t += 2) {
;       OPAQ;
;       LDB(B0, 0, 0); SCHED; LDA(At, 0, 0); STAGE_A(SA(1, 1), 1, t + 1);
;       WAIT_L(8); BAR; WAIT_L(0); MMA(0, 0, At, B0); BAR; SCHED;
;       LDB(B1, 0, 1); STAGE_B(SB(0, 0), 0, t + 2);
;       BAR; WAIT_L(0); MMA(0, 1, At, B1); BAR;
;       LDA(At, 0, 1); STAGE_A(SA(0, 0), 0, t + 2);
;       BAR; WAIT_L(0); MMA(1, 0, At, B0); BAR; SCHED;
;       STAGE_B(SB(0, 1), 1, t + 2);
;       WAIT_V(6); BAR; MMA(1, 1, At, B1); BAR;
.LBB0_1153:
	s_nop 0
	v_add_u32_e32 v162, 0, v205
	v_add_u32_e32 v175, 0, v204
	ds_read_b128 v[138:141], v162
	ds_read_b128 v[142:145], v162 offset:1024
	ds_read_b128 v[146:149], v162 offset:2048
	ds_read_b128 v[150:153], v162 offset:3072
	ds_read_b128 v[208:211], v162 offset:16384
	ds_read_b128 v[212:215], v162 offset:17408
	ds_read_b128 v[216:219], v162 offset:18432
	ds_read_b128 v[220:223], v162 offset:19456
	ds_read_b128 v[154:157], v175
	ds_read_b128 v[158:161], v175 offset:1024
	ds_read_b128 v[178:181], v175 offset:2048
	ds_read_b128 v[182:185], v175 offset:3072
	ds_read_b128 v[186:189], v175 offset:4096
	ds_read_b128 v[190:193], v175 offset:5120
	ds_read_b128 v[194:197], v175 offset:6144
	ds_read_b128 v[198:201], v175 offset:7168
	s_add_i32 s59, s64, 0xc000
	s_mov_b32 m0, s59
	s_nop 0
	global_load_lds_dwordx4 v202, s[98:99]
	s_add_i32 s68, s64, 0xe000
	s_mov_b32 m0, s68
	s_nop 0
	global_load_lds_dwordx4 v203, s[98:99]
	s_waitcnt vmcnt(8)
	s_waitcnt lgkmcnt(0)
	s_barrier
	v_mfma_f32_16x16x32_bf16 v[2:5], v[154:157], v[138:141], v[2:5]
	v_mfma_f32_16x16x32_bf16 v[6:9], v[154:157], v[146:149], v[6:9]
	v_mfma_f32_16x16x32_bf16 v[10:13], v[178:181], v[138:141], v[10:13]
	v_mfma_f32_16x16x32_bf16 v[18:21], v[178:181], v[146:149], v[18:21]
	v_mfma_f32_16x16x32_bf16 v[30:33], v[186:189], v[138:141], v[30:33]
	v_mfma_f32_16x16x32_bf16 v[42:45], v[186:189], v[146:149], v[42:45]
	v_mfma_f32_16x16x32_bf16 v[54:57], v[194:197], v[138:141], v[54:57]
	v_mfma_f32_16x16x32_bf16 v[66:69], v[194:197], v[146:149], v[66:69]
	v_mfma_f32_16x16x32_bf16 v[2:5], v[158:161], v[142:145], v[2:5]
	v_mfma_f32_16x16x32_bf16 v[6:9], v[158:161], v[150:153], v[6:9]
	v_mfma_f32_16x16x32_bf16 v[10:13], v[182:185], v[142:145], v[10:13]
	v_mfma_f32_16x16x32_bf16 v[18:21], v[182:185], v[150:153], v[18:21]
	v_mfma_f32_16x16x32_bf16 v[30:33], v[190:193], v[142:145], v[30:33]
	v_mfma_f32_16x16x32_bf16 v[42:45], v[190:193], v[150:153], v[42:45]
	v_mfma_f32_16x16x32_bf16 v[54:57], v[198:201], v[142:145], v[54:57]
	v_mfma_f32_16x16x32_bf16 v[66:69], v[198:201], v[150:153], v[66:69]
	v_mfma_f32_16x16x32_bf16 v[14:17], v[154:157], v[208:211], v[14:17]
	v_mfma_f32_16x16x32_bf16 v[22:25], v[154:157], v[216:219], v[22:25]
	v_mfma_f32_16x16x32_bf16 v[34:37], v[178:181], v[208:211], v[34:37]
	v_mfma_f32_16x16x32_bf16 v[46:49], v[178:181], v[216:219], v[46:49]
	v_mfma_f32_16x16x32_bf16 v[58:61], v[186:189], v[208:211], v[58:61]
	v_mfma_f32_16x16x32_bf16 v[70:73], v[186:189], v[216:219], v[70:73]
	v_mfma_f32_16x16x32_bf16 v[78:81], v[194:197], v[208:211], v[78:81]
	v_mfma_f32_16x16x32_bf16 v[86:89], v[194:197], v[216:219], v[86:89]
	v_mfma_f32_16x16x32_bf16 v[14:17], v[158:161], v[212:215], v[14:17]
	v_mfma_f32_16x16x32_bf16 v[22:25], v[158:161], v[220:223], v[22:25]
	v_mfma_f32_16x16x32_bf16 v[34:37], v[182:185], v[212:215], v[34:37]
	v_mfma_f32_16x16x32_bf16 v[46:49], v[182:185], v[220:223], v[46:49]
	v_mfma_f32_16x16x32_bf16 v[58:61], v[190:193], v[212:215], v[58:61]
	v_mfma_f32_16x16x32_bf16 v[70:73], v[190:193], v[220:223], v[70:73]
	v_mfma_f32_16x16x32_bf16 v[78:81], v[198:201], v[212:215], v[78:81]
	v_mfma_f32_16x16x32_bf16 v[86:89], v[198:201], v[220:223], v[86:89]
	s_barrier
	ds_read_b128 v[154:157], v175 offset:16384
	ds_read_b128 v[158:161], v175 offset:17408
	ds_read_b128 v[178:181], v175 offset:18432
	ds_read_b128 v[182:185], v175 offset:19456
	ds_read_b128 v[186:189], v175 offset:20480
	ds_read_b128 v[190:193], v175 offset:21504
	ds_read_b128 v[194:197], v175 offset:22528
	ds_read_b128 v[198:201], v175 offset:23552
	s_mov_b32 m0, s65
	s_nop 0
	global_load_lds_dwordx4 v224, s[100:101]
	s_mov_b32 m0, s66
	s_nop 0
	global_load_lds_dwordx4 v225, s[100:101]
	s_mov_b32 m0, s64
	s_nop 0
	global_load_lds_dwordx4 v226, s[98:99]
	s_mov_b32 m0, s67
	s_nop 0
	global_load_lds_dwordx4 v227, s[98:99]
	s_mov_b32 m0, s71
	s_nop 0
	global_load_lds_dwordx4 v228, s[100:101]
	s_mov_b32 m0, s76
	s_nop 0
	global_load_lds_dwordx4 v229, s[100:101]
	s_waitcnt vmcnt(8)
	s_waitcnt lgkmcnt(0)
	s_barrier
	v_mfma_f32_16x16x32_bf16 v[26:29], v[154:157], v[138:141], v[26:29]
	v_mfma_f32_16x16x32_bf16 v[38:41], v[154:157], v[146:149], v[38:41]
	v_mfma_f32_16x16x32_bf16 v[50:53], v[178:181], v[138:141], v[50:53]
	v_mfma_f32_16x16x32_bf16 v[62:65], v[178:181], v[146:149], v[62:65]
	v_mfma_f32_16x16x32_bf16 v[74:77], v[186:189], v[138:141], v[74:77]
	v_mfma_f32_16x16x32_bf16 v[82:85], v[186:189], v[146:149], v[82:85]
	v_mfma_f32_16x16x32_bf16 v[90:93], v[194:197], v[138:141], v[90:93]
	v_mfma_f32_16x16x32_bf16 v[94:97], v[194:197], v[146:149], v[94:97]
	v_mfma_f32_16x16x32_bf16 v[26:29], v[158:161], v[142:145], v[26:29]
	v_mfma_f32_16x16x32_bf16 v[38:41], v[158:161], v[150:153], v[38:41]
	v_mfma_f32_16x16x32_bf16 v[50:53], v[182:185], v[142:145], v[50:53]
	v_mfma_f32_16x16x32_bf16 v[62:65], v[182:185], v[150:153], v[62:65]
	v_mfma_f32_16x16x32_bf16 v[74:77], v[190:193], v[142:145], v[74:77]
	v_mfma_f32_16x16x32_bf16 v[82:85], v[190:193], v[150:153], v[82:85]
	v_mfma_f32_16x16x32_bf16 v[90:93], v[198:201], v[142:145], v[90:93]
	v_mfma_f32_16x16x32_bf16 v[94:97], v[198:201], v[150:153], v[94:97]
	v_mfma_f32_16x16x32_bf16 v[98:101], v[154:157], v[208:211], v[98:101]
	v_mfma_f32_16x16x32_bf16 v[102:105], v[154:157], v[216:219], v[102:105]
	v_mfma_f32_16x16x32_bf16 v[106:109], v[178:181], v[208:211], v[106:109]
	v_mfma_f32_16x16x32_bf16 v[110:113], v[178:181], v[216:219], v[110:113]
	v_mfma_f32_16x16x32_bf16 v[114:117], v[186:189], v[208:211], v[114:117]
	v_mfma_f32_16x16x32_bf16 v[118:121], v[186:189], v[216:219], v[118:121]
	v_mfma_f32_16x16x32_bf16 v[122:125], v[194:197], v[208:211], v[122:125]
	v_mfma_f32_16x16x32_bf16 v[126:129], v[194:197], v[216:219], v[126:129]
	v_mfma_f32_16x16x32_bf16 v[98:101], v[158:161], v[212:215], v[98:101]
	v_mfma_f32_16x16x32_bf16 v[102:105], v[158:161], v[220:223], v[102:105]
	v_mfma_f32_16x16x32_bf16 v[106:109], v[182:185], v[212:215], v[106:109]
	v_mfma_f32_16x16x32_bf16 v[110:113], v[182:185], v[220:223], v[110:113]
	v_mfma_f32_16x16x32_bf16 v[114:117], v[190:193], v[212:215], v[114:117]
	v_mfma_f32_16x16x32_bf16 v[118:121], v[190:193], v[220:223], v[118:121]
	v_mfma_f32_16x16x32_bf16 v[122:125], v[198:201], v[212:215], v[122:125]
	v_mfma_f32_16x16x32_bf16 v[126:129], v[198:201], v[220:223], v[126:129]
	s_barrier
; #define LDA(dst, b, h)                                                                                     \
;   _Pragma("unroll") for (int m = 0; m < 4; ++m) _Pragma("unroll") for (int k = 0; k < 2; ++k) dst[m][k] = \
;       *reinterpret_cast<const bf16x8*>(shmc + aL + (((b) * 2 + (h)) * 16384 + (m * 2 + k) * 1024))
; #define LDB(dst, b, h)                                                                                     \
;   _Pragma("unroll") for (int n = 0; n < 2; ++n) _Pragma("unroll") for (int k = 0; k < 2; ++k) dst[n][k] = \
;       *reinterpret_cast<const bf16x8*>(shmc + bL + (((b) * 2 + (h)) * 16384 + (n * 2 + k) * 1024))
; #define WAIT_V(n) asm volatile("s_waitcnt vmcnt(" #n ")" ::: "memory")
; #define WAIT_L(n) asm volatile("s_waitcnt lgkmcnt(" #n ")" ::: "memory")
; #define BAR __builtin_amdgcn_s_barrier()
; #define SCHED __builtin_amdgcn_sched_barrier(0)
; template <int EPI>
; __device__ __forceinline__ void phase_gemm(const Params& p, const GemmDesc& d, char* shmc) {
;     ...
;       LDB(B0, 1, 0); SCHED; LDA(At, 1, 0); STAGE_A(SA(0, 1), 1, t + 2);
;       WAIT_L(8); BAR; WAIT_L(0); MMA(0, 0, At, B0); BAR; SCHED;
;       LDB(B1, 1, 1); STAGE_B(SB(1, 0), 0, t + 3);
;       BAR; WAIT_L(0); MMA(0, 1, At, B1); BAR;
;       LDA(At, 1, 1); STAGE_A(SA(1, 0), 0, t + 3);
;       BAR; WAIT_L(0); MMA(1, 0, At, B0); BAR; SCHED;
;       STAGE_B(SB(1, 1), 1, t + 3);
;       WAIT_V(6); BAR; MMA(1, 1, At, B1); BAR;
	ds_read_b128 v[138:141], v162 offset:32768
	ds_read_b128 v[142:145], v162 offset:33792
	ds_read_b128 v[146:149], v162 offset:34816
	ds_read_b128 v[150:153], v162 offset:35840
	ds_read_b128 v[208:211], v162 offset:49152
	ds_read_b128 v[212:215], v162 offset:50176
	ds_read_b128 v[216:219], v162 offset:51200
	ds_read_b128 v[220:223], v162 offset:52224
	ds_read_b128 v[154:157], v175 offset:32768
	ds_read_b128 v[158:161], v175 offset:33792
	ds_read_b128 v[178:181], v175 offset:34816
	ds_read_b128 v[182:185], v175 offset:35840
	ds_read_b128 v[186:189], v175 offset:36864
	ds_read_b128 v[190:193], v175 offset:37888
	ds_read_b128 v[194:197], v175 offset:38912
	ds_read_b128 v[198:201], v175 offset:39936
	s_mov_b32 m0, s77
	s_nop 0
	global_load_lds_dwordx4 v230, s[98:99]
	s_mov_b32 m0, s78
	s_nop 0
	global_load_lds_dwordx4 v231, s[98:99]
	s_waitcnt vmcnt(8)
	s_waitcnt lgkmcnt(0)
	s_barrier
	v_mfma_f32_16x16x32_bf16 v[2:5], v[154:157], v[138:141], v[2:5]
	v_mfma_f32_16x16x32_bf16 v[6:9], v[154:157], v[146:149], v[6:9]
	v_mfma_f32_16x16x32_bf16 v[10:13], v[178:181], v[138:141], v[10:13]
	v_mfma_f32_16x16x32_bf16 v[18:21], v[178:181], v[146:149], v[18:21]
	v_mfma_f32_16x16x32_bf16 v[30:33], v[186:189], v[138:141], v[30:33]
	v_mfma_f32_16x16x32_bf16 v[42:45], v[186:189], v[146:149], v[42:45]
	v_mfma_f32_16x16x32_bf16 v[54:57], v[194:197], v[138:141], v[54:57]
	v_mfma_f32_16x16x32_bf16 v[66:69], v[194:197], v[146:149], v[66:69]
	v_mfma_f32_16x16x32_bf16 v[2:5], v[158:161], v[142:145], v[2:5]
	v_mfma_f32_16x16x32_bf16 v[6:9], v[158:161], v[150:153], v[6:9]
	v_mfma_f32_16x16x32_bf16 v[10:13], v[182:185], v[142:145], v[10:13]
	v_mfma_f32_16x16x32_bf16 v[18:21], v[182:185], v[150:153], v[18:21]
	v_mfma_f32_16x16x32_bf16 v[30:33], v[190:193], v[142:145], v[30:33]
	v_mfma_f32_16x16x32_bf16 v[42:45], v[190:193], v[150:153], v[42:45]
	v_mfma_f32_16x16x32_bf16 v[54:57], v[198:201], v[142:145], v[54:57]
	v_mfma_f32_16x16x32_bf16 v[66:69], v[198:201], v[150:153], v[66:69]
	v_mfma_f32_16x16x32_bf16 v[14:17], v[154:157], v[208:211], v[14:17]
	v_mfma_f32_16x16x32_bf16 v[22:25], v[154:157], v[216:219], v[22:25]
	v_mfma_f32_16x16x32_bf16 v[34:37], v[178:181], v[208:211], v[34:37]
	v_mfma_f32_16x16x32_bf16 v[46:49], v[178:181], v[216:219], v[46:49]
	v_mfma_f32_16x16x32_bf16 v[58:61], v[186:189], v[208:211], v[58:61]
	v_mfma_f32_16x16x32_bf16 v[70:73], v[186:189], v[216:219], v[70:73]
	v_mfma_f32_16x16x32_bf16 v[78:81], v[194:197], v[208:211], v[78:81]
	v_mfma_f32_16x16x32_bf16 v[86:89], v[194:197], v[216:219], v[86:89]
	v_mfma_f32_16x16x32_bf16 v[14:17], v[158:161], v[212:215], v[14:17]
	v_mfma_f32_16x16x32_bf16 v[22:25], v[158:161], v[220:223], v[22:25]
	v_mfma_f32_16x16x32_bf16 v[34:37], v[182:185], v[212:215], v[34:37]
	v_mfma_f32_16x16x32_bf16 v[46:49], v[182:185], v[220:223], v[46:49]
	v_mfma_f32_16x16x32_bf16 v[58:61], v[190:193], v[212:215], v[58:61]
	v_mfma_f32_16x16x32_bf16 v[70:73], v[190:193], v[220:223], v[70:73]
	v_mfma_f32_16x16x32_bf16 v[78:81], v[198:201], v[212:215], v[78:81]
	v_mfma_f32_16x16x32_bf16 v[86:89], v[198:201], v[220:223], v[86:89]
	s_barrier
	ds_read_b128 v[154:157], v175 offset:49152
	ds_read_b128 v[158:161], v175 offset:50176
	ds_read_b128 v[178:181], v175 offset:51200
	ds_read_b128 v[182:185], v175 offset:52224
	ds_read_b128 v[186:189], v175 offset:53248
	ds_read_b128 v[190:193], v175 offset:54272
	ds_read_b128 v[194:197], v175 offset:55296
	ds_read_b128 v[198:201], v175 offset:56320
	s_mov_b32 m0, s35
	s_nop 0
	global_load_lds_dwordx4 v232, s[100:101]
	s_mov_b32 m0, s53
	s_nop 0
	global_load_lds_dwordx4 v233, s[100:101]
	s_mov_b32 m0, s56
	s_nop 0
	global_load_lds_dwordx4 v234, s[98:99]
	s_mov_b32 m0, s57
	s_nop 0
	global_load_lds_dwordx4 v235, s[98:99]
	s_mov_b32 m0, s54
	s_nop 0
	global_load_lds_dwordx4 v236, s[100:101]
	s_mov_b32 m0, s55
	s_nop 0
	global_load_lds_dwordx4 v237, s[100:101]
	s_add_i32 s58, s58, 2
	s_add_u32 s10, s10, 0x100
	s_addc_u32 s11, s11, 0
	s_add_u32 s98, s98, 0x100
	s_addc_u32 s99, s99, 0
	s_add_u32 s100, s100, 0x100
	s_addc_u32 s101, s101, 0
	s_cmp_gt_u32 s58, 27
	s_waitcnt vmcnt(8)
	s_waitcnt lgkmcnt(0)
	s_barrier
	v_mfma_f32_16x16x32_bf16 v[26:29], v[154:157], v[138:141], v[26:29]
	v_mfma_f32_16x16x32_bf16 v[38:41], v[154:157], v[146:149], v[38:41]
	v_mfma_f32_16x16x32_bf16 v[50:53], v[178:181], v[138:141], v[50:53]
	v_mfma_f32_16x16x32_bf16 v[62:65], v[178:181], v[146:149], v[62:65]
	v_mfma_f32_16x16x32_bf16 v[74:77], v[186:189], v[138:141], v[74:77]
	v_mfma_f32_16x16x32_bf16 v[82:85], v[186:189], v[146:149], v[82:85]
	v_mfma_f32_16x16x32_bf16 v[90:93], v[194:197], v[138:141], v[90:93]
	v_mfma_f32_16x16x32_bf16 v[94:97], v[194:197], v[146:149], v[94:97]
	v_mfma_f32_16x16x32_bf16 v[26:29], v[158:161], v[142:145], v[26:29]
	v_mfma_f32_16x16x32_bf16 v[38:41], v[158:161], v[150:153], v[38:41]
	v_mfma_f32_16x16x32_bf16 v[50:53], v[182:185], v[142:145], v[50:53]
	v_mfma_f32_16x16x32_bf16 v[62:65], v[182:185], v[150:153], v[62:65]
	v_mfma_f32_16x16x32_bf16 v[74:77], v[190:193], v[142:145], v[74:77]
	v_mfma_f32_16x16x32_bf16 v[82:85], v[190:193], v[150:153], v[82:85]
	v_mfma_f32_16x16x32_bf16 v[90:93], v[198:201], v[142:145], v[90:93]
	v_mfma_f32_16x16x32_bf16 v[94:97], v[198:201], v[150:153], v[94:97]
	v_mfma_f32_16x16x32_bf16 v[98:101], v[154:157], v[208:211], v[98:101]
	v_mfma_f32_16x16x32_bf16 v[102:105], v[154:157], v[216:219], v[102:105]
	v_mfma_f32_16x16x32_bf16 v[106:109], v[178:181], v[208:211], v[106:109]
	v_mfma_f32_16x16x32_bf16 v[110:113], v[178:181], v[216:219], v[110:113]
	v_mfma_f32_16x16x32_bf16 v[114:117], v[186:189], v[208:211], v[114:117]
	v_mfma_f32_16x16x32_bf16 v[118:121], v[186:189], v[216:219], v[118:121]
	v_mfma_f32_16x16x32_bf16 v[122:125], v[194:197], v[208:211], v[122:125]
	v_mfma_f32_16x16x32_bf16 v[126:129], v[194:197], v[216:219], v[126:129]
	v_mfma_f32_16x16x32_bf16 v[98:101], v[158:161], v[212:215], v[98:101]
	v_mfma_f32_16x16x32_bf16 v[102:105], v[158:161], v[220:223], v[102:105]
	v_mfma_f32_16x16x32_bf16 v[106:109], v[182:185], v[212:215], v[106:109]
	v_mfma_f32_16x16x32_bf16 v[110:113], v[182:185], v[220:223], v[110:113]
	v_mfma_f32_16x16x32_bf16 v[114:117], v[190:193], v[212:215], v[114:117]
	v_mfma_f32_16x16x32_bf16 v[118:121], v[190:193], v[220:223], v[118:121]
	v_mfma_f32_16x16x32_bf16 v[122:125], v[198:201], v[212:215], v[122:125]
	v_mfma_f32_16x16x32_bf16 v[126:129], v[198:201], v[220:223], v[126:129]
	s_barrier
; #define LDA(dst, b, h)                                                                                     \
;   _Pragma("unroll") for (int m = 0; m < 4; ++m) _Pragma("unroll") for (int k = 0; k < 2; ++k) dst[m][k] = \
;       *reinterpret_cast<const bf16x8*>(shmc + aL + (((b) * 2 + (h)) * 16384 + (m * 2 + k) * 1024))
; #define LDB(dst, b, h)                                                                                     \
;   _Pragma("unroll") for (int n = 0; n < 2; ++n) _Pragma("unroll") for (int k = 0; k < 2; ++k) dst[n][k] = \
;       *reinterpret_cast<const bf16x8*>(shmc + bL + (((b) * 2 + (h)) * 16384 + (n * 2 + k) * 1024))
; #define OPAQ asm volatile("" : "+v"(aL), "+v"(bL))
; #define WAIT_V(n) asm volatile("s_waitcnt vmcnt(" #n ")" ::: "memory")
; #define WAIT_L(n) asm volatile("s_waitcnt lgkmcnt(" #n ")" ::: "memory")
; #define BAR __builtin_amdgcn_s_barrier()
; template <int EPI>
; __device__ __forceinline__ void phase_gemm(const Params& p, const GemmDesc& d, char* shmc) {
;     ...
;     {
;       OPAQ;
;       LDB(B0, 0, 0); LDA(At, 0, 0); STAGE_A(SA(1, 1), 1, nt - 1);
;       BAR; WAIT_L(0); MMA(0, 0, At, B0); BAR;
;       LDB(B1, 0, 1); BAR; WAIT_L(0); MMA(0, 1, At, B1); BAR;
;       LDA(At, 0, 1); WAIT_V(4); BAR; WAIT_L(0); MMA(1, 0, At, B0); MMA(1, 1, At, B1); BAR;
;     }
	s_cbranch_scc0 .LBB0_1153
	s_setprio 0
	s_add_u32 s8, s8, 0x80f80
	s_addc_u32 s9, s9, 0
	v_add_u32_e32 v162, 0, v205
	v_add_u32_e32 v175, 0, v204
	s_mov_b32 m0, s59
	ds_read_b128 v[130:133], v162
	ds_read_b128 v[134:137], v162 offset:1024
	ds_read_b128 v[138:141], v162 offset:2048
	ds_read_b128 v[142:145], v162 offset:3072
	ds_read_b128 v[146:149], v175
	ds_read_b128 v[150:153], v175 offset:1024
	ds_read_b128 v[154:157], v175 offset:2048
	ds_read_b128 v[158:161], v175 offset:3072
	ds_read_b128 v[178:181], v175 offset:4096
	ds_read_b128 v[182:185], v175 offset:5120
	ds_read_b128 v[186:189], v175 offset:6144
	ds_read_b128 v[190:193], v175 offset:7168
	global_load_lds_dwordx4 v174, s[8:9]
	s_mov_b32 m0, s68
	s_nop 0
	global_load_lds_dwordx4 v176, s[8:9]
	s_waitcnt vmcnt(8)
	s_barrier
	s_waitcnt lgkmcnt(0)
	s_setprio 1
	s_waitcnt lgkmcnt(0)
	v_mfma_f32_16x16x32_bf16 v[2:5], v[146:149], v[130:133], v[2:5]
	v_mfma_f32_16x16x32_bf16 v[6:9], v[146:149], v[138:141], v[6:9]
	v_mfma_f32_16x16x32_bf16 v[10:13], v[154:157], v[130:133], v[10:13]
	v_mfma_f32_16x16x32_bf16 v[18:21], v[154:157], v[138:141], v[18:21]
	v_mfma_f32_16x16x32_bf16 v[66:69], v[186:189], v[138:141], v[66:69]
	v_mfma_f32_16x16x32_bf16 v[2:5], v[150:153], v[134:137], v[2:5]
	v_mfma_f32_16x16x32_bf16 v[6:9], v[150:153], v[142:145], v[6:9]
	v_mfma_f32_16x16x32_bf16 v[10:13], v[158:161], v[134:137], v[10:13]
	v_mfma_f32_16x16x32_bf16 v[18:21], v[158:161], v[142:145], v[18:21]
	v_mfma_f32_16x16x32_bf16 v[30:33], v[178:181], v[130:133], v[30:33]
	v_mfma_f32_16x16x32_bf16 v[42:45], v[178:181], v[138:141], v[42:45]
	v_mfma_f32_16x16x32_bf16 v[54:57], v[186:189], v[130:133], v[54:57]
	v_mfma_f32_16x16x32_bf16 v[66:69], v[190:193], v[142:145], v[66:69]
	v_mfma_f32_16x16x32_bf16 v[30:33], v[182:185], v[134:137], v[30:33]
	v_mfma_f32_16x16x32_bf16 v[42:45], v[182:185], v[142:145], v[42:45]
	v_mfma_f32_16x16x32_bf16 v[54:57], v[190:193], v[134:137], v[54:57]
	s_setprio 0
	s_barrier
	ds_read_b128 v[194:197], v162 offset:16384
	ds_read_b128 v[198:201], v162 offset:17408
	ds_read_b128 v[208:211], v162 offset:18432
	ds_read_b128 v[212:215], v162 offset:19456
	s_barrier
	s_waitcnt lgkmcnt(0)
	s_setprio 1
	s_waitcnt lgkmcnt(0)
	v_mfma_f32_16x16x32_bf16 v[14:17], v[146:149], v[194:197], v[14:17]
	v_mfma_f32_16x16x32_bf16 v[22:25], v[146:149], v[208:211], v[22:25]
	v_mfma_f32_16x16x32_bf16 v[58:61], v[178:181], v[194:197], v[58:61]
	v_mfma_f32_16x16x32_bf16 v[14:17], v[150:153], v[198:201], v[14:17]
	v_mfma_f32_16x16x32_bf16 v[22:25], v[150:153], v[212:215], v[22:25]
	v_mfma_f32_16x16x32_bf16 v[150:153], v[182:185], v[198:201], v[58:61]
	v_mfma_f32_16x16x32_bf16 v[58:61], v[178:181], v[208:211], v[70:73]
	v_mfma_f32_16x16x32_bf16 v[34:37], v[154:157], v[194:197], v[34:37]
	v_mfma_f32_16x16x32_bf16 v[46:49], v[154:157], v[208:211], v[46:49]
	v_mfma_f32_16x16x32_bf16 v[154:157], v[182:185], v[212:215], v[58:61]
	v_mfma_f32_16x16x32_bf16 v[58:61], v[186:189], v[194:197], v[78:81]
	v_mfma_f32_16x16x32_bf16 v[78:81], v[190:193], v[198:201], v[58:61]
	v_mfma_f32_16x16x32_bf16 v[58:61], v[186:189], v[208:211], v[86:89]
	v_mfma_f32_16x16x32_bf16 v[86:89], v[190:193], v[212:215], v[58:61]
	v_mfma_f32_16x16x32_bf16 v[34:37], v[158:161], v[198:201], v[34:37]
	v_mfma_f32_16x16x32_bf16 v[46:49], v[158:161], v[212:215], v[46:49]
	s_setprio 0
	s_barrier
	s_nop 2
	ds_read_b128 v[58:61], v175 offset:16384
	ds_read_b128 v[70:73], v175 offset:17408
	ds_read_b128 v[146:149], v175 offset:18432
	ds_read_b128 v[158:161], v175 offset:19456
	ds_read_b128 v[178:181], v175 offset:20480
	ds_read_b128 v[182:185], v175 offset:21504
	ds_read_b128 v[186:189], v175 offset:22528
	ds_read_b128 v[190:193], v175 offset:23552
	s_waitcnt vmcnt(4)
	s_barrier
	s_waitcnt lgkmcnt(0)
	s_setprio 1
	s_waitcnt lgkmcnt(0)
	v_mfma_f32_16x16x32_bf16 v[74:77], v[178:181], v[130:133], v[74:77]
	v_mfma_f32_16x16x32_bf16 v[216:219], v[182:185], v[134:137], v[74:77]
	v_mfma_f32_16x16x32_bf16 v[74:77], v[178:181], v[138:141], v[82:85]
	v_mfma_f32_16x16x32_bf16 v[26:29], v[58:61], v[130:133], v[26:29]
	v_mfma_f32_16x16x32_bf16 v[82:85], v[182:185], v[142:145], v[74:77]
	v_mfma_f32_16x16x32_bf16 v[74:77], v[186:189], v[130:133], v[90:93]
	v_mfma_f32_16x16x32_bf16 v[26:29], v[70:73], v[134:137], v[26:29]
	v_mfma_f32_16x16x32_bf16 v[38:41], v[58:61], v[138:141], v[38:41]
	v_mfma_f32_16x16x32_bf16 v[50:53], v[146:149], v[130:133], v[50:53]
	v_mfma_f32_16x16x32_bf16 v[62:65], v[146:149], v[138:141], v[62:65]
	v_mfma_f32_16x16x32_bf16 v[90:93], v[190:193], v[134:137], v[74:77]
	v_mfma_f32_16x16x32_bf16 v[74:77], v[186:189], v[138:141], v[94:97]
	v_mfma_f32_16x16x32_bf16 v[38:41], v[70:73], v[142:145], v[38:41]
	v_mfma_f32_16x16x32_bf16 v[50:53], v[158:161], v[134:137], v[50:53]
	v_mfma_f32_16x16x32_bf16 v[62:65], v[158:161], v[142:145], v[62:65]
	v_mfma_f32_16x16x32_bf16 v[220:223], v[190:193], v[142:145], v[74:77]
	s_setprio 0
	s_setprio 1
	v_mfma_f32_16x16x32_bf16 v[74:77], v[58:61], v[194:197], v[98:101]
	v_mfma_f32_16x16x32_bf16 v[58:61], v[58:61], v[208:211], v[102:105]
	v_mfma_f32_16x16x32_bf16 v[228:231], v[70:73], v[212:215], v[58:61]
	v_mfma_f32_16x16x32_bf16 v[58:61], v[146:149], v[194:197], v[106:109]
	v_mfma_f32_16x16x32_bf16 v[232:235], v[158:161], v[198:201], v[58:61]
	v_mfma_f32_16x16x32_bf16 v[58:61], v[146:149], v[208:211], v[110:113]
	v_mfma_f32_16x16x32_bf16 v[236:239], v[158:161], v[212:215], v[58:61]
	v_mfma_f32_16x16x32_bf16 v[58:61], v[178:181], v[194:197], v[114:117]
	v_mfma_f32_16x16x32_bf16 v[240:243], v[182:185], v[198:201], v[58:61]
	v_mfma_f32_16x16x32_bf16 v[58:61], v[178:181], v[208:211], v[118:121]
	v_mfma_f32_16x16x32_bf16 v[178:181], v[182:185], v[212:215], v[58:61]
	v_mfma_f32_16x16x32_bf16 v[58:61], v[186:189], v[194:197], v[122:125]
	v_mfma_f32_16x16x32_bf16 v[182:185], v[190:193], v[198:201], v[58:61]
	v_mfma_f32_16x16x32_bf16 v[58:61], v[186:189], v[208:211], v[126:129]
	v_mfma_f32_16x16x32_bf16 v[224:227], v[70:73], v[198:201], v[74:77]
	v_mfma_f32_16x16x32_bf16 v[186:189], v[190:193], v[212:215], v[58:61]
	s_setprio 0
	s_barrier
; #define LDA(dst, b, h)                                                                                     \
;   _Pragma("unroll") for (int m = 0; m < 4; ++m) _Pragma("unroll") for (int k = 0; k < 2; ++k) dst[m][k] = \
;       *reinterpret_cast<const bf16x8*>(shmc + aL + (((b) * 2 + (h)) * 16384 + (m * 2 + k) * 1024))
; #define LDB(dst, b, h)                                                                                     \
;   _Pragma("unroll") for (int n = 0; n < 2; ++n) _Pragma("unroll") for (int k = 0; k < 2; ++k) dst[n][k] = \
;       *reinterpret_cast<const bf16x8*>(shmc + bL + (((b) * 2 + (h)) * 16384 + (n * 2 + k) * 1024))
; #define WAIT_V(n) asm volatile("s_waitcnt vmcnt(" #n ")" ::: "memory")
; #define WAIT_L(n) asm volatile("s_waitcnt lgkmcnt(" #n ")" ::: "memory")
; #define BAR __builtin_amdgcn_s_barrier()
; template <int EPI>
; __device__ __forceinline__ void phase_gemm(const Params& p, const GemmDesc& d, char* shmc) {
;     ...
;     {
;       LDB(B0, 1, 0); LDA(At, 1, 0); WAIT_V(2); BAR; WAIT_L(0); MMA(0, 0, At, B0); BAR;
;       LDB(B1, 1, 1); WAIT_V(0); BAR; WAIT_L(0); MMA(0, 1, At, B1); BAR;
;       LDA(At, 1, 1); BAR; WAIT_L(0); MMA(1, 0, At, B0); MMA(1, 1, At, B1); BAR;
;     }
;     if (wr == 0) BAR;
	ds_read_b128 v[98:101], v162 offset:32768
	ds_read_b128 v[106:109], v162 offset:33792
	ds_read_b128 v[190:193], v162 offset:34816
	ds_read_b128 v[194:197], v162 offset:35840
	ds_read_b128 v[58:61], v175 offset:32768
	ds_read_b128 v[70:73], v175 offset:33792
	ds_read_b128 v[114:117], v175 offset:34816
	ds_read_b128 v[122:125], v175 offset:35840
	ds_read_b128 v[130:133], v175 offset:36864
	ds_read_b128 v[138:141], v175 offset:37888
	ds_read_b128 v[198:201], v175 offset:38912
	ds_read_b128 v[208:211], v175 offset:39936
	s_waitcnt vmcnt(2)
	s_barrier
	s_waitcnt lgkmcnt(0)
	s_setprio 1
	s_waitcnt lgkmcnt(0)
	v_mfma_f32_16x16x32_bf16 v[2:5], v[58:61], v[98:101], v[2:5]
	v_mfma_f32_16x16x32_bf16 v[158:161], v[70:73], v[106:109], v[2:5]
	v_mfma_f32_16x16x32_bf16 v[2:5], v[58:61], v[190:193], v[6:9]
	v_mfma_f32_16x16x32_bf16 v[146:149], v[70:73], v[194:197], v[2:5]
	v_mfma_f32_16x16x32_bf16 v[2:5], v[114:117], v[98:101], v[10:13]
	v_mfma_f32_16x16x32_bf16 v[142:145], v[122:125], v[106:109], v[2:5]
	v_mfma_f32_16x16x32_bf16 v[2:5], v[114:117], v[190:193], v[18:21]
	v_mfma_f32_16x16x32_bf16 v[134:137], v[122:125], v[194:197], v[2:5]
	v_mfma_f32_16x16x32_bf16 v[2:5], v[130:133], v[98:101], v[30:33]
	v_mfma_f32_16x16x32_bf16 v[126:129], v[138:141], v[106:109], v[2:5]
	v_mfma_f32_16x16x32_bf16 v[2:5], v[130:133], v[190:193], v[42:45]
	v_mfma_f32_16x16x32_bf16 v[118:121], v[138:141], v[194:197], v[2:5]
	v_mfma_f32_16x16x32_bf16 v[2:5], v[198:201], v[98:101], v[54:57]
	v_mfma_f32_16x16x32_bf16 v[110:113], v[208:211], v[106:109], v[2:5]
	v_mfma_f32_16x16x32_bf16 v[2:5], v[198:201], v[190:193], v[66:69]
	v_mfma_f32_16x16x32_bf16 v[102:105], v[208:211], v[194:197], v[2:5]
	s_setprio 0
	s_barrier
	ds_read_b128 v[30:33], v162 offset:49152
	ds_read_b128 v[42:45], v162 offset:50176
	ds_read_b128 v[54:57], v162 offset:51200
	ds_read_b128 v[212:215], v162 offset:52224
	s_waitcnt vmcnt(0)
	s_barrier
	s_waitcnt lgkmcnt(0)
	s_setprio 1
	s_waitcnt lgkmcnt(0)
	v_mfma_f32_16x16x32_bf16 v[2:5], v[58:61], v[30:33], v[14:17]
	v_mfma_f32_16x16x32_bf16 v[94:97], v[70:73], v[42:45], v[2:5]
	v_mfma_f32_16x16x32_bf16 v[2:5], v[58:61], v[54:57], v[22:25]
	v_mfma_f32_16x16x32_bf16 v[58:61], v[70:73], v[212:215], v[2:5]
	v_mfma_f32_16x16x32_bf16 v[2:5], v[114:117], v[30:33], v[34:37]
	v_mfma_f32_16x16x32_bf16 v[74:77], v[122:125], v[42:45], v[2:5]
	v_mfma_f32_16x16x32_bf16 v[2:5], v[114:117], v[54:57], v[46:49]
	v_mfma_f32_16x16x32_bf16 v[10:13], v[122:125], v[212:215], v[2:5]
	v_mfma_f32_16x16x32_bf16 v[2:5], v[130:133], v[30:33], v[150:153]
	v_mfma_f32_16x16x32_bf16 v[70:73], v[138:141], v[42:45], v[2:5]
	v_mfma_f32_16x16x32_bf16 v[2:5], v[130:133], v[54:57], v[154:157]
	v_mfma_f32_16x16x32_bf16 v[6:9], v[138:141], v[212:215], v[2:5]
	v_mfma_f32_16x16x32_bf16 v[2:5], v[198:201], v[30:33], v[78:81]
	v_mfma_f32_16x16x32_bf16 v[66:69], v[208:211], v[42:45], v[2:5]
	v_mfma_f32_16x16x32_bf16 v[2:5], v[198:201], v[54:57], v[86:89]
	v_mfma_f32_16x16x32_bf16 v[2:5], v[208:211], v[212:215], v[2:5]
	s_setprio 0
	s_barrier
	ds_read_b128 v[14:17], v175 offset:49152
	ds_read_b128 v[18:21], v175 offset:50176
	ds_read_b128 v[22:25], v175 offset:51200
	ds_read_b128 v[34:37], v175 offset:52224
	ds_read_b128 v[46:49], v175 offset:53248
	ds_read_b128 v[78:81], v175 offset:54272
	ds_read_b128 v[198:201], v175 offset:55296
	ds_read_b128 v[208:211], v175 offset:56320
	s_barrier
	s_waitcnt lgkmcnt(0)
	s_setprio 1
	s_waitcnt lgkmcnt(0)
	v_mfma_f32_16x16x32_bf16 v[26:29], v[14:17], v[98:101], v[26:29]
	v_mfma_f32_16x16x32_bf16 v[154:157], v[18:21], v[106:109], v[26:29]
	v_mfma_f32_16x16x32_bf16 v[26:29], v[14:17], v[190:193], v[38:41]
	v_mfma_f32_16x16x32_bf16 v[150:153], v[18:21], v[194:197], v[26:29]
	v_mfma_f32_16x16x32_bf16 v[26:29], v[22:25], v[98:101], v[50:53]
	v_mfma_f32_16x16x32_bf16 v[138:141], v[34:37], v[106:109], v[26:29]
	v_mfma_f32_16x16x32_bf16 v[26:29], v[22:25], v[190:193], v[62:65]
	v_mfma_f32_16x16x32_bf16 v[130:133], v[34:37], v[194:197], v[26:29]
	v_mfma_f32_16x16x32_bf16 v[26:29], v[46:49], v[98:101], v[216:219]
	v_mfma_f32_16x16x32_bf16 v[122:125], v[78:81], v[106:109], v[26:29]
	v_mfma_f32_16x16x32_bf16 v[26:29], v[46:49], v[190:193], v[82:85]
	v_mfma_f32_16x16x32_bf16 v[114:117], v[78:81], v[194:197], v[26:29]
	v_mfma_f32_16x16x32_bf16 v[26:29], v[198:201], v[98:101], v[90:93]
	v_mfma_f32_16x16x32_bf16 v[106:109], v[208:211], v[106:109], v[26:29]
	v_mfma_f32_16x16x32_bf16 v[26:29], v[198:201], v[190:193], v[220:223]
	v_mfma_f32_16x16x32_bf16 v[98:101], v[208:211], v[194:197], v[26:29]
	s_setprio 0
	s_setprio 1
	v_mfma_f32_16x16x32_bf16 v[26:29], v[14:17], v[30:33], v[224:227]
	v_mfma_f32_16x16x32_bf16 v[14:17], v[14:17], v[54:57], v[228:231]
	v_mfma_f32_16x16x32_bf16 v[90:93], v[18:21], v[42:45], v[26:29]
	v_mfma_f32_16x16x32_bf16 v[26:29], v[18:21], v[212:215], v[14:17]
	v_mfma_f32_16x16x32_bf16 v[14:17], v[22:25], v[30:33], v[232:235]
	v_mfma_f32_16x16x32_bf16 v[86:89], v[34:37], v[42:45], v[14:17]
	v_mfma_f32_16x16x32_bf16 v[14:17], v[22:25], v[54:57], v[236:239]
	v_mfma_f32_16x16x32_bf16 v[22:25], v[34:37], v[212:215], v[14:17]
	v_mfma_f32_16x16x32_bf16 v[14:17], v[46:49], v[30:33], v[240:243]
	v_mfma_f32_16x16x32_bf16 v[82:85], v[78:81], v[42:45], v[14:17]
	v_mfma_f32_16x16x32_bf16 v[14:17], v[46:49], v[54:57], v[178:181]
	v_mfma_f32_16x16x32_bf16 v[18:21], v[78:81], v[212:215], v[14:17]
	v_mfma_f32_16x16x32_bf16 v[14:17], v[198:201], v[30:33], v[182:185]
	v_mfma_f32_16x16x32_bf16 v[78:81], v[208:211], v[42:45], v[14:17]
	v_mfma_f32_16x16x32_bf16 v[14:17], v[198:201], v[54:57], v[186:189]
	v_mfma_f32_16x16x32_bf16 v[14:17], v[208:211], v[212:215], v[14:17]
	s_setprio 0
	s_barrier
	s_and_saveexec_b64 s[8:9], s[6:7]
	s_cbranch_execz .LBB0_1156
	s_barrier

; #define LDA(dst, b, h)                                                                                     \
;   _Pragma("unroll") for (int m = 0; m < 4; ++m) _Pragma("unroll") for (int k = 0; k < 2; ++k) dst[m][k] = \
;       *reinterpret_cast<const bf16x8*>(shmc + aL + (((b) * 2 + (h)) * 16384 + (m * 2 + k) * 1024))
; #define LDB(dst, b, h)                                                                                     \
;   _Pragma("unroll") for (int n = 0; n < 2; ++n) _Pragma("unroll") for (int k = 0; k < 2; ++k) dst[n][k] = \
;       *reinterpret_cast<const bf16x8*>(shmc + bL + (((b) * 2 + (h)) * 16384 + (n * 2 + k) * 1024))
; #define OPAQ asm volatile("" : "+v"(aL), "+v"(bL))
; #define WAIT_V(n) asm volatile("s_waitcnt vmcnt(" #n ")" ::: "memory")
; #define WAIT_L(n) asm volatile("s_waitcnt lgkmcnt(" #n ")" ::: "memory")
; #define BAR __builtin_amdgcn_s_barrier()
; #define SCHED __builtin_amdgcn_sched_barrier(0)
; template <int EPI>
; __device__ __forceinline__ void phase_gemm(const Params& p, const GemmDesc& d, char* shmc) {
;     ...
;     for (int t = 0; t < nt - 2; t += 2) {
;       OPAQ;
;       LDB(B0, 0, 0); SCHED; LDA(At, 0, 0); STAGE_A(SA(1, 1), 1, t + 1);
;       WAIT_L(8); BAR; WAIT_L(0); MMA(0, 0, At, B0); BAR; SCHED;
;       LDB(B1, 0, 1); STAGE_B(SB(0, 0), 0, t + 2);
;       BAR; WAIT_L(0); MMA(0, 1, At, B1); BAR;
;       LDA(At, 0, 1); STAGE_A(SA(0, 0), 0, t + 2);
;       BAR; WAIT_L(0); MMA(1, 0, At, B0); BAR; SCHED;
;       STAGE_B(SB(0, 1), 1, t + 2);
;       WAIT_V(6); BAR; MMA(1, 1, At, B1); BAR;
.LBB0_1312:
	s_nop 0
	v_add_u32_e32 v130, 0, v153
	v_add_u32_e32 v141, 0, v152
	ds_read_b128 v[156:159], v130
	ds_read_b128 v[160:163], v130 offset:1024
	ds_read_b128 v[164:167], v130 offset:2048
	ds_read_b128 v[168:171], v130 offset:3072
	ds_read_b128 v[204:207], v130 offset:16384
	ds_read_b128 v[208:211], v130 offset:17408
	ds_read_b128 v[212:215], v130 offset:18432
	ds_read_b128 v[216:219], v130 offset:19456
	ds_read_b128 v[172:175], v141
	ds_read_b128 v[176:179], v141 offset:1024
	ds_read_b128 v[180:183], v141 offset:2048
	ds_read_b128 v[184:187], v141 offset:3072
	ds_read_b128 v[188:191], v141 offset:4096
	ds_read_b128 v[192:195], v141 offset:5120
	ds_read_b128 v[196:199], v141 offset:6144
	ds_read_b128 v[200:203], v141 offset:7168
	s_mov_b32 m0, s59
	s_nop 0
	global_load_lds_dwordx4 v220, s[98:99]
	s_mov_b32 m0, s60
	s_nop 0
	global_load_lds_dwordx4 v221, s[98:99]
	s_waitcnt vmcnt(8)
	s_waitcnt lgkmcnt(0)
	s_barrier
	v_mfma_f32_16x16x32_bf16 v[126:129], v[156:159], v[172:175], v[126:129]
	v_mfma_f32_16x16x32_bf16 v[122:125], v[164:167], v[172:175], v[122:125]
	v_mfma_f32_16x16x32_bf16 v[118:121], v[156:159], v[180:183], v[118:121]
	v_mfma_f32_16x16x32_bf16 v[114:117], v[164:167], v[180:183], v[114:117]
	v_mfma_f32_16x16x32_bf16 v[110:113], v[156:159], v[188:191], v[110:113]
	v_mfma_f32_16x16x32_bf16 v[106:109], v[164:167], v[188:191], v[106:109]
	v_mfma_f32_16x16x32_bf16 v[102:105], v[156:159], v[196:199], v[102:105]
	v_mfma_f32_16x16x32_bf16 v[98:101], v[164:167], v[196:199], v[98:101]
	v_mfma_f32_16x16x32_bf16 v[126:129], v[160:163], v[176:179], v[126:129]
	v_mfma_f32_16x16x32_bf16 v[122:125], v[168:171], v[176:179], v[122:125]
	v_mfma_f32_16x16x32_bf16 v[118:121], v[160:163], v[184:187], v[118:121]
	v_mfma_f32_16x16x32_bf16 v[114:117], v[168:171], v[184:187], v[114:117]
	v_mfma_f32_16x16x32_bf16 v[110:113], v[160:163], v[192:195], v[110:113]
	v_mfma_f32_16x16x32_bf16 v[106:109], v[168:171], v[192:195], v[106:109]
	v_mfma_f32_16x16x32_bf16 v[102:105], v[160:163], v[200:203], v[102:105]
	v_mfma_f32_16x16x32_bf16 v[98:101], v[168:171], v[200:203], v[98:101]
	v_mfma_f32_16x16x32_bf16 v[86:89], v[204:207], v[172:175], v[86:89]
	v_mfma_f32_16x16x32_bf16 v[70:73], v[212:215], v[172:175], v[70:73]
	v_mfma_f32_16x16x32_bf16 v[54:57], v[204:207], v[180:183], v[54:57]
	v_mfma_f32_16x16x32_bf16 v[50:53], v[212:215], v[180:183], v[50:53]
	v_mfma_f32_16x16x32_bf16 v[46:49], v[204:207], v[188:191], v[46:49]
	v_mfma_f32_16x16x32_bf16 v[42:45], v[212:215], v[188:191], v[42:45]
	v_mfma_f32_16x16x32_bf16 v[38:41], v[204:207], v[196:199], v[38:41]
	v_mfma_f32_16x16x32_bf16 v[34:37], v[212:215], v[196:199], v[34:37]
	v_mfma_f32_16x16x32_bf16 v[86:89], v[208:211], v[176:179], v[86:89]
	v_mfma_f32_16x16x32_bf16 v[70:73], v[216:219], v[176:179], v[70:73]
	v_mfma_f32_16x16x32_bf16 v[54:57], v[208:211], v[184:187], v[54:57]
	v_mfma_f32_16x16x32_bf16 v[50:53], v[216:219], v[184:187], v[50:53]
	v_mfma_f32_16x16x32_bf16 v[46:49], v[208:211], v[192:195], v[46:49]
	v_mfma_f32_16x16x32_bf16 v[42:45], v[216:219], v[192:195], v[42:45]
	v_mfma_f32_16x16x32_bf16 v[38:41], v[208:211], v[200:203], v[38:41]
	v_mfma_f32_16x16x32_bf16 v[34:37], v[216:219], v[200:203], v[34:37]
	s_barrier
	ds_read_b128 v[172:175], v141 offset:16384
	ds_read_b128 v[176:179], v141 offset:17408
	ds_read_b128 v[180:183], v141 offset:18432
	ds_read_b128 v[184:187], v141 offset:19456
	ds_read_b128 v[188:191], v141 offset:20480
	ds_read_b128 v[192:195], v141 offset:21504
	ds_read_b128 v[196:199], v141 offset:22528
	ds_read_b128 v[200:203], v141 offset:23552
	s_mov_b32 m0, s34
	s_nop 0
	global_load_lds_dwordx4 v222, s[100:101]
	s_mov_b32 m0, s35
	s_nop 0
	global_load_lds_dwordx4 v223, s[100:101]
	s_mov_b32 m0, s33
	s_nop 0
	global_load_lds_dwordx4 v224, s[98:99]
	s_mov_b32 m0, s46
	s_nop 0
	global_load_lds_dwordx4 v225, s[98:99]
	s_mov_b32 m0, s47
	s_nop 0
	global_load_lds_dwordx4 v226, s[100:101]
	s_mov_b32 m0, s48
	s_nop 0
	global_load_lds_dwordx4 v227, s[100:101]
	s_waitcnt vmcnt(8)
	s_waitcnt lgkmcnt(0)
	s_barrier
	v_mfma_f32_16x16x32_bf16 v[30:33], v[156:159], v[172:175], v[30:33]
	v_mfma_f32_16x16x32_bf16 v[26:29], v[164:167], v[172:175], v[26:29]
	v_mfma_f32_16x16x32_bf16 v[22:25], v[156:159], v[180:183], v[22:25]
	v_mfma_f32_16x16x32_bf16 v[18:21], v[164:167], v[180:183], v[18:21]
	v_mfma_f32_16x16x32_bf16 v[14:17], v[156:159], v[188:191], v[14:17]
	v_mfma_f32_16x16x32_bf16 v[10:13], v[164:167], v[188:191], v[10:13]
	v_mfma_f32_16x16x32_bf16 v[6:9], v[156:159], v[196:199], v[6:9]
	v_mfma_f32_16x16x32_bf16 v[2:5], v[164:167], v[196:199], v[2:5]
	v_mfma_f32_16x16x32_bf16 v[30:33], v[160:163], v[176:179], v[30:33]
	v_mfma_f32_16x16x32_bf16 v[26:29], v[168:171], v[176:179], v[26:29]
	v_mfma_f32_16x16x32_bf16 v[22:25], v[160:163], v[184:187], v[22:25]
	v_mfma_f32_16x16x32_bf16 v[18:21], v[168:171], v[184:187], v[18:21]
	v_mfma_f32_16x16x32_bf16 v[14:17], v[160:163], v[192:195], v[14:17]
	v_mfma_f32_16x16x32_bf16 v[10:13], v[168:171], v[192:195], v[10:13]
	v_mfma_f32_16x16x32_bf16 v[6:9], v[160:163], v[200:203], v[6:9]
	v_mfma_f32_16x16x32_bf16 v[2:5], v[168:171], v[200:203], v[2:5]
	v_mfma_f32_16x16x32_bf16 v[58:61], v[204:207], v[172:175], v[58:61]
	v_mfma_f32_16x16x32_bf16 v[62:65], v[212:215], v[172:175], v[62:65]
	v_mfma_f32_16x16x32_bf16 v[66:69], v[204:207], v[180:183], v[66:69]
	v_mfma_f32_16x16x32_bf16 v[74:77], v[212:215], v[180:183], v[74:77]
	v_mfma_f32_16x16x32_bf16 v[78:81], v[204:207], v[188:191], v[78:81]
	v_mfma_f32_16x16x32_bf16 v[82:85], v[212:215], v[188:191], v[82:85]
	v_mfma_f32_16x16x32_bf16 v[90:93], v[204:207], v[196:199], v[90:93]
	v_mfma_f32_16x16x32_bf16 v[94:97], v[212:215], v[196:199], v[94:97]
	v_mfma_f32_16x16x32_bf16 v[58:61], v[208:211], v[176:179], v[58:61]
	v_mfma_f32_16x16x32_bf16 v[62:65], v[216:219], v[176:179], v[62:65]
	v_mfma_f32_16x16x32_bf16 v[66:69], v[208:211], v[184:187], v[66:69]
	v_mfma_f32_16x16x32_bf16 v[74:77], v[216:219], v[184:187], v[74:77]
	v_mfma_f32_16x16x32_bf16 v[78:81], v[208:211], v[192:195], v[78:81]
	v_mfma_f32_16x16x32_bf16 v[82:85], v[216:219], v[192:195], v[82:85]
	v_mfma_f32_16x16x32_bf16 v[90:93], v[208:211], v[200:203], v[90:93]
	v_mfma_f32_16x16x32_bf16 v[94:97], v[216:219], v[200:203], v[94:97]
	s_barrier
; #define LDA(dst, b, h)                                                                                     \
;   _Pragma("unroll") for (int m = 0; m < 4; ++m) _Pragma("unroll") for (int k = 0; k < 2; ++k) dst[m][k] = \
;       *reinterpret_cast<const bf16x8*>(shmc + aL + (((b) * 2 + (h)) * 16384 + (m * 2 + k) * 1024))
; #define LDB(dst, b, h)                                                                                     \
;   _Pragma("unroll") for (int n = 0; n < 2; ++n) _Pragma("unroll") for (int k = 0; k < 2; ++k) dst[n][k] = \
;       *reinterpret_cast<const bf16x8*>(shmc + bL + (((b) * 2 + (h)) * 16384 + (n * 2 + k) * 1024))
; #define WAIT_V(n) asm volatile("s_waitcnt vmcnt(" #n ")" ::: "memory")
; #define WAIT_L(n) asm volatile("s_waitcnt lgkmcnt(" #n ")" ::: "memory")
; #define BAR __builtin_amdgcn_s_barrier()
; #define SCHED __builtin_amdgcn_sched_barrier(0)
; template <int EPI>
; __device__ __forceinline__ void phase_gemm(const Params& p, const GemmDesc& d, char* shmc) {
;     ...
;       LDB(B0, 1, 0); SCHED; LDA(At, 1, 0); STAGE_A(SA(0, 1), 1, t + 2);
;       WAIT_L(8); BAR; WAIT_L(0); MMA(0, 0, At, B0); BAR; SCHED;
;       LDB(B1, 1, 1); STAGE_B(SB(1, 0), 0, t + 3);
;       BAR; WAIT_L(0); MMA(0, 1, At, B1); BAR;
;       LDA(At, 1, 1); STAGE_A(SA(1, 0), 0, t + 3);
;       BAR; WAIT_L(0); MMA(1, 0, At, B0); BAR; SCHED;
;       STAGE_B(SB(1, 1), 1, t + 3);
;       WAIT_V(6); BAR; MMA(1, 1, At, B1); BAR;
	ds_read_b128 v[156:159], v130 offset:32768
	ds_read_b128 v[160:163], v130 offset:33792
	ds_read_b128 v[164:167], v130 offset:34816
	ds_read_b128 v[168:171], v130 offset:35840
	ds_read_b128 v[204:207], v130 offset:49152
	ds_read_b128 v[208:211], v130 offset:50176
	ds_read_b128 v[212:215], v130 offset:51200
	ds_read_b128 v[216:219], v130 offset:52224
	ds_read_b128 v[172:175], v141 offset:32768
	ds_read_b128 v[176:179], v141 offset:33792
	ds_read_b128 v[180:183], v141 offset:34816
	ds_read_b128 v[184:187], v141 offset:35840
	ds_read_b128 v[188:191], v141 offset:36864
	ds_read_b128 v[192:195], v141 offset:37888
	ds_read_b128 v[196:199], v141 offset:38912
	ds_read_b128 v[200:203], v141 offset:39936
	s_mov_b32 m0, s49
	s_nop 0
	global_load_lds_dwordx4 v228, s[98:99]
	s_mov_b32 m0, s52
	s_nop 0
	global_load_lds_dwordx4 v229, s[98:99]
	s_waitcnt vmcnt(8)
	s_waitcnt lgkmcnt(0)
	s_barrier
	v_mfma_f32_16x16x32_bf16 v[126:129], v[156:159], v[172:175], v[126:129]
	v_mfma_f32_16x16x32_bf16 v[122:125], v[164:167], v[172:175], v[122:125]
	v_mfma_f32_16x16x32_bf16 v[118:121], v[156:159], v[180:183], v[118:121]
	v_mfma_f32_16x16x32_bf16 v[114:117], v[164:167], v[180:183], v[114:117]
	v_mfma_f32_16x16x32_bf16 v[110:113], v[156:159], v[188:191], v[110:113]
	v_mfma_f32_16x16x32_bf16 v[106:109], v[164:167], v[188:191], v[106:109]
	v_mfma_f32_16x16x32_bf16 v[102:105], v[156:159], v[196:199], v[102:105]
	v_mfma_f32_16x16x32_bf16 v[98:101], v[164:167], v[196:199], v[98:101]
	v_mfma_f32_16x16x32_bf16 v[126:129], v[160:163], v[176:179], v[126:129]
	v_mfma_f32_16x16x32_bf16 v[122:125], v[168:171], v[176:179], v[122:125]
	v_mfma_f32_16x16x32_bf16 v[118:121], v[160:163], v[184:187], v[118:121]
	v_mfma_f32_16x16x32_bf16 v[114:117], v[168:171], v[184:187], v[114:117]
	v_mfma_f32_16x16x32_bf16 v[110:113], v[160:163], v[192:195], v[110:113]
	v_mfma_f32_16x16x32_bf16 v[106:109], v[168:171], v[192:195], v[106:109]
	v_mfma_f32_16x16x32_bf16 v[102:105], v[160:163], v[200:203], v[102:105]
	v_mfma_f32_16x16x32_bf16 v[98:101], v[168:171], v[200:203], v[98:101]
	v_mfma_f32_16x16x32_bf16 v[86:89], v[204:207], v[172:175], v[86:89]
	v_mfma_f32_16x16x32_bf16 v[70:73], v[212:215], v[172:175], v[70:73]
	v_mfma_f32_16x16x32_bf16 v[54:57], v[204:207], v[180:183], v[54:57]
	v_mfma_f32_16x16x32_bf16 v[50:53], v[212:215], v[180:183], v[50:53]
	v_mfma_f32_16x16x32_bf16 v[46:49], v[204:207], v[188:191], v[46:49]
	v_mfma_f32_16x16x32_bf16 v[42:45], v[212:215], v[188:191], v[42:45]
	v_mfma_f32_16x16x32_bf16 v[38:41], v[204:207], v[196:199], v[38:41]
	v_mfma_f32_16x16x32_bf16 v[34:37], v[212:215], v[196:199], v[34:37]
	v_mfma_f32_16x16x32_bf16 v[86:89], v[208:211], v[176:179], v[86:89]
	v_mfma_f32_16x16x32_bf16 v[70:73], v[216:219], v[176:179], v[70:73]
	v_mfma_f32_16x16x32_bf16 v[54:57], v[208:211], v[184:187], v[54:57]
	v_mfma_f32_16x16x32_bf16 v[50:53], v[216:219], v[184:187], v[50:53]
	v_mfma_f32_16x16x32_bf16 v[46:49], v[208:211], v[192:195], v[46:49]
	v_mfma_f32_16x16x32_bf16 v[42:45], v[216:219], v[192:195], v[42:45]
	v_mfma_f32_16x16x32_bf16 v[38:41], v[208:211], v[200:203], v[38:41]
	v_mfma_f32_16x16x32_bf16 v[34:37], v[216:219], v[200:203], v[34:37]
	s_barrier
	ds_read_b128 v[172:175], v141 offset:49152
	ds_read_b128 v[176:179], v141 offset:50176
	ds_read_b128 v[180:183], v141 offset:51200
	ds_read_b128 v[184:187], v141 offset:52224
	ds_read_b128 v[188:191], v141 offset:53248
	ds_read_b128 v[192:195], v141 offset:54272
	ds_read_b128 v[196:199], v141 offset:55296
	ds_read_b128 v[200:203], v141 offset:56320
	s_mov_b32 m0, s53
	s_nop 0
	global_load_lds_dwordx4 v232, s[100:101]
	s_mov_b32 m0, s54
	s_nop 0
	global_load_lds_dwordx4 v233, s[100:101]
	s_mov_b32 m0, s55
	s_nop 0
	global_load_lds_dwordx4 v234, s[98:99]
	s_mov_b32 m0, s56
	s_nop 0
	global_load_lds_dwordx4 v235, s[98:99]
	s_mov_b32 m0, s57
	s_nop 0
	global_load_lds_dwordx4 v236, s[100:101]
	s_mov_b32 m0, s58
	s_nop 0
	global_load_lds_dwordx4 v237, s[100:101]
	s_add_i32 s42, s42, 2
	s_add_u32 s40, s40, 0x100
	s_addc_u32 s41, s41, 0
	s_add_u32 s98, s98, 0x100
	s_addc_u32 s99, s99, 0
	s_add_u32 s100, s100, 0x100
	s_addc_u32 s101, s101, 0
	s_cmpk_gt_u32 s42, 0x53
	s_waitcnt vmcnt(8)
	s_waitcnt lgkmcnt(0)
	s_barrier
	v_mfma_f32_16x16x32_bf16 v[30:33], v[156:159], v[172:175], v[30:33]
	v_mfma_f32_16x16x32_bf16 v[26:29], v[164:167], v[172:175], v[26:29]
	v_mfma_f32_16x16x32_bf16 v[22:25], v[156:159], v[180:183], v[22:25]
	v_mfma_f32_16x16x32_bf16 v[18:21], v[164:167], v[180:183], v[18:21]
	v_mfma_f32_16x16x32_bf16 v[14:17], v[156:159], v[188:191], v[14:17]
	v_mfma_f32_16x16x32_bf16 v[10:13], v[164:167], v[188:191], v[10:13]
	v_mfma_f32_16x16x32_bf16 v[6:9], v[156:159], v[196:199], v[6:9]
	v_mfma_f32_16x16x32_bf16 v[2:5], v[164:167], v[196:199], v[2:5]
	v_mfma_f32_16x16x32_bf16 v[30:33], v[160:163], v[176:179], v[30:33]
	v_mfma_f32_16x16x32_bf16 v[26:29], v[168:171], v[176:179], v[26:29]
	v_mfma_f32_16x16x32_bf16 v[22:25], v[160:163], v[184:187], v[22:25]
	v_mfma_f32_16x16x32_bf16 v[18:21], v[168:171], v[184:187], v[18:21]
	v_mfma_f32_16x16x32_bf16 v[14:17], v[160:163], v[192:195], v[14:17]
	v_mfma_f32_16x16x32_bf16 v[10:13], v[168:171], v[192:195], v[10:13]
	v_mfma_f32_16x16x32_bf16 v[6:9], v[160:163], v[200:203], v[6:9]
	v_mfma_f32_16x16x32_bf16 v[2:5], v[168:171], v[200:203], v[2:5]
	v_mfma_f32_16x16x32_bf16 v[58:61], v[204:207], v[172:175], v[58:61]
	v_mfma_f32_16x16x32_bf16 v[62:65], v[212:215], v[172:175], v[62:65]
	v_mfma_f32_16x16x32_bf16 v[66:69], v[204:207], v[180:183], v[66:69]
	v_mfma_f32_16x16x32_bf16 v[74:77], v[212:215], v[180:183], v[74:77]
	v_mfma_f32_16x16x32_bf16 v[78:81], v[204:207], v[188:191], v[78:81]
	v_mfma_f32_16x16x32_bf16 v[82:85], v[212:215], v[188:191], v[82:85]
	v_mfma_f32_16x16x32_bf16 v[90:93], v[204:207], v[196:199], v[90:93]
	v_mfma_f32_16x16x32_bf16 v[94:97], v[212:215], v[196:199], v[94:97]
	v_mfma_f32_16x16x32_bf16 v[58:61], v[208:211], v[176:179], v[58:61]
	v_mfma_f32_16x16x32_bf16 v[62:65], v[216:219], v[176:179], v[62:65]
	v_mfma_f32_16x16x32_bf16 v[66:69], v[208:211], v[184:187], v[66:69]
	v_mfma_f32_16x16x32_bf16 v[74:77], v[216:219], v[184:187], v[74:77]
	v_mfma_f32_16x16x32_bf16 v[78:81], v[208:211], v[192:195], v[78:81]
	v_mfma_f32_16x16x32_bf16 v[82:85], v[216:219], v[192:195], v[82:85]
	v_mfma_f32_16x16x32_bf16 v[90:93], v[208:211], v[200:203], v[90:93]
	v_mfma_f32_16x16x32_bf16 v[94:97], v[216:219], v[200:203], v[94:97]
	s_barrier
; #define LDA(dst, b, h)                                                                                     \
;   _Pragma("unroll") for (int m = 0; m < 4; ++m) _Pragma("unroll") for (int k = 0; k < 2; ++k) dst[m][k] = \
;       *reinterpret_cast<const bf16x8*>(shmc + aL + (((b) * 2 + (h)) * 16384 + (m * 2 + k) * 1024))
; #define LDB(dst, b, h)                                                                                     \
;   _Pragma("unroll") for (int n = 0; n < 2; ++n) _Pragma("unroll") for (int k = 0; k < 2; ++k) dst[n][k] = \
;       *reinterpret_cast<const bf16x8*>(shmc + bL + (((b) * 2 + (h)) * 16384 + (n * 2 + k) * 1024))
; #define OPAQ asm volatile("" : "+v"(aL), "+v"(bL))
; #define WAIT_V(n) asm volatile("s_waitcnt vmcnt(" #n ")" ::: "memory")
; #define WAIT_L(n) asm volatile("s_waitcnt lgkmcnt(" #n ")" ::: "memory")
; #define BAR __builtin_amdgcn_s_barrier()
; template <int EPI>
; __device__ __forceinline__ void phase_gemm(const Params& p, const GemmDesc& d, char* shmc) {
;     ...
;     {
;       OPAQ;
;       LDB(B0, 0, 0); LDA(At, 0, 0); STAGE_A(SA(1, 1), 1, nt - 1);
;       BAR; WAIT_L(0); MMA(0, 0, At, B0); BAR;
;       LDB(B1, 0, 1); BAR; WAIT_L(0); MMA(0, 1, At, B1); BAR;
;       LDA(At, 0, 1); WAIT_V(4); BAR; WAIT_L(0); MMA(1, 0, At, B0); MMA(1, 1, At, B1); BAR;
;     }
	s_cbranch_scc0 .LBB0_1312
	s_setprio 0
	s_add_u32 s38, s38, 0x162b80
	s_addc_u32 s39, s39, 0
	v_add_u32_e32 v130, 0, v153
	v_add_u32_e32 v141, 0, v152
	s_mov_b32 m0, s59
	ds_read_b128 v[144:147], v130
	ds_read_b128 v[148:151], v130 offset:1024
	ds_read_b128 v[156:159], v130 offset:2048
	ds_read_b128 v[160:163], v130 offset:3072
	ds_read_b128 v[164:167], v141
	ds_read_b128 v[168:171], v141 offset:1024
	ds_read_b128 v[172:175], v141 offset:2048
	ds_read_b128 v[176:179], v141 offset:3072
	ds_read_b128 v[180:183], v141 offset:4096
	ds_read_b128 v[184:187], v141 offset:5120
	ds_read_b128 v[188:191], v141 offset:6144
	ds_read_b128 v[192:195], v141 offset:7168
	global_load_lds_dwordx4 v140, s[38:39]
	s_mov_b32 m0, s60
	s_nop 0
	global_load_lds_dwordx4 v142, s[38:39]
	s_waitcnt vmcnt(8)
	s_barrier
	s_waitcnt lgkmcnt(0)
	s_setprio 1
	s_waitcnt lgkmcnt(0)
	v_mfma_f32_16x16x32_bf16 v[126:129], v[144:147], v[164:167], v[126:129]
	v_mfma_f32_16x16x32_bf16 v[122:125], v[156:159], v[164:167], v[122:125]
	v_mfma_f32_16x16x32_bf16 v[114:117], v[156:159], v[172:175], v[114:117]
	v_mfma_f32_16x16x32_bf16 v[110:113], v[144:147], v[180:183], v[110:113]
	v_mfma_f32_16x16x32_bf16 v[102:105], v[144:147], v[188:191], v[102:105]
	v_mfma_f32_16x16x32_bf16 v[126:129], v[148:151], v[168:171], v[126:129]
	v_mfma_f32_16x16x32_bf16 v[122:125], v[160:163], v[168:171], v[122:125]
	v_mfma_f32_16x16x32_bf16 v[118:121], v[144:147], v[172:175], v[118:121]
	v_mfma_f32_16x16x32_bf16 v[114:117], v[160:163], v[176:179], v[114:117]
	v_mfma_f32_16x16x32_bf16 v[110:113], v[148:151], v[184:187], v[110:113]
	v_mfma_f32_16x16x32_bf16 v[106:109], v[156:159], v[180:183], v[106:109]
	v_mfma_f32_16x16x32_bf16 v[102:105], v[148:151], v[192:195], v[102:105]
	v_mfma_f32_16x16x32_bf16 v[98:101], v[156:159], v[188:191], v[98:101]
	v_mfma_f32_16x16x32_bf16 v[196:199], v[148:151], v[176:179], v[118:121]
	v_mfma_f32_16x16x32_bf16 v[200:203], v[160:163], v[184:187], v[106:109]
	v_mfma_f32_16x16x32_bf16 v[204:207], v[160:163], v[192:195], v[98:101]
	s_setprio 0
	s_barrier
	s_nop 2
	ds_read_b128 v[98:101], v130 offset:16384
	ds_read_b128 v[106:109], v130 offset:17408
	ds_read_b128 v[118:121], v130 offset:18432
	ds_read_b128 v[208:211], v130 offset:19456
	s_barrier
	s_waitcnt lgkmcnt(0)
	s_setprio 1
	s_waitcnt lgkmcnt(0)
	v_mfma_f32_16x16x32_bf16 v[86:89], v[98:101], v[164:167], v[86:89]
	v_mfma_f32_16x16x32_bf16 v[70:73], v[118:121], v[164:167], v[70:73]
	v_mfma_f32_16x16x32_bf16 v[54:57], v[98:101], v[172:175], v[54:57]
	v_mfma_f32_16x16x32_bf16 v[50:53], v[118:121], v[172:175], v[50:53]
	v_mfma_f32_16x16x32_bf16 v[46:49], v[98:101], v[180:183], v[46:49]
	v_mfma_f32_16x16x32_bf16 v[42:45], v[118:121], v[180:183], v[42:45]
	v_mfma_f32_16x16x32_bf16 v[38:41], v[98:101], v[188:191], v[38:41]
	v_mfma_f32_16x16x32_bf16 v[34:37], v[118:121], v[188:191], v[34:37]
	v_mfma_f32_16x16x32_bf16 v[86:89], v[106:109], v[168:171], v[86:89]
	v_mfma_f32_16x16x32_bf16 v[70:73], v[208:211], v[168:171], v[70:73]
	v_mfma_f32_16x16x32_bf16 v[54:57], v[106:109], v[176:179], v[54:57]
	v_mfma_f32_16x16x32_bf16 v[50:53], v[208:211], v[176:179], v[50:53]
	v_mfma_f32_16x16x32_bf16 v[46:49], v[106:109], v[184:187], v[46:49]
	v_mfma_f32_16x16x32_bf16 v[42:45], v[208:211], v[184:187], v[42:45]
	v_mfma_f32_16x16x32_bf16 v[38:41], v[106:109], v[192:195], v[38:41]
	v_mfma_f32_16x16x32_bf16 v[34:37], v[208:211], v[192:195], v[34:37]
	s_setprio 0
	s_barrier
	ds_read_b128 v[164:167], v141 offset:16384
	ds_read_b128 v[168:171], v141 offset:17408
	ds_read_b128 v[172:175], v141 offset:18432
	ds_read_b128 v[176:179], v141 offset:19456
	ds_read_b128 v[180:183], v141 offset:20480
	ds_read_b128 v[184:187], v141 offset:21504
	ds_read_b128 v[188:191], v141 offset:22528
	ds_read_b128 v[192:195], v141 offset:23552
	s_waitcnt vmcnt(4)
	s_barrier
	s_waitcnt lgkmcnt(0)
	s_setprio 1
	s_waitcnt lgkmcnt(0)
	v_mfma_f32_16x16x32_bf16 v[30:33], v[144:147], v[164:167], v[30:33]
	v_mfma_f32_16x16x32_bf16 v[26:29], v[156:159], v[164:167], v[26:29]
	v_mfma_f32_16x16x32_bf16 v[22:25], v[144:147], v[172:175], v[22:25]
	v_mfma_f32_16x16x32_bf16 v[18:21], v[156:159], v[172:175], v[18:21]
	v_mfma_f32_16x16x32_bf16 v[14:17], v[144:147], v[180:183], v[14:17]
	v_mfma_f32_16x16x32_bf16 v[10:13], v[156:159], v[180:183], v[10:13]
	v_mfma_f32_16x16x32_bf16 v[6:9], v[144:147], v[188:191], v[6:9]
	v_mfma_f32_16x16x32_bf16 v[2:5], v[156:159], v[188:191], v[2:5]
	v_mfma_f32_16x16x32_bf16 v[30:33], v[148:151], v[168:171], v[30:33]
	v_mfma_f32_16x16x32_bf16 v[26:29], v[160:163], v[168:171], v[26:29]
	v_mfma_f32_16x16x32_bf16 v[22:25], v[148:151], v[176:179], v[22:25]
	v_mfma_f32_16x16x32_bf16 v[18:21], v[160:163], v[176:179], v[18:21]
	v_mfma_f32_16x16x32_bf16 v[14:17], v[148:151], v[184:187], v[14:17]
	v_mfma_f32_16x16x32_bf16 v[10:13], v[160:163], v[184:187], v[10:13]
	v_mfma_f32_16x16x32_bf16 v[6:9], v[148:151], v[192:195], v[6:9]
	v_mfma_f32_16x16x32_bf16 v[2:5], v[160:163], v[192:195], v[2:5]
	s_setprio 0
	s_setprio 1
	v_mfma_f32_16x16x32_bf16 v[62:65], v[118:121], v[164:167], v[62:65]
	v_mfma_f32_16x16x32_bf16 v[144:147], v[208:211], v[168:171], v[62:65]
	v_mfma_f32_16x16x32_bf16 v[62:65], v[98:101], v[172:175], v[66:69]
	v_mfma_f32_16x16x32_bf16 v[148:151], v[106:109], v[176:179], v[62:65]
	v_mfma_f32_16x16x32_bf16 v[62:65], v[118:121], v[172:175], v[74:77]
	v_mfma_f32_16x16x32_bf16 v[156:159], v[208:211], v[176:179], v[62:65]
	v_mfma_f32_16x16x32_bf16 v[62:65], v[98:101], v[180:183], v[78:81]
	v_mfma_f32_16x16x32_bf16 v[160:163], v[106:109], v[184:187], v[62:65]
	v_mfma_f32_16x16x32_bf16 v[62:65], v[118:121], v[180:183], v[82:85]
	v_mfma_f32_16x16x32_bf16 v[58:61], v[98:101], v[164:167], v[58:61]
	v_mfma_f32_16x16x32_bf16 v[164:167], v[208:211], v[184:187], v[62:65]
	v_mfma_f32_16x16x32_bf16 v[62:65], v[98:101], v[188:191], v[90:93]
	v_mfma_f32_16x16x32_bf16 v[58:61], v[106:109], v[168:171], v[58:61]
	v_mfma_f32_16x16x32_bf16 v[168:171], v[106:109], v[192:195], v[62:65]
	v_mfma_f32_16x16x32_bf16 v[62:65], v[118:121], v[188:191], v[94:97]
	v_mfma_f32_16x16x32_bf16 v[172:175], v[208:211], v[192:195], v[62:65]
	s_setprio 0
	s_barrier
; #define LDA(dst, b, h)                                                                                     \
;   _Pragma("unroll") for (int m = 0; m < 4; ++m) _Pragma("unroll") for (int k = 0; k < 2; ++k) dst[m][k] = \
;       *reinterpret_cast<const bf16x8*>(shmc + aL + (((b) * 2 + (h)) * 16384 + (m * 2 + k) * 1024))
; #define LDB(dst, b, h)                                                                                     \
;   _Pragma("unroll") for (int n = 0; n < 2; ++n) _Pragma("unroll") for (int k = 0; k < 2; ++k) dst[n][k] = \
;       *reinterpret_cast<const bf16x8*>(shmc + bL + (((b) * 2 + (h)) * 16384 + (n * 2 + k) * 1024))
; #define WAIT_V(n) asm volatile("s_waitcnt vmcnt(" #n ")" ::: "memory")
; #define WAIT_L(n) asm volatile("s_waitcnt lgkmcnt(" #n ")" ::: "memory")
; #define BAR __builtin_amdgcn_s_barrier()
; template <int EPI>
; __device__ __forceinline__ void phase_gemm(const Params& p, const GemmDesc& d, char* shmc) {
;     ...
;     {
;       LDB(B0, 1, 0); LDA(At, 1, 0); WAIT_V(2); BAR; WAIT_L(0); MMA(0, 0, At, B0); BAR;
;       LDB(B1, 1, 1); WAIT_V(0); BAR; WAIT_L(0); MMA(0, 1, At, B1); BAR;
;       LDA(At, 1, 1); BAR; WAIT_L(0); MMA(1, 0, At, B0); MMA(1, 1, At, B1); BAR;
;     }
;     if (wr == 0) BAR;
	ds_read_b128 v[176:179], v130 offset:32768
	ds_read_b128 v[180:183], v130 offset:33792
	ds_read_b128 v[184:187], v130 offset:34816
	ds_read_b128 v[188:191], v130 offset:35840
	s_nop 0
	ds_read_b128 v[62:65], v141 offset:32768
	ds_read_b128 v[78:81], v141 offset:33792
	ds_read_b128 v[94:97], v141 offset:34816
	ds_read_b128 v[192:195], v141 offset:35840
	ds_read_b128 v[208:211], v141 offset:36864
	ds_read_b128 v[212:215], v141 offset:37888
	ds_read_b128 v[216:219], v141 offset:38912
	ds_read_b128 v[220:223], v141 offset:39936
	s_waitcnt vmcnt(2)
	s_barrier
	s_waitcnt lgkmcnt(0)
	s_setprio 1
	s_waitcnt lgkmcnt(0)
	v_mfma_f32_16x16x32_bf16 v[66:69], v[176:179], v[62:65], v[126:129]
	v_mfma_f32_16x16x32_bf16 v[126:129], v[180:183], v[78:81], v[66:69]
	v_mfma_f32_16x16x32_bf16 v[66:69], v[184:187], v[62:65], v[122:125]
	v_mfma_f32_16x16x32_bf16 v[118:121], v[188:191], v[78:81], v[66:69]
	v_mfma_f32_16x16x32_bf16 v[66:69], v[176:179], v[94:97], v[196:199]
	v_mfma_f32_16x16x32_bf16 v[106:109], v[180:183], v[192:195], v[66:69]
	v_mfma_f32_16x16x32_bf16 v[66:69], v[184:187], v[94:97], v[114:117]
	v_mfma_f32_16x16x32_bf16 v[98:101], v[188:191], v[192:195], v[66:69]
	v_mfma_f32_16x16x32_bf16 v[66:69], v[176:179], v[208:211], v[110:113]
	v_mfma_f32_16x16x32_bf16 v[90:93], v[180:183], v[212:215], v[66:69]
	v_mfma_f32_16x16x32_bf16 v[66:69], v[184:187], v[208:211], v[200:203]
	v_mfma_f32_16x16x32_bf16 v[82:85], v[188:191], v[212:215], v[66:69]
	v_mfma_f32_16x16x32_bf16 v[66:69], v[176:179], v[216:219], v[102:105]
	v_mfma_f32_16x16x32_bf16 v[74:77], v[180:183], v[220:223], v[66:69]
	v_mfma_f32_16x16x32_bf16 v[66:69], v[184:187], v[216:219], v[204:207]
	v_mfma_f32_16x16x32_bf16 v[66:69], v[188:191], v[220:223], v[66:69]
	s_setprio 0
	s_barrier
	ds_read_b128 v[196:199], v130 offset:49152
	ds_read_b128 v[200:203], v130 offset:50176
	ds_read_b128 v[204:207], v130 offset:51200
	ds_read_b128 v[224:227], v130 offset:52224
	s_waitcnt vmcnt(0)
	s_barrier
	s_waitcnt lgkmcnt(0)
	s_setprio 1
	s_waitcnt lgkmcnt(0)
	v_mfma_f32_16x16x32_bf16 v[86:89], v[196:199], v[62:65], v[86:89]
	v_mfma_f32_16x16x32_bf16 v[62:65], v[204:207], v[62:65], v[70:73]
	v_mfma_f32_16x16x32_bf16 v[54:57], v[196:199], v[94:97], v[54:57]
	v_mfma_f32_16x16x32_bf16 v[50:53], v[204:207], v[94:97], v[50:53]
	v_mfma_f32_16x16x32_bf16 v[46:49], v[196:199], v[208:211], v[46:49]
	v_mfma_f32_16x16x32_bf16 v[42:45], v[204:207], v[208:211], v[42:45]
	v_mfma_f32_16x16x32_bf16 v[38:41], v[196:199], v[216:219], v[38:41]
	v_mfma_f32_16x16x32_bf16 v[34:37], v[204:207], v[216:219], v[34:37]
	v_mfma_f32_16x16x32_bf16 v[122:125], v[200:203], v[78:81], v[86:89]
	v_mfma_f32_16x16x32_bf16 v[114:117], v[224:227], v[78:81], v[62:65]
	v_mfma_f32_16x16x32_bf16 v[110:113], v[200:203], v[192:195], v[54:57]
	v_mfma_f32_16x16x32_bf16 v[102:105], v[224:227], v[192:195], v[50:53]
	v_mfma_f32_16x16x32_bf16 v[94:97], v[200:203], v[212:215], v[46:49]
	v_mfma_f32_16x16x32_bf16 v[86:89], v[224:227], v[212:215], v[42:45]
	v_mfma_f32_16x16x32_bf16 v[78:81], v[200:203], v[220:223], v[38:41]
	v_mfma_f32_16x16x32_bf16 v[70:73], v[224:227], v[220:223], v[34:37]
	s_setprio 0
	s_barrier
	s_nop 0
	ds_read_b128 v[34:37], v141 offset:49152
	ds_read_b128 v[42:45], v141 offset:50176
	ds_read_b128 v[192:195], v141 offset:51200
	ds_read_b128 v[208:211], v141 offset:52224
	ds_read_b128 v[212:215], v141 offset:53248
	ds_read_b128 v[216:219], v141 offset:54272
	ds_read_b128 v[220:223], v141 offset:55296
	ds_read_b128 v[228:231], v141 offset:56320
	s_barrier
	s_waitcnt lgkmcnt(0)
	s_setprio 1
	s_waitcnt lgkmcnt(0)
	v_mfma_f32_16x16x32_bf16 v[30:33], v[176:179], v[34:37], v[30:33]
	v_mfma_f32_16x16x32_bf16 v[26:29], v[184:187], v[34:37], v[26:29]
	v_mfma_f32_16x16x32_bf16 v[22:25], v[176:179], v[192:195], v[22:25]
	v_mfma_f32_16x16x32_bf16 v[18:21], v[184:187], v[192:195], v[18:21]
	v_mfma_f32_16x16x32_bf16 v[14:17], v[176:179], v[212:215], v[14:17]
	v_mfma_f32_16x16x32_bf16 v[10:13], v[184:187], v[212:215], v[10:13]
	v_mfma_f32_16x16x32_bf16 v[6:9], v[176:179], v[220:223], v[6:9]
	v_mfma_f32_16x16x32_bf16 v[2:5], v[184:187], v[220:223], v[2:5]
	v_mfma_f32_16x16x32_bf16 v[62:65], v[180:183], v[42:45], v[30:33]
	v_mfma_f32_16x16x32_bf16 v[54:57], v[188:191], v[42:45], v[26:29]
	v_mfma_f32_16x16x32_bf16 v[46:49], v[180:183], v[208:211], v[22:25]
	v_mfma_f32_16x16x32_bf16 v[38:41], v[188:191], v[208:211], v[18:21]
	v_mfma_f32_16x16x32_bf16 v[30:33], v[180:183], v[216:219], v[14:17]
	v_mfma_f32_16x16x32_bf16 v[22:25], v[188:191], v[216:219], v[10:13]
	v_mfma_f32_16x16x32_bf16 v[14:17], v[180:183], v[228:231], v[6:9]
	v_mfma_f32_16x16x32_bf16 v[6:9], v[188:191], v[228:231], v[2:5]
	s_setprio 0
	s_setprio 1
	v_mfma_f32_16x16x32_bf16 v[2:5], v[196:199], v[34:37], v[58:61]
	v_mfma_f32_16x16x32_bf16 v[58:61], v[200:203], v[42:45], v[2:5]
	v_mfma_f32_16x16x32_bf16 v[2:5], v[204:207], v[34:37], v[144:147]
	v_mfma_f32_16x16x32_bf16 v[50:53], v[224:227], v[42:45], v[2:5]
	v_mfma_f32_16x16x32_bf16 v[2:5], v[196:199], v[192:195], v[148:151]
	v_mfma_f32_16x16x32_bf16 v[42:45], v[200:203], v[208:211], v[2:5]
	v_mfma_f32_16x16x32_bf16 v[2:5], v[204:207], v[192:195], v[156:159]
	v_mfma_f32_16x16x32_bf16 v[34:37], v[224:227], v[208:211], v[2:5]
	v_mfma_f32_16x16x32_bf16 v[2:5], v[196:199], v[212:215], v[160:163]
	v_mfma_f32_16x16x32_bf16 v[26:29], v[200:203], v[216:219], v[2:5]
	v_mfma_f32_16x16x32_bf16 v[2:5], v[204:207], v[212:215], v[164:167]
	v_mfma_f32_16x16x32_bf16 v[18:21], v[224:227], v[216:219], v[2:5]
	v_mfma_f32_16x16x32_bf16 v[2:5], v[196:199], v[220:223], v[168:171]
	v_mfma_f32_16x16x32_bf16 v[10:13], v[200:203], v[228:231], v[2:5]
	v_mfma_f32_16x16x32_bf16 v[2:5], v[204:207], v[220:223], v[172:175]
	v_mfma_f32_16x16x32_bf16 v[2:5], v[224:227], v[228:231], v[2:5]
	s_setprio 0
	s_barrier
	s_and_saveexec_b64 s[38:39], s[4:5]
	s_cbranch_execz .LBB0_1315
	s_barrier
